# 21 K-loop LDS-DMA loads switched to SGPR-base + VGPR-offset addressing (64-bit VALU adds removed), on top of v5
# speedup vs baseline: 1.0068x; 1.0000x over previous
.LBB0_279:
	s_add_u32 s12, s10, 0xfffc0080
	s_addc_u32 s13, s11, -1
	s_add_i32 s19, 0, 0x10000
	v_add_u32_e32 v140, s19, v188
	ds_read_b128 v[120:123], v140
	ds_read_b128 v[124:127], v140 offset:1024
	ds_read_b128 v[136:139], v140 offset:2048
	ds_read_b128 v[140:143], v140 offset:3072
	s_cmp_eq_u32 s18, 12
	s_cselect_b32 s15, s0, s13
	s_cselect_b32 s14, s1, s12
	s_cselect_b32 s13, s7, s17
	s_cselect_b32 s12, s9, s16
	s_add_i32 m0, s68, 0xc000
	ds_read_b128 v[144:147], v189
	ds_read_b128 v[148:151], v189 offset:1024
	ds_read_b128 v[152:155], v189 offset:2048
	ds_read_b128 v[156:159], v189 offset:3072
	ds_read_b128 v[168:171], v189 offset:4096
	ds_read_b128 v[172:175], v189 offset:5120
	ds_read_b128 v[176:179], v189 offset:6144
	ds_read_b128 v[180:183], v189 offset:7168
	global_load_lds_dwordx4 v166, s[10:11]
	v_lshl_add_u64 v[184:185], s[10:11], 0, v[164:165]
	s_add_i32 m0, s68, 0xe000
	s_nop 0
	global_load_lds_dwordx4 v[184:185], off
	s_waitcnt lgkmcnt(8)
	s_barrier
	s_waitcnt lgkmcnt(0)
	s_setprio 1
	s_waitcnt lgkmcnt(0)
	v_mfma_f32_16x16x32_bf16 v[132:135], v[120:123], v[144:147], v[132:135]
	v_mfma_f32_16x16x32_bf16 v[128:131], v[136:139], v[144:147], v[128:131]
	v_mfma_f32_16x16x32_bf16 v[108:111], v[120:123], v[152:155], v[108:111]
	v_mfma_f32_16x16x32_bf16 v[104:107], v[136:139], v[152:155], v[104:107]
	v_mfma_f32_16x16x32_bf16 v[92:95], v[120:123], v[168:171], v[92:95]
	v_mfma_f32_16x16x32_bf16 v[88:91], v[136:139], v[168:171], v[88:91]
	v_mfma_f32_16x16x32_bf16 v[76:79], v[120:123], v[176:179], v[76:79]
	v_mfma_f32_16x16x32_bf16 v[72:75], v[136:139], v[176:179], v[72:75]
	v_mfma_f32_16x16x32_bf16 v[132:135], v[124:127], v[148:151], v[132:135]
	v_mfma_f32_16x16x32_bf16 v[128:131], v[140:143], v[148:151], v[128:131]
	v_mfma_f32_16x16x32_bf16 v[108:111], v[124:127], v[156:159], v[108:111]
	v_mfma_f32_16x16x32_bf16 v[104:107], v[140:143], v[156:159], v[104:107]
	v_mfma_f32_16x16x32_bf16 v[92:95], v[124:127], v[172:175], v[92:95]
	v_mfma_f32_16x16x32_bf16 v[88:91], v[140:143], v[172:175], v[88:91]
	v_mfma_f32_16x16x32_bf16 v[76:79], v[124:127], v[180:183], v[76:79]
	v_mfma_f32_16x16x32_bf16 v[72:75], v[140:143], v[180:183], v[72:75]
	s_setprio 0
	s_barrier
	s_add_i32 s33, 0, 0x14000
	v_add_u32_e32 v190, s33, v188
	s_add_i32 s19, s19, s67
	ds_read_b128 v[184:187], v190
	ds_read_b128 v[198:201], v190 offset:1024
	ds_read_b128 v[206:209], v190 offset:2048
	ds_read_b128 v[210:213], v190 offset:3072
	v_lshl_add_u64 v[190:191], s[12:13], 0, v[160:161]
	s_mov_b32 m0, s19
	v_lshl_add_u64 v[214:215], s[12:13], 0, v[162:163]
	global_load_lds_dwordx4 v[190:191], off
	s_add_i32 m0, s19, 0x2000
	s_nop 0
	global_load_lds_dwordx4 v[214:215], off
	s_barrier
	s_waitcnt lgkmcnt(0)
	s_setprio 1
	s_waitcnt lgkmcnt(0)
	v_mfma_f32_16x16x32_bf16 v[116:119], v[184:187], v[144:147], v[116:119]
	v_mfma_f32_16x16x32_bf16 v[112:115], v[206:209], v[144:147], v[112:115]
	v_mfma_f32_16x16x32_bf16 v[100:103], v[184:187], v[152:155], v[100:103]
	v_mfma_f32_16x16x32_bf16 v[96:99], v[206:209], v[152:155], v[96:99]
	v_mfma_f32_16x16x32_bf16 v[84:87], v[184:187], v[168:171], v[84:87]
	v_mfma_f32_16x16x32_bf16 v[80:83], v[206:209], v[168:171], v[80:83]
	v_mfma_f32_16x16x32_bf16 v[68:71], v[184:187], v[176:179], v[68:71]
	v_mfma_f32_16x16x32_bf16 v[64:67], v[206:209], v[176:179], v[64:67]
	v_mfma_f32_16x16x32_bf16 v[116:119], v[198:201], v[148:151], v[116:119]
	v_mfma_f32_16x16x32_bf16 v[112:115], v[210:213], v[148:151], v[112:115]
	v_mfma_f32_16x16x32_bf16 v[100:103], v[198:201], v[156:159], v[100:103]
	v_mfma_f32_16x16x32_bf16 v[96:99], v[210:213], v[156:159], v[96:99]
	v_mfma_f32_16x16x32_bf16 v[84:87], v[198:201], v[172:175], v[84:87]
	v_mfma_f32_16x16x32_bf16 v[80:83], v[210:213], v[172:175], v[80:83]
	v_mfma_f32_16x16x32_bf16 v[68:71], v[198:201], v[180:183], v[68:71]
	v_mfma_f32_16x16x32_bf16 v[64:67], v[210:213], v[180:183], v[64:67]
	s_setprio 0
	s_mov_b32 m0, s68
	v_lshl_add_u64 v[216:217], s[14:15], 0, v[160:161]
	s_barrier
	ds_read_b128 v[144:147], v189 offset:16384
	ds_read_b128 v[148:151], v189 offset:17408
	ds_read_b128 v[152:155], v189 offset:18432
	ds_read_b128 v[156:159], v189 offset:19456
	ds_read_b128 v[168:171], v189 offset:20480
	ds_read_b128 v[172:175], v189 offset:21504
	ds_read_b128 v[176:179], v189 offset:22528
	ds_read_b128 v[180:183], v189 offset:23552
	global_load_lds_dwordx4 v[216:217], off
	v_lshl_add_u64 v[218:219], s[14:15], 0, v[162:163]
	s_mov_b32 m0, s69
	s_nop 0
	global_load_lds_dwordx4 v[218:219], off
	s_barrier
	s_waitcnt lgkmcnt(0)
	s_setprio 1
	s_waitcnt lgkmcnt(0)
	v_mfma_f32_16x16x32_bf16 v[60:63], v[120:123], v[144:147], v[60:63]
	v_mfma_f32_16x16x32_bf16 v[56:59], v[136:139], v[144:147], v[56:59]
	v_mfma_f32_16x16x32_bf16 v[44:47], v[120:123], v[152:155], v[44:47]
	v_mfma_f32_16x16x32_bf16 v[40:43], v[136:139], v[152:155], v[40:43]
	v_mfma_f32_16x16x32_bf16 v[28:31], v[120:123], v[168:171], v[28:31]
	v_mfma_f32_16x16x32_bf16 v[24:27], v[136:139], v[168:171], v[24:27]
	v_mfma_f32_16x16x32_bf16 v[12:15], v[120:123], v[176:179], v[12:15]
	v_mfma_f32_16x16x32_bf16 v[8:11], v[136:139], v[176:179], v[8:11]
	v_mfma_f32_16x16x32_bf16 v[60:63], v[124:127], v[148:151], v[60:63]
	v_mfma_f32_16x16x32_bf16 v[56:59], v[140:143], v[148:151], v[56:59]
	v_mfma_f32_16x16x32_bf16 v[44:47], v[124:127], v[156:159], v[44:47]
	v_mfma_f32_16x16x32_bf16 v[40:43], v[140:143], v[156:159], v[40:43]
	v_mfma_f32_16x16x32_bf16 v[28:31], v[124:127], v[172:175], v[28:31]
	v_mfma_f32_16x16x32_bf16 v[24:27], v[140:143], v[172:175], v[24:27]
	v_mfma_f32_16x16x32_bf16 v[12:15], v[124:127], v[180:183], v[12:15]
	v_mfma_f32_16x16x32_bf16 v[8:11], v[140:143], v[180:183], v[8:11]
	s_setprio 0
	s_barrier
	s_add_u32 s44, s12, 0x40000
	s_addc_u32 s45, s13, 0
	s_add_i32 s19, s33, s67
	s_mov_b32 m0, s19
	s_nop 0
	global_load_lds_dwordx4 v160, s[44:45]
	v_lshl_add_u64 v[120:121], s[44:45], 0, v[162:163]
	s_add_i32 m0, s19, 0x2000
	s_nop 0
	global_load_lds_dwordx4 v[120:121], off
	s_waitcnt vmcnt(6)
	s_barrier
	s_setprio 1
	v_mfma_f32_16x16x32_bf16 v[52:55], v[184:187], v[144:147], v[52:55]
	v_mfma_f32_16x16x32_bf16 v[48:51], v[206:209], v[144:147], v[48:51]
	v_mfma_f32_16x16x32_bf16 v[36:39], v[184:187], v[152:155], v[36:39]
	v_mfma_f32_16x16x32_bf16 v[32:35], v[206:209], v[152:155], v[32:35]
	v_mfma_f32_16x16x32_bf16 v[20:23], v[184:187], v[168:171], v[20:23]
	v_mfma_f32_16x16x32_bf16 v[16:19], v[206:209], v[168:171], v[16:19]
	v_mfma_f32_16x16x32_bf16 v[4:7], v[184:187], v[176:179], v[4:7]
	v_mfma_f32_16x16x32_bf16 v[0:3], v[206:209], v[176:179], v[0:3]
	v_mfma_f32_16x16x32_bf16 v[52:55], v[198:201], v[148:151], v[52:55]
	v_mfma_f32_16x16x32_bf16 v[48:51], v[210:213], v[148:151], v[48:51]
	v_mfma_f32_16x16x32_bf16 v[36:39], v[198:201], v[156:159], v[36:39]
	v_mfma_f32_16x16x32_bf16 v[32:35], v[210:213], v[156:159], v[32:35]
	v_mfma_f32_16x16x32_bf16 v[20:23], v[198:201], v[172:175], v[20:23]
	v_mfma_f32_16x16x32_bf16 v[16:19], v[210:213], v[172:175], v[16:19]
	v_mfma_f32_16x16x32_bf16 v[4:7], v[198:201], v[180:183], v[4:7]
	v_mfma_f32_16x16x32_bf16 v[0:3], v[210:213], v[180:183], v[0:3]
	s_setprio 0
	s_add_i32 s19, 0, 0x18000
	v_add_u32_e32 v140, s19, v188
	s_barrier
	ds_read_b128 v[120:123], v140
	ds_read_b128 v[124:127], v140 offset:1024
	ds_read_b128 v[136:139], v140 offset:2048
	ds_read_b128 v[140:143], v140 offset:3072
	s_add_u32 s14, s14, 0x40000
	s_addc_u32 s15, s15, 0
	s_mov_b32 m0, s72
	ds_read_b128 v[144:147], v189 offset:32768
	ds_read_b128 v[148:151], v189 offset:33792
	ds_read_b128 v[152:155], v189 offset:34816
	ds_read_b128 v[156:159], v189 offset:35840
	ds_read_b128 v[168:171], v189 offset:36864
	ds_read_b128 v[172:175], v189 offset:37888
	ds_read_b128 v[176:179], v189 offset:38912
	ds_read_b128 v[180:183], v189 offset:39936
	global_load_lds_dwordx4 v160, s[14:15]
	v_lshl_add_u64 v[184:185], s[14:15], 0, v[162:163]
	s_mov_b32 m0, s73
	s_nop 0
	global_load_lds_dwordx4 v[184:185], off
	s_waitcnt lgkmcnt(8)
	s_barrier
	s_waitcnt lgkmcnt(0)
	s_setprio 1
	s_waitcnt lgkmcnt(0)
	v_mfma_f32_16x16x32_bf16 v[132:135], v[120:123], v[144:147], v[132:135]
	v_mfma_f32_16x16x32_bf16 v[128:131], v[136:139], v[144:147], v[128:131]
	v_mfma_f32_16x16x32_bf16 v[108:111], v[120:123], v[152:155], v[108:111]
	v_mfma_f32_16x16x32_bf16 v[104:107], v[136:139], v[152:155], v[104:107]
	v_mfma_f32_16x16x32_bf16 v[92:95], v[120:123], v[168:171], v[92:95]
	v_mfma_f32_16x16x32_bf16 v[88:91], v[136:139], v[168:171], v[88:91]
	v_mfma_f32_16x16x32_bf16 v[76:79], v[120:123], v[176:179], v[76:79]
	v_mfma_f32_16x16x32_bf16 v[72:75], v[136:139], v[176:179], v[72:75]
	v_mfma_f32_16x16x32_bf16 v[132:135], v[124:127], v[148:151], v[132:135]
	v_mfma_f32_16x16x32_bf16 v[128:131], v[140:143], v[148:151], v[128:131]
	v_mfma_f32_16x16x32_bf16 v[108:111], v[124:127], v[156:159], v[108:111]
	v_mfma_f32_16x16x32_bf16 v[104:107], v[140:143], v[156:159], v[104:107]
	v_mfma_f32_16x16x32_bf16 v[92:95], v[124:127], v[172:175], v[92:95]
	v_mfma_f32_16x16x32_bf16 v[88:91], v[140:143], v[172:175], v[88:91]
	v_mfma_f32_16x16x32_bf16 v[76:79], v[124:127], v[180:183], v[76:79]
	v_mfma_f32_16x16x32_bf16 v[72:75], v[140:143], v[180:183], v[72:75]
	s_setprio 0
	s_barrier
	s_add_i32 s14, 0, 0x1c000
	s_add_i32 s15, s19, s67
	v_add_u32_e32 v192, s14, v188
	v_lshl_add_u64 v[190:191], v[190:191], 0, s[80:81]
	s_mov_b32 m0, s15
	ds_read_b128 v[184:187], v192
	ds_read_b128 v[198:201], v192 offset:1024
	ds_read_b128 v[206:209], v192 offset:2048
	ds_read_b128 v[210:213], v192 offset:3072
	global_load_lds_dwordx4 v[190:191], off
	v_lshl_add_u64 v[190:191], v[214:215], 0, s[80:81]
	s_add_i32 m0, s15, 0x2000
	s_nop 0
	global_load_lds_dwordx4 v[190:191], off
	s_barrier
	s_waitcnt lgkmcnt(0)
	s_setprio 1
	s_waitcnt lgkmcnt(0)
	v_mfma_f32_16x16x32_bf16 v[116:119], v[184:187], v[144:147], v[116:119]
	v_mfma_f32_16x16x32_bf16 v[112:115], v[206:209], v[144:147], v[112:115]
	v_mfma_f32_16x16x32_bf16 v[100:103], v[184:187], v[152:155], v[100:103]
	v_mfma_f32_16x16x32_bf16 v[96:99], v[206:209], v[152:155], v[96:99]
	v_mfma_f32_16x16x32_bf16 v[84:87], v[184:187], v[168:171], v[84:87]
	v_mfma_f32_16x16x32_bf16 v[80:83], v[206:209], v[168:171], v[80:83]
	v_mfma_f32_16x16x32_bf16 v[68:71], v[184:187], v[176:179], v[68:71]
	v_mfma_f32_16x16x32_bf16 v[64:67], v[206:209], v[176:179], v[64:67]
	v_mfma_f32_16x16x32_bf16 v[116:119], v[198:201], v[148:151], v[116:119]
	v_mfma_f32_16x16x32_bf16 v[112:115], v[210:213], v[148:151], v[112:115]
	v_mfma_f32_16x16x32_bf16 v[100:103], v[198:201], v[156:159], v[100:103]
	v_mfma_f32_16x16x32_bf16 v[96:99], v[210:213], v[156:159], v[96:99]
	v_mfma_f32_16x16x32_bf16 v[84:87], v[198:201], v[172:175], v[84:87]
	v_mfma_f32_16x16x32_bf16 v[80:83], v[210:213], v[172:175], v[80:83]
	v_mfma_f32_16x16x32_bf16 v[68:71], v[198:201], v[180:183], v[68:71]
	v_mfma_f32_16x16x32_bf16 v[64:67], v[210:213], v[180:183], v[64:67]
	s_setprio 0
	s_mov_b32 m0, s74
	v_lshl_add_u64 v[190:191], v[216:217], 0, s[80:81]
	s_barrier
	ds_read_b128 v[144:147], v189 offset:49152
	ds_read_b128 v[148:151], v189 offset:50176
	ds_read_b128 v[152:155], v189 offset:51200
	ds_read_b128 v[156:159], v189 offset:52224
	ds_read_b128 v[168:171], v189 offset:53248
	ds_read_b128 v[172:175], v189 offset:54272
	ds_read_b128 v[176:179], v189 offset:55296
	ds_read_b128 v[180:183], v189 offset:56320
	global_load_lds_dwordx4 v[190:191], off
	v_lshl_add_u64 v[190:191], v[218:219], 0, s[80:81]
	s_mov_b32 m0, s75
	s_nop 0
	global_load_lds_dwordx4 v[190:191], off
	s_barrier
	s_waitcnt lgkmcnt(0)
	s_setprio 1
	s_waitcnt lgkmcnt(0)
	v_mfma_f32_16x16x32_bf16 v[60:63], v[120:123], v[144:147], v[60:63]
	v_mfma_f32_16x16x32_bf16 v[56:59], v[136:139], v[144:147], v[56:59]
	v_mfma_f32_16x16x32_bf16 v[44:47], v[120:123], v[152:155], v[44:47]
	v_mfma_f32_16x16x32_bf16 v[40:43], v[136:139], v[152:155], v[40:43]
	v_mfma_f32_16x16x32_bf16 v[28:31], v[120:123], v[168:171], v[28:31]
	v_mfma_f32_16x16x32_bf16 v[24:27], v[136:139], v[168:171], v[24:27]
	v_mfma_f32_16x16x32_bf16 v[12:15], v[120:123], v[176:179], v[12:15]
	v_mfma_f32_16x16x32_bf16 v[8:11], v[136:139], v[176:179], v[8:11]
	v_mfma_f32_16x16x32_bf16 v[60:63], v[124:127], v[148:151], v[60:63]
	v_mfma_f32_16x16x32_bf16 v[56:59], v[140:143], v[148:151], v[56:59]
	v_mfma_f32_16x16x32_bf16 v[44:47], v[124:127], v[156:159], v[44:47]
	v_mfma_f32_16x16x32_bf16 v[40:43], v[140:143], v[156:159], v[40:43]
	v_mfma_f32_16x16x32_bf16 v[28:31], v[124:127], v[172:175], v[28:31]
	v_mfma_f32_16x16x32_bf16 v[24:27], v[140:143], v[172:175], v[24:27]
	v_mfma_f32_16x16x32_bf16 v[12:15], v[124:127], v[180:183], v[12:15]
	v_mfma_f32_16x16x32_bf16 v[8:11], v[140:143], v[180:183], v[8:11]
	s_setprio 0
	s_barrier
	s_add_u32 s12, s12, 0x40080
	s_addc_u32 s13, s13, 0
	s_add_i32 s14, s14, s67
	s_mov_b32 m0, s14
	s_nop 0
	global_load_lds_dwordx4 v160, s[12:13]
	v_lshl_add_u64 v[120:121], s[12:13], 0, v[162:163]
	s_add_i32 m0, s14, 0x2000
	s_nop 0
	global_load_lds_dwordx4 v[120:121], off
	s_waitcnt vmcnt(6)
	s_barrier
	s_setprio 1
	v_mfma_f32_16x16x32_bf16 v[52:55], v[184:187], v[144:147], v[52:55]
	v_mfma_f32_16x16x32_bf16 v[48:51], v[206:209], v[144:147], v[48:51]
	v_mfma_f32_16x16x32_bf16 v[36:39], v[184:187], v[152:155], v[36:39]
	v_mfma_f32_16x16x32_bf16 v[32:35], v[206:209], v[152:155], v[32:35]
	v_mfma_f32_16x16x32_bf16 v[20:23], v[184:187], v[168:171], v[20:23]
	v_mfma_f32_16x16x32_bf16 v[16:19], v[206:209], v[168:171], v[16:19]
	v_mfma_f32_16x16x32_bf16 v[4:7], v[184:187], v[176:179], v[4:7]
	v_mfma_f32_16x16x32_bf16 v[0:3], v[206:209], v[176:179], v[0:3]
	v_mfma_f32_16x16x32_bf16 v[52:55], v[198:201], v[148:151], v[52:55]
	v_mfma_f32_16x16x32_bf16 v[48:51], v[210:213], v[148:151], v[48:51]
	v_mfma_f32_16x16x32_bf16 v[36:39], v[198:201], v[156:159], v[36:39]
	v_mfma_f32_16x16x32_bf16 v[32:35], v[210:213], v[156:159], v[32:35]
	v_mfma_f32_16x16x32_bf16 v[20:23], v[198:201], v[172:175], v[20:23]
	v_mfma_f32_16x16x32_bf16 v[16:19], v[210:213], v[172:175], v[16:19]
	v_mfma_f32_16x16x32_bf16 v[4:7], v[198:201], v[180:183], v[4:7]
	v_mfma_f32_16x16x32_bf16 v[0:3], v[210:213], v[180:183], v[0:3]
	s_setprio 0
	s_add_i32 s18, s18, 2
	s_add_u32 s16, s16, 0x100
	s_addc_u32 s17, s17, 0
	s_add_u32 s10, s10, 0x100
	s_addc_u32 s11, s11, 0
	s_cmp_gt_u32 s18, 13
	s_barrier
	s_cbranch_scc0 .LBB0_279
	v_mov_b32_e32 v120, v252
	s_lshl_b32 s0, s8, 8
	v_readfirstlane_b32 s1, v120
	s_ashr_i32 s7, s1, 2
	s_andn2_b32 s7, s7, 63
	v_and_b32_e32 v121, 15, v120
	s_add_i32 s0, s7, s0
	v_or_b32_e32 v172, s0, v121
	v_ashrrev_i32_e32 v173, 31, v172
	v_lshl_add_u64 v[174:175], v[172:173], 2, s[34:35]
	global_load_dword v171, v[174:175], off
	s_lshr_b32 s1, s1, 1
	s_and_b32 s1, s1, 0x60
	s_lshl_b32 s6, s6, 8
	s_or_b32 s1, s1, s6
	v_lshrrev_b32_e32 v120, 2, v120
	s_cmpk_eq_i32 s1, 0x100
	v_and_b32_e32 v170, 12, v120
	s_movk_i32 s6, 0x4000
	v_mov_b32_e32 v120, 0x1fcf
	s_cselect_b64 s[8:9], -1, 0
	v_lshlrev_b32_e32 v168, 1, v170
	v_cmp_gt_i32_e64 s[10:11], s6, v172
	v_bitop3_b32 v169, s0, v120, v121 bitop3:0xc8
	v_mov_b32_e32 v144, 0
	s_and_b64 vcc, exec, s[8:9]
	v_mov_b32_e32 v152, 0
	v_mov_b32_e32 v153, 0
	v_mov_b32_e32 v154, 0
	v_mov_b32_e32 v155, 0
	v_mov_b32_e32 v156, 0
	v_mov_b32_e32 v157, 0
	v_mov_b32_e32 v158, 0
	v_mov_b32_e32 v159, 0
	s_cbranch_vccz .LBB0_282
	v_or_b32_e32 v120, 16, v169
	v_add_u32_e32 v121, 0x7ffc000, v172
	v_cndmask_b32_e64 v120, v121, v120, s[10:11]
	v_lshl_or_b32 v192, v120, 5, v168
	v_lshl_add_u64 v[120:121], v[192:193], 2, s[30:31]
	global_load_dwordx4 v[152:155], v[120:121], off
	global_load_dwordx4 v[156:159], v[120:121], off offset:16

.LBB0_402:
	s_add_u32 s20, s18, 0xfffc0080
	s_addc_u32 s21, s19, -1
	s_add_i32 s41, 0, 0x10000
	v_add_u32_e32 v142, s41, v145
	ds_read_b128 v[138:141], v142
	ds_read_b128 v[148:151], v142 offset:1024
	ds_read_b128 v[152:155], v142 offset:2048
	ds_read_b128 v[156:159], v142 offset:3072
	s_cmp_eq_u32 s40, 12
	s_cselect_b32 s23, s1, s21
	s_cselect_b32 s22, s9, s20
	s_cselect_b32 s21, s11, s39
	s_cselect_b32 s20, s33, s38
	s_add_i32 m0, s17, 0xc000
	ds_read_b128 v[160:163], v146
	ds_read_b128 v[164:167], v146 offset:1024
	ds_read_b128 v[168:171], v146 offset:2048
	ds_read_b128 v[172:175], v146 offset:3072
	ds_read_b128 v[176:179], v146 offset:4096
	ds_read_b128 v[180:183], v146 offset:5120
	ds_read_b128 v[184:187], v146 offset:6144
	ds_read_b128 v[188:191], v146 offset:7168
	global_load_lds_dwordx4 v136, s[18:19]
	v_lshl_add_u64 v[142:143], s[18:19], 0, v[134:135]
	s_add_i32 m0, s17, 0xe000
	s_nop 0
	global_load_lds_dwordx4 v[142:143], off
	s_waitcnt lgkmcnt(8)
	s_barrier
	s_waitcnt lgkmcnt(0)
	s_setprio 1
	s_waitcnt lgkmcnt(0)
	v_mfma_f32_16x16x32_bf16 v[124:127], v[138:141], v[160:163], v[124:127]
	v_mfma_f32_16x16x32_bf16 v[116:119], v[152:155], v[160:163], v[116:119]
	v_mfma_f32_16x16x32_bf16 v[108:111], v[138:141], v[168:171], v[108:111]
	v_mfma_f32_16x16x32_bf16 v[100:103], v[152:155], v[168:171], v[100:103]
	v_mfma_f32_16x16x32_bf16 v[92:95], v[138:141], v[176:179], v[92:95]
	v_mfma_f32_16x16x32_bf16 v[84:87], v[152:155], v[176:179], v[84:87]
	v_mfma_f32_16x16x32_bf16 v[76:79], v[138:141], v[184:187], v[76:79]
	v_mfma_f32_16x16x32_bf16 v[68:71], v[152:155], v[184:187], v[68:71]
	v_mfma_f32_16x16x32_bf16 v[124:127], v[148:151], v[164:167], v[124:127]
	v_mfma_f32_16x16x32_bf16 v[116:119], v[156:159], v[164:167], v[116:119]
	v_mfma_f32_16x16x32_bf16 v[108:111], v[148:151], v[172:175], v[108:111]
	v_mfma_f32_16x16x32_bf16 v[100:103], v[156:159], v[172:175], v[100:103]
	v_mfma_f32_16x16x32_bf16 v[92:95], v[148:151], v[180:183], v[92:95]
	v_mfma_f32_16x16x32_bf16 v[84:87], v[156:159], v[180:183], v[84:87]
	v_mfma_f32_16x16x32_bf16 v[76:79], v[148:151], v[188:191], v[76:79]
	v_mfma_f32_16x16x32_bf16 v[68:71], v[156:159], v[188:191], v[68:71]
	s_setprio 0
	s_barrier
	s_add_i32 s44, 0, 0x14000
	v_add_u32_e32 v142, s44, v145
	s_add_i32 s41, s41, s28
	ds_read_b128 v[198:201], v142
	ds_read_b128 v[206:209], v142 offset:1024
	ds_read_b128 v[210:213], v142 offset:2048
	ds_read_b128 v[214:217], v142 offset:3072
	v_lshl_add_u64 v[142:143], s[20:21], 0, v[192:193]
	s_mov_b32 m0, s41
	v_lshl_add_u64 v[218:219], s[20:21], 0, v[128:129]
	global_load_lds_dwordx4 v[142:143], off
	s_add_i32 m0, s41, 0x2000
	s_nop 0
	global_load_lds_dwordx4 v[218:219], off
	s_barrier
	s_waitcnt lgkmcnt(0)
	s_setprio 1
	s_waitcnt lgkmcnt(0)
	v_mfma_f32_16x16x32_bf16 v[120:123], v[198:201], v[160:163], v[120:123]
	v_mfma_f32_16x16x32_bf16 v[112:115], v[210:213], v[160:163], v[112:115]
	v_mfma_f32_16x16x32_bf16 v[104:107], v[198:201], v[168:171], v[104:107]
	v_mfma_f32_16x16x32_bf16 v[96:99], v[210:213], v[168:171], v[96:99]
	v_mfma_f32_16x16x32_bf16 v[88:91], v[198:201], v[176:179], v[88:91]
	v_mfma_f32_16x16x32_bf16 v[80:83], v[210:213], v[176:179], v[80:83]
	v_mfma_f32_16x16x32_bf16 v[72:75], v[198:201], v[184:187], v[72:75]
	v_mfma_f32_16x16x32_bf16 v[64:67], v[210:213], v[184:187], v[64:67]
	v_mfma_f32_16x16x32_bf16 v[120:123], v[206:209], v[164:167], v[120:123]
	v_mfma_f32_16x16x32_bf16 v[112:115], v[214:217], v[164:167], v[112:115]
	v_mfma_f32_16x16x32_bf16 v[104:107], v[206:209], v[172:175], v[104:107]
	v_mfma_f32_16x16x32_bf16 v[96:99], v[214:217], v[172:175], v[96:99]
	v_mfma_f32_16x16x32_bf16 v[88:91], v[206:209], v[180:183], v[88:91]
	v_mfma_f32_16x16x32_bf16 v[80:83], v[214:217], v[180:183], v[80:83]
	v_mfma_f32_16x16x32_bf16 v[72:75], v[206:209], v[188:191], v[72:75]
	v_mfma_f32_16x16x32_bf16 v[64:67], v[214:217], v[188:191], v[64:67]
	s_setprio 0
	s_mov_b32 m0, s17
	v_lshl_add_u64 v[220:221], s[22:23], 0, v[132:133]
	s_barrier
	ds_read_b128 v[160:163], v146 offset:16384
	ds_read_b128 v[164:167], v146 offset:17408
	ds_read_b128 v[168:171], v146 offset:18432
	ds_read_b128 v[172:175], v146 offset:19456
	ds_read_b128 v[176:179], v146 offset:20480
	ds_read_b128 v[180:183], v146 offset:21504
	ds_read_b128 v[184:187], v146 offset:22528
	ds_read_b128 v[188:191], v146 offset:23552
	global_load_lds_dwordx4 v[220:221], off
	v_lshl_add_u64 v[222:223], s[22:23], 0, v[130:131]
	s_mov_b32 m0, s29
	s_nop 0
	global_load_lds_dwordx4 v[222:223], off
	s_barrier
	s_waitcnt lgkmcnt(0)
	s_setprio 1
	s_waitcnt lgkmcnt(0)
	v_mfma_f32_16x16x32_bf16 v[60:63], v[138:141], v[160:163], v[60:63]
	v_mfma_f32_16x16x32_bf16 v[52:55], v[152:155], v[160:163], v[52:55]
	v_mfma_f32_16x16x32_bf16 v[44:47], v[138:141], v[168:171], v[44:47]
	v_mfma_f32_16x16x32_bf16 v[36:39], v[152:155], v[168:171], v[36:39]
	v_mfma_f32_16x16x32_bf16 v[28:31], v[138:141], v[176:179], v[28:31]
	v_mfma_f32_16x16x32_bf16 v[20:23], v[152:155], v[176:179], v[20:23]
	v_mfma_f32_16x16x32_bf16 v[12:15], v[138:141], v[184:187], v[12:15]
	v_mfma_f32_16x16x32_bf16 v[4:7], v[152:155], v[184:187], v[4:7]
	v_mfma_f32_16x16x32_bf16 v[60:63], v[148:151], v[164:167], v[60:63]
	v_mfma_f32_16x16x32_bf16 v[52:55], v[156:159], v[164:167], v[52:55]
	v_mfma_f32_16x16x32_bf16 v[44:47], v[148:151], v[172:175], v[44:47]
	v_mfma_f32_16x16x32_bf16 v[36:39], v[156:159], v[172:175], v[36:39]
	v_mfma_f32_16x16x32_bf16 v[28:31], v[148:151], v[180:183], v[28:31]
	v_mfma_f32_16x16x32_bf16 v[20:23], v[156:159], v[180:183], v[20:23]
	v_mfma_f32_16x16x32_bf16 v[12:15], v[148:151], v[188:191], v[12:15]
	v_mfma_f32_16x16x32_bf16 v[4:7], v[156:159], v[188:191], v[4:7]
	s_setprio 0
	s_barrier
	s_add_u32 s42, s20, 0x40000
	s_addc_u32 s43, s21, 0
	s_add_i32 s41, s44, s28
	v_lshl_add_u64 v[138:139], s[42:43], 0, v[192:193]
	s_mov_b32 m0, s41
	s_nop 0
	global_load_lds_dwordx4 v[138:139], off
	v_lshl_add_u64 v[138:139], s[42:43], 0, v[128:129]
	s_add_i32 m0, s41, 0x2000
	s_nop 0
	global_load_lds_dwordx4 v[138:139], off
	s_waitcnt vmcnt(6)
	s_barrier
	s_setprio 1
	v_mfma_f32_16x16x32_bf16 v[56:59], v[198:201], v[160:163], v[56:59]
	v_mfma_f32_16x16x32_bf16 v[48:51], v[210:213], v[160:163], v[48:51]
	v_mfma_f32_16x16x32_bf16 v[40:43], v[198:201], v[168:171], v[40:43]
	v_mfma_f32_16x16x32_bf16 v[32:35], v[210:213], v[168:171], v[32:35]
	v_mfma_f32_16x16x32_bf16 v[24:27], v[198:201], v[176:179], v[24:27]
	v_mfma_f32_16x16x32_bf16 v[16:19], v[210:213], v[176:179], v[16:19]
	v_mfma_f32_16x16x32_bf16 v[8:11], v[198:201], v[184:187], v[8:11]
	v_mfma_f32_16x16x32_bf16 v[0:3], v[210:213], v[184:187], v[0:3]
	v_mfma_f32_16x16x32_bf16 v[56:59], v[206:209], v[164:167], v[56:59]
	v_mfma_f32_16x16x32_bf16 v[48:51], v[214:217], v[164:167], v[48:51]
	v_mfma_f32_16x16x32_bf16 v[40:43], v[206:209], v[172:175], v[40:43]
	v_mfma_f32_16x16x32_bf16 v[32:35], v[214:217], v[172:175], v[32:35]
	v_mfma_f32_16x16x32_bf16 v[24:27], v[206:209], v[180:183], v[24:27]
	v_mfma_f32_16x16x32_bf16 v[16:19], v[214:217], v[180:183], v[16:19]
	v_mfma_f32_16x16x32_bf16 v[8:11], v[206:209], v[188:191], v[8:11]
	v_mfma_f32_16x16x32_bf16 v[0:3], v[214:217], v[188:191], v[0:3]
	s_setprio 0
	s_add_i32 s41, 0, 0x18000
	v_add_u32_e32 v144, s41, v145
	s_barrier
	ds_read_b128 v[138:141], v144
	ds_read_b128 v[148:151], v144 offset:1024
	ds_read_b128 v[152:155], v144 offset:2048
	ds_read_b128 v[156:159], v144 offset:3072
	s_add_u32 s22, s22, 0x40000
	s_addc_u32 s23, s23, 0
	s_mov_b32 m0, s30
	ds_read_b128 v[160:163], v146 offset:32768
	ds_read_b128 v[164:167], v146 offset:33792
	ds_read_b128 v[168:171], v146 offset:34816
	ds_read_b128 v[172:175], v146 offset:35840
	ds_read_b128 v[176:179], v146 offset:36864
	ds_read_b128 v[180:183], v146 offset:37888
	ds_read_b128 v[184:187], v146 offset:38912
	ds_read_b128 v[188:191], v146 offset:39936
	global_load_lds_dwordx4 v132, s[22:23]
	v_lshl_add_u64 v[198:199], s[22:23], 0, v[130:131]
	s_mov_b32 m0, s31
	s_nop 0
	global_load_lds_dwordx4 v[198:199], off
	s_waitcnt lgkmcnt(8)
	s_barrier
	s_waitcnt lgkmcnt(0)
	s_setprio 1
	s_waitcnt lgkmcnt(0)
	v_mfma_f32_16x16x32_bf16 v[124:127], v[138:141], v[160:163], v[124:127]
	v_mfma_f32_16x16x32_bf16 v[116:119], v[152:155], v[160:163], v[116:119]
	v_mfma_f32_16x16x32_bf16 v[108:111], v[138:141], v[168:171], v[108:111]
	v_mfma_f32_16x16x32_bf16 v[100:103], v[152:155], v[168:171], v[100:103]
	v_mfma_f32_16x16x32_bf16 v[92:95], v[138:141], v[176:179], v[92:95]
	v_mfma_f32_16x16x32_bf16 v[84:87], v[152:155], v[176:179], v[84:87]
	v_mfma_f32_16x16x32_bf16 v[76:79], v[138:141], v[184:187], v[76:79]
	v_mfma_f32_16x16x32_bf16 v[68:71], v[152:155], v[184:187], v[68:71]
	v_mfma_f32_16x16x32_bf16 v[124:127], v[148:151], v[164:167], v[124:127]
	v_mfma_f32_16x16x32_bf16 v[116:119], v[156:159], v[164:167], v[116:119]
	v_mfma_f32_16x16x32_bf16 v[108:111], v[148:151], v[172:175], v[108:111]
	v_mfma_f32_16x16x32_bf16 v[100:103], v[156:159], v[172:175], v[100:103]
	v_mfma_f32_16x16x32_bf16 v[92:95], v[148:151], v[180:183], v[92:95]
	v_mfma_f32_16x16x32_bf16 v[84:87], v[156:159], v[180:183], v[84:87]
	v_mfma_f32_16x16x32_bf16 v[76:79], v[148:151], v[188:191], v[76:79]
	v_mfma_f32_16x16x32_bf16 v[68:71], v[156:159], v[188:191], v[68:71]
	s_setprio 0
	s_barrier
	s_add_i32 s22, 0, 0x1c000
	s_add_i32 s23, s41, s28
	v_add_u32_e32 v144, s22, v145
	v_lshl_add_u64 v[142:143], v[142:143], 0, s[80:81]
	s_mov_b32 m0, s23
	ds_read_b128 v[198:201], v144
	ds_read_b128 v[206:209], v144 offset:1024
	ds_read_b128 v[210:213], v144 offset:2048
	ds_read_b128 v[214:217], v144 offset:3072
	global_load_lds_dwordx4 v[142:143], off
	v_lshl_add_u64 v[142:143], v[218:219], 0, s[80:81]
	s_add_i32 m0, s23, 0x2000
	s_nop 0
	global_load_lds_dwordx4 v[142:143], off
	s_barrier
	s_waitcnt lgkmcnt(0)
	s_setprio 1
	s_waitcnt lgkmcnt(0)
	v_mfma_f32_16x16x32_bf16 v[120:123], v[198:201], v[160:163], v[120:123]
	v_mfma_f32_16x16x32_bf16 v[112:115], v[210:213], v[160:163], v[112:115]
	v_mfma_f32_16x16x32_bf16 v[104:107], v[198:201], v[168:171], v[104:107]
	v_mfma_f32_16x16x32_bf16 v[96:99], v[210:213], v[168:171], v[96:99]
	v_mfma_f32_16x16x32_bf16 v[88:91], v[198:201], v[176:179], v[88:91]
	v_mfma_f32_16x16x32_bf16 v[80:83], v[210:213], v[176:179], v[80:83]
	v_mfma_f32_16x16x32_bf16 v[72:75], v[198:201], v[184:187], v[72:75]
	v_mfma_f32_16x16x32_bf16 v[64:67], v[210:213], v[184:187], v[64:67]
	v_mfma_f32_16x16x32_bf16 v[120:123], v[206:209], v[164:167], v[120:123]
	v_mfma_f32_16x16x32_bf16 v[112:115], v[214:217], v[164:167], v[112:115]
	v_mfma_f32_16x16x32_bf16 v[104:107], v[206:209], v[172:175], v[104:107]
	v_mfma_f32_16x16x32_bf16 v[96:99], v[214:217], v[172:175], v[96:99]
	v_mfma_f32_16x16x32_bf16 v[88:91], v[206:209], v[180:183], v[88:91]
	v_mfma_f32_16x16x32_bf16 v[80:83], v[214:217], v[180:183], v[80:83]
	v_mfma_f32_16x16x32_bf16 v[72:75], v[206:209], v[188:191], v[72:75]
	v_mfma_f32_16x16x32_bf16 v[64:67], v[214:217], v[188:191], v[64:67]
	s_setprio 0
	s_mov_b32 m0, s34
	v_lshl_add_u64 v[142:143], v[220:221], 0, s[80:81]
	s_barrier
	ds_read_b128 v[160:163], v146 offset:49152
	ds_read_b128 v[164:167], v146 offset:50176
	ds_read_b128 v[168:171], v146 offset:51200
	ds_read_b128 v[172:175], v146 offset:52224
	ds_read_b128 v[176:179], v146 offset:53248
	ds_read_b128 v[180:183], v146 offset:54272
	ds_read_b128 v[184:187], v146 offset:55296
	ds_read_b128 v[188:191], v146 offset:56320
	global_load_lds_dwordx4 v[142:143], off
	v_lshl_add_u64 v[142:143], v[222:223], 0, s[80:81]
	s_mov_b32 m0, s35
	s_nop 0
	global_load_lds_dwordx4 v[142:143], off
	s_barrier
	s_waitcnt lgkmcnt(0)
	s_setprio 1
	s_waitcnt lgkmcnt(0)
	v_mfma_f32_16x16x32_bf16 v[60:63], v[138:141], v[160:163], v[60:63]
	v_mfma_f32_16x16x32_bf16 v[52:55], v[152:155], v[160:163], v[52:55]
	v_mfma_f32_16x16x32_bf16 v[44:47], v[138:141], v[168:171], v[44:47]
	v_mfma_f32_16x16x32_bf16 v[36:39], v[152:155], v[168:171], v[36:39]
	v_mfma_f32_16x16x32_bf16 v[28:31], v[138:141], v[176:179], v[28:31]
	v_mfma_f32_16x16x32_bf16 v[20:23], v[152:155], v[176:179], v[20:23]
	v_mfma_f32_16x16x32_bf16 v[12:15], v[138:141], v[184:187], v[12:15]
	v_mfma_f32_16x16x32_bf16 v[4:7], v[152:155], v[184:187], v[4:7]
	v_mfma_f32_16x16x32_bf16 v[60:63], v[148:151], v[164:167], v[60:63]
	v_mfma_f32_16x16x32_bf16 v[52:55], v[156:159], v[164:167], v[52:55]
	v_mfma_f32_16x16x32_bf16 v[44:47], v[148:151], v[172:175], v[44:47]
	v_mfma_f32_16x16x32_bf16 v[36:39], v[156:159], v[172:175], v[36:39]
	v_mfma_f32_16x16x32_bf16 v[28:31], v[148:151], v[180:183], v[28:31]
	v_mfma_f32_16x16x32_bf16 v[20:23], v[156:159], v[180:183], v[20:23]
	v_mfma_f32_16x16x32_bf16 v[12:15], v[148:151], v[188:191], v[12:15]
	v_mfma_f32_16x16x32_bf16 v[4:7], v[156:159], v[188:191], v[4:7]
	s_setprio 0
	s_barrier
	s_add_u32 s20, s20, 0x40080
	s_addc_u32 s21, s21, 0
	s_add_i32 s22, s22, s28
	v_lshl_add_u64 v[138:139], s[20:21], 0, v[192:193]
	s_mov_b32 m0, s22
	s_nop 0
	global_load_lds_dwordx4 v[138:139], off
	v_lshl_add_u64 v[138:139], s[20:21], 0, v[128:129]
	s_add_i32 m0, s22, 0x2000
	s_nop 0
	global_load_lds_dwordx4 v[138:139], off
	s_waitcnt vmcnt(6)
	s_barrier
	s_setprio 1
	v_mfma_f32_16x16x32_bf16 v[56:59], v[198:201], v[160:163], v[56:59]
	v_mfma_f32_16x16x32_bf16 v[48:51], v[210:213], v[160:163], v[48:51]
	v_mfma_f32_16x16x32_bf16 v[40:43], v[198:201], v[168:171], v[40:43]
	v_mfma_f32_16x16x32_bf16 v[32:35], v[210:213], v[168:171], v[32:35]
	v_mfma_f32_16x16x32_bf16 v[24:27], v[198:201], v[176:179], v[24:27]
	v_mfma_f32_16x16x32_bf16 v[16:19], v[210:213], v[176:179], v[16:19]
	v_mfma_f32_16x16x32_bf16 v[8:11], v[198:201], v[184:187], v[8:11]
	v_mfma_f32_16x16x32_bf16 v[0:3], v[210:213], v[184:187], v[0:3]
	v_mfma_f32_16x16x32_bf16 v[56:59], v[206:209], v[164:167], v[56:59]
	v_mfma_f32_16x16x32_bf16 v[48:51], v[214:217], v[164:167], v[48:51]
	v_mfma_f32_16x16x32_bf16 v[40:43], v[206:209], v[172:175], v[40:43]
	v_mfma_f32_16x16x32_bf16 v[32:35], v[214:217], v[172:175], v[32:35]
	v_mfma_f32_16x16x32_bf16 v[24:27], v[206:209], v[180:183], v[24:27]
	v_mfma_f32_16x16x32_bf16 v[16:19], v[214:217], v[180:183], v[16:19]
	v_mfma_f32_16x16x32_bf16 v[8:11], v[206:209], v[188:191], v[8:11]
	v_mfma_f32_16x16x32_bf16 v[0:3], v[214:217], v[188:191], v[0:3]
	s_setprio 0
	s_add_i32 s40, s40, 2
	s_add_u32 s38, s38, 0x100
	s_addc_u32 s39, s39, 0
	s_add_u32 s18, s18, 0x100
	s_addc_u32 s19, s19, 0
	s_cmp_gt_u32 s40, 13
	s_barrier
	s_cbranch_scc0 .LBB0_402
	v_mov_b32_e32 v139, v252
	s_lshl_b32 s9, s16, 8
	v_readfirstlane_b32 s1, v139
	s_ashr_i32 s11, s1, 2
	s_andn2_b32 s11, s11, 63
	s_lshr_b32 s1, s1, 1
	s_add_i32 s11, s11, s9
	s_lshl_b32 s0, s0, 7
	s_and_b32 s1, s1, 0x60
	v_and_or_b32 v138, v139, 15, s11
	s_or_b32 s0, s1, s0
	v_lshrrev_b32_e32 v139, 1, v139
	v_and_or_b32 v142, v139, 24, s0
	v_ashrrev_i32_e32 v139, 31, v138
	v_lshl_add_u64 v[140:141], v[138:139], 2, s[6:7]
	v_pk_mul_f32 v[120:121], v[124:125], v[120:121]
	v_pk_mul_f32 v[122:123], v[126:127], v[122:123]
	v_pk_mul_f32 v[112:113], v[116:117], v[112:113]
	v_pk_mul_f32 v[114:115], v[118:119], v[114:115]
	v_ashrrev_i32_e32 v143, 31, v142
	s_movk_i32 s9, 0x1600
	v_pk_mul_f32 v[104:105], v[108:109], v[104:105]
	v_pk_mul_f32 v[106:107], v[110:111], v[106:107]
	v_pk_mul_f32 v[96:97], v[100:101], v[96:97]
	v_or_b32_e32 v150, 16, v138
	v_pk_mul_f32 v[98:99], v[102:103], v[98:99]
	v_pk_mul_f32 v[88:89], v[92:93], v[88:89]
	v_pk_mul_f32 v[90:91], v[94:95], v[90:91]
	v_pk_mul_f32 v[80:81], v[84:85], v[80:81]
	v_or_b32_e32 v148, 32, v138
	v_pk_mul_f32 v[82:83], v[86:87], v[82:83]
	v_pk_mul_f32 v[72:73], v[76:77], v[72:73]
	v_pk_mul_f32 v[74:75], v[78:79], v[74:75]
	v_pk_mul_f32 v[64:65], v[68:69], v[64:65]
	v_or_b32_e32 v139, 48, v138
	v_pk_mul_f32 v[66:67], v[70:71], v[66:67]
	v_pk_mul_f32 v[56:57], v[60:61], v[56:57]
	v_pk_mul_f32 v[58:59], v[62:63], v[58:59]
	v_pk_mul_f32 v[48:49], v[52:53], v[48:49]
	v_pk_mul_f32 v[50:51], v[54:55], v[50:51]
	v_pk_mul_f32 v[40:41], v[44:45], v[40:41]
	v_pk_mul_f32 v[42:43], v[46:47], v[42:43]
	v_pk_mul_f32 v[32:33], v[36:37], v[32:33]
	v_pk_mul_f32 v[34:35], v[38:39], v[34:35]
	v_pk_mul_f32 v[24:25], v[28:29], v[24:25]
	v_pk_mul_f32 v[26:27], v[30:31], v[26:27]
	v_pk_mul_f32 v[16:17], v[20:21], v[16:17]
	v_pk_mul_f32 v[18:19], v[22:23], v[18:19]
	v_pk_mul_f32 v[8:9], v[12:13], v[8:9]
	v_pk_mul_f32 v[10:11], v[14:15], v[10:11]
	v_pk_mul_f32 v[0:1], v[4:5], v[0:1]
	v_pk_mul_f32 v[2:3], v[6:7], v[2:3]
	s_mov_b32 s16, s8
	s_mov_b64 s[18:19], s[14:15]
	s_mov_b64 s[20:21], s[12:13]
	v_fmamk_f32 v144, v231, 0x3a800000, v194
	v_cmp_gt_f32_e32 vcc, s2, v144
	v_mul_f32_e32 v152, 0x4b800000, v144
	s_nop 0
	v_cndmask_b32_e32 v144, v144, v152, vcc
	v_rsq_f32_e32 v144, v144
	s_nop 0
	v_mul_f32_e32 v152, 0x45800000, v144
	v_cndmask_b32_e32 v144, v144, v152, vcc
	v_mul_f32_e32 v152, 0xbfb8aa3b, v144
	v_pk_mul_f32 v[156:157], v[124:125], v[152:153] op_sel_hi:[1,0]
	v_pk_mul_f32 v[154:155], v[126:127], v[152:153] op_sel_hi:[1,0]
	v_exp_f32_e32 v153, v156
	v_mul_f32_e32 v144, v144, v144
	v_add_f32_e32 v153, 1.0, v153
	v_rcp_f32_e32 v156, v153
	v_exp_f32_e32 v153, v157
	s_nop 0
	v_add_f32_e32 v153, 1.0, v153
	v_rcp_f32_e32 v157, v153
	v_exp_f32_e32 v153, v154
	v_pk_mul_f32 v[124:125], v[144:145], v[156:157] op_sel_hi:[0,1]
	v_add_f32_e32 v153, 1.0, v153
	v_rcp_f32_e32 v154, v153
	v_exp_f32_e32 v153, v155
	v_pk_mul_f32 v[120:121], v[120:121], v[124:125]
	v_add_f32_e32 v153, 1.0, v153
	v_rcp_f32_e32 v155, v153
	v_cvt_pk_bf16_f32 v124, v121, s0
	v_cvt_pk_bf16_f32 v120, v120, s0
	v_readlane_b32 s0, v254, 29
	v_pk_mul_f32 v[126:127], v[144:145], v[154:155] op_sel_hi:[0,1]
	v_pk_mul_f32 v[122:123], v[122:123], v[126:127]
	v_readlane_b32 s1, v254, 30
	v_cvt_pk_bf16_f32 v121, v122, v123
	v_lshlrev_b32_e32 v122, 16, v124
	v_pk_mul_f32 v[124:125], v[116:117], v[152:153] op_sel_hi:[1,0]
	v_or_b32_sdwa v120, v122, v120 dst_sel:DWORD dst_unused:UNUSED_PAD src0_sel:DWORD src1_sel:WORD_0
	v_pk_mul_f32 v[122:123], v[118:119], v[152:153] op_sel_hi:[1,0]
	v_exp_f32_e32 v124, v124
	v_exp_f32_e32 v125, v125
	v_exp_f32_e32 v122, v122
	v_exp_f32_e32 v123, v123
	v_add_f32_e32 v124, 1.0, v124
	v_add_f32_e32 v125, 1.0, v125
	v_rcp_f32_e32 v124, v124
	v_rcp_f32_e32 v125, v125
	v_add_f32_e32 v122, 1.0, v122
	v_add_f32_e32 v123, 1.0, v123
	v_rcp_f32_e32 v122, v122
	v_rcp_f32_e32 v123, v123
	v_pk_mul_f32 v[116:117], v[144:145], v[124:125] op_sel_hi:[0,1]
	v_pk_mul_f32 v[112:113], v[112:113], v[116:117]
	v_pk_mul_f32 v[118:119], v[144:145], v[122:123] op_sel_hi:[0,1]
	v_pk_mul_f32 v[114:115], v[114:115], v[118:119]
	v_cvt_pk_bf16_f32 v122, v112, v113
	v_mov_b64_e32 v[112:113], s[0:1]
	v_cvt_pk_bf16_f32 v123, v114, v115
	v_mad_i64_i32 v[116:117], s[0:1], v138, s9, v[112:113]
	v_lshlrev_b64 v[114:115], 1, v[142:143]
	v_lshl_add_u64 v[116:117], v[116:117], 0, v[114:115]
	global_store_dwordx4 v[116:117], v[120:123], off
	v_fmamk_f32 v116, v232, 0x3a800000, v194
	v_cmp_gt_f32_e32 vcc, s2, v116
	v_mul_f32_e32 v117, 0x4b800000, v116
	s_nop 0
	v_cndmask_b32_e32 v116, v116, v117, vcc
	v_rsq_f32_e32 v116, v116
	s_nop 0
	v_mul_f32_e32 v117, 0x45800000, v116
	v_cndmask_b32_e32 v116, v116, v117, vcc
	v_mul_f32_e32 v118, 0xbfb8aa3b, v116
	v_pk_mul_f32 v[120:121], v[108:109], v[118:119] op_sel_hi:[1,0]
	v_pk_mul_f32 v[122:123], v[110:111], v[118:119] op_sel_hi:[1,0]
	v_exp_f32_e32 v117, v120
	v_mul_f32_e32 v116, v116, v116
	v_add_f32_e32 v117, 1.0, v117
	v_rcp_f32_e32 v120, v117
	v_exp_f32_e32 v117, v121
	s_nop 0
	v_add_f32_e32 v117, 1.0, v117
	v_rcp_f32_e32 v121, v117
	v_exp_f32_e32 v117, v122
	s_nop 0
	v_add_f32_e32 v117, 1.0, v117
	v_rcp_f32_e32 v122, v117
	v_exp_f32_e32 v117, v123
	s_nop 0
	v_add_f32_e32 v117, 1.0, v117
	v_rcp_f32_e32 v123, v117
	v_pk_mul_f32 v[108:109], v[116:117], v[120:121] op_sel_hi:[0,1]
	v_pk_mul_f32 v[104:105], v[104:105], v[108:109]
	v_pk_mul_f32 v[110:111], v[116:117], v[122:123] op_sel_hi:[0,1]
	v_pk_mul_f32 v[106:107], v[106:107], v[110:111]
	v_cvt_pk_bf16_f32 v108, v105, s0
	v_cvt_pk_bf16_f32 v104, v104, s0
	v_cvt_pk_bf16_f32 v105, v106, v107
	v_lshlrev_b32_e32 v106, 16, v108
	v_pk_mul_f32 v[108:109], v[100:101], v[118:119] op_sel_hi:[1,0]
	v_or_b32_sdwa v104, v106, v104 dst_sel:DWORD dst_unused:UNUSED_PAD src0_sel:DWORD src1_sel:WORD_0
	v_pk_mul_f32 v[106:107], v[102:103], v[118:119] op_sel_hi:[1,0]
	v_exp_f32_e32 v108, v108
	v_exp_f32_e32 v109, v109
	v_exp_f32_e32 v106, v106
	v_exp_f32_e32 v107, v107
	v_add_f32_e32 v108, 1.0, v108
	v_add_f32_e32 v109, 1.0, v109
	v_rcp_f32_e32 v108, v108
	v_rcp_f32_e32 v109, v109
	v_add_f32_e32 v106, 1.0, v106
	v_add_f32_e32 v107, 1.0, v107
	v_rcp_f32_e32 v106, v106
	v_rcp_f32_e32 v107, v107
	v_pk_mul_f32 v[100:101], v[116:117], v[108:109] op_sel_hi:[0,1]
	v_pk_mul_f32 v[96:97], v[96:97], v[100:101]
	v_pk_mul_f32 v[102:103], v[116:117], v[106:107] op_sel_hi:[0,1]
	v_pk_mul_f32 v[98:99], v[98:99], v[102:103]
	v_cvt_pk_bf16_f32 v106, v96, v97
	v_mad_i64_i32 v[96:97], s[0:1], v150, s9, v[112:113]
	v_cvt_pk_bf16_f32 v107, v98, v99
	v_lshl_add_u64 v[96:97], v[96:97], 0, v[114:115]
	global_store_dwordx4 v[96:97], v[104:107], off
	v_fmamk_f32 v96, v233, 0x3a800000, v194
	v_cmp_gt_f32_e32 vcc, s2, v96
	v_mul_f32_e32 v97, 0x4b800000, v96
	s_nop 0
	v_cndmask_b32_e32 v96, v96, v97, vcc
	v_rsq_f32_e32 v96, v96
	s_nop 0
	v_mul_f32_e32 v97, 0x45800000, v96
	v_cndmask_b32_e32 v97, v96, v97, vcc
	v_mul_f32_e32 v96, 0xbfb8aa3b, v97
	v_pk_mul_f32 v[102:103], v[92:93], v[96:97] op_sel_hi:[1,0]
	v_mul_f32_e32 v98, v97, v97
	v_pk_mul_f32 v[100:101], v[94:95], v[96:97] op_sel_hi:[1,0]
	v_exp_f32_e32 v97, v102
	s_nop 0
	v_add_f32_e32 v97, 1.0, v97
	v_rcp_f32_e32 v102, v97
	v_exp_f32_e32 v97, v103
	s_nop 0
	v_add_f32_e32 v97, 1.0, v97
	v_rcp_f32_e32 v103, v97
	v_exp_f32_e32 v97, v100
	v_pk_mul_f32 v[92:93], v[98:99], v[102:103] op_sel_hi:[0,1]
	v_add_f32_e32 v97, 1.0, v97
	v_rcp_f32_e32 v100, v97
	v_exp_f32_e32 v97, v101
	v_pk_mul_f32 v[88:89], v[88:89], v[92:93]
	v_add_f32_e32 v97, 1.0, v97
	v_rcp_f32_e32 v101, v97
	v_cvt_pk_bf16_f32 v92, v89, s0
	v_cvt_pk_bf16_f32 v88, v88, s0
	v_pk_mul_f32 v[94:95], v[98:99], v[100:101] op_sel_hi:[0,1]
	v_pk_mul_f32 v[90:91], v[90:91], v[94:95]
	s_nop 0
	v_cvt_pk_bf16_f32 v89, v90, v91
	v_lshlrev_b32_e32 v90, 16, v92
	v_pk_mul_f32 v[92:93], v[84:85], v[96:97] op_sel_hi:[1,0]
	v_or_b32_sdwa v88, v90, v88 dst_sel:DWORD dst_unused:UNUSED_PAD src0_sel:DWORD src1_sel:WORD_0
	v_pk_mul_f32 v[90:91], v[86:87], v[96:97] op_sel_hi:[1,0]
	v_exp_f32_e32 v92, v92
	v_exp_f32_e32 v93, v93
	v_exp_f32_e32 v90, v90
	v_exp_f32_e32 v91, v91
	v_add_f32_e32 v92, 1.0, v92
	v_add_f32_e32 v93, 1.0, v93
	v_rcp_f32_e32 v92, v92
	v_rcp_f32_e32 v93, v93
	v_add_f32_e32 v90, 1.0, v90
	v_add_f32_e32 v91, 1.0, v91
	v_rcp_f32_e32 v90, v90
	v_rcp_f32_e32 v91, v91
	v_pk_mul_f32 v[84:85], v[98:99], v[92:93] op_sel_hi:[0,1]
	v_pk_mul_f32 v[80:81], v[80:81], v[84:85]
	v_pk_mul_f32 v[86:87], v[98:99], v[90:91] op_sel_hi:[0,1]
	v_pk_mul_f32 v[82:83], v[82:83], v[86:87]
	v_cvt_pk_bf16_f32 v90, v80, v81
	v_mad_i64_i32 v[80:81], s[0:1], v148, s9, v[112:113]
	v_cvt_pk_bf16_f32 v91, v82, v83
	v_lshl_add_u64 v[80:81], v[80:81], 0, v[114:115]
	global_store_dwordx4 v[80:81], v[88:91], off
	v_fmamk_f32 v80, v234, 0x3a800000, v194
	v_cmp_gt_f32_e32 vcc, s2, v80
	v_mul_f32_e32 v81, 0x4b800000, v80
	s_nop 0
	v_cndmask_b32_e32 v80, v80, v81, vcc
	v_rsq_f32_e32 v80, v80
	s_nop 0
	v_mul_f32_e32 v81, 0x45800000, v80
	v_cndmask_b32_e32 v81, v80, v81, vcc
	v_mul_f32_e32 v80, 0xbfb8aa3b, v81
	v_pk_mul_f32 v[86:87], v[76:77], v[80:81] op_sel_hi:[1,0]
	v_mul_f32_e32 v82, v81, v81
	v_pk_mul_f32 v[84:85], v[78:79], v[80:81] op_sel_hi:[1,0]
	v_exp_f32_e32 v81, v86
	s_nop 0
	v_add_f32_e32 v81, 1.0, v81
	v_rcp_f32_e32 v86, v81
	v_exp_f32_e32 v81, v87
	s_nop 0
	v_add_f32_e32 v81, 1.0, v81
	v_rcp_f32_e32 v87, v81
	v_exp_f32_e32 v81, v84
	v_pk_mul_f32 v[76:77], v[82:83], v[86:87] op_sel_hi:[0,1]
	v_add_f32_e32 v81, 1.0, v81
	v_rcp_f32_e32 v84, v81
	v_exp_f32_e32 v81, v85
	v_pk_mul_f32 v[72:73], v[72:73], v[76:77]
	v_add_f32_e32 v81, 1.0, v81
	v_rcp_f32_e32 v85, v81
	v_cvt_pk_bf16_f32 v76, v73, s0
	v_cvt_pk_bf16_f32 v72, v72, s0
	v_pk_mul_f32 v[78:79], v[82:83], v[84:85] op_sel_hi:[0,1]
	v_pk_mul_f32 v[74:75], v[74:75], v[78:79]
	s_nop 0
	v_cvt_pk_bf16_f32 v73, v74, v75
	v_lshlrev_b32_e32 v74, 16, v76
	v_pk_mul_f32 v[76:77], v[68:69], v[80:81] op_sel_hi:[1,0]
	v_or_b32_sdwa v72, v74, v72 dst_sel:DWORD dst_unused:UNUSED_PAD src0_sel:DWORD src1_sel:WORD_0
	v_pk_mul_f32 v[74:75], v[70:71], v[80:81] op_sel_hi:[1,0]
	v_exp_f32_e32 v76, v76
	v_exp_f32_e32 v77, v77
	v_exp_f32_e32 v74, v74
	v_exp_f32_e32 v75, v75
	v_add_f32_e32 v76, 1.0, v76
	v_add_f32_e32 v77, 1.0, v77
	v_rcp_f32_e32 v76, v76
	v_rcp_f32_e32 v77, v77
	v_add_f32_e32 v74, 1.0, v74
	v_add_f32_e32 v75, 1.0, v75
	v_rcp_f32_e32 v74, v74
	v_rcp_f32_e32 v75, v75
	v_pk_mul_f32 v[68:69], v[82:83], v[76:77] op_sel_hi:[0,1]
	v_pk_mul_f32 v[64:65], v[64:65], v[68:69]
	v_add_u32_e32 v69, 0x90, v138
	v_pk_mul_f32 v[70:71], v[82:83], v[74:75] op_sel_hi:[0,1]
	v_pk_mul_f32 v[66:67], v[66:67], v[70:71]
	v_cvt_pk_bf16_f32 v74, v64, v65
	v_mad_i64_i32 v[64:65], s[0:1], v139, s9, v[112:113]
	v_cvt_pk_bf16_f32 v75, v66, v67
	v_lshl_add_u64 v[64:65], v[64:65], 0, v[114:115]
	global_store_dwordx4 v[64:65], v[72:75], off
	v_add_u32_e32 v67, 0x80, v138
	v_add_u32_e32 v66, 0xa0, v138
	v_add_u32_e32 v64, 0xb0, v138
	v_fmamk_f32 v68, v235, 0x3a800000, v194
	v_cmp_gt_f32_e32 vcc, s2, v68
	v_mul_f32_e32 v70, 0x4b800000, v68
	s_nop 0
	v_cndmask_b32_e32 v68, v68, v70, vcc
	v_rsq_f32_e32 v68, v68
	s_nop 0
	v_mul_f32_e32 v70, 0x45800000, v68
	v_cndmask_b32_e32 v70, v68, v70, vcc
	v_mul_f32_e32 v68, 0xbfb8aa3b, v70
	v_pk_mul_f32 v[74:75], v[60:61], v[68:69] op_sel_hi:[1,0]
	v_pk_mul_f32 v[72:73], v[62:63], v[68:69] op_sel_hi:[1,0]
	v_exp_f32_e32 v74, v74
	v_exp_f32_e32 v75, v75
	v_exp_f32_e32 v72, v72
	v_exp_f32_e32 v73, v73
	v_add_f32_e32 v74, 1.0, v74
	v_add_f32_e32 v75, 1.0, v75
	v_rcp_f32_e32 v74, v74
	v_rcp_f32_e32 v75, v75
	v_add_f32_e32 v72, 1.0, v72
	v_add_f32_e32 v73, 1.0, v73
	v_rcp_f32_e32 v72, v72
	v_rcp_f32_e32 v73, v73
	v_mul_f32_e32 v70, v70, v70
	v_pk_mul_f32 v[60:61], v[70:71], v[74:75] op_sel_hi:[0,1]
	v_pk_mul_f32 v[56:57], v[56:57], v[60:61]
	v_pk_mul_f32 v[62:63], v[70:71], v[72:73] op_sel_hi:[0,1]
	v_pk_mul_f32 v[58:59], v[58:59], v[62:63]
	v_cvt_pk_bf16_f32 v60, v57, s0
	v_cvt_pk_bf16_f32 v56, v56, s0
	v_cvt_pk_bf16_f32 v57, v58, v59
	v_lshlrev_b32_e32 v58, 16, v60
	v_pk_mul_f32 v[60:61], v[52:53], v[68:69] op_sel_hi:[1,0]
	v_or_b32_sdwa v56, v58, v56 dst_sel:DWORD dst_unused:UNUSED_PAD src0_sel:DWORD src1_sel:WORD_0
	v_pk_mul_f32 v[58:59], v[54:55], v[68:69] op_sel_hi:[1,0]
	v_exp_f32_e32 v60, v60
	v_exp_f32_e32 v61, v61
	v_exp_f32_e32 v58, v58
	v_exp_f32_e32 v59, v59
	v_add_f32_e32 v60, 1.0, v60
	v_add_f32_e32 v61, 1.0, v61
	v_rcp_f32_e32 v60, v60
	v_rcp_f32_e32 v61, v61
	v_add_f32_e32 v58, 1.0, v58
	v_add_f32_e32 v59, 1.0, v59
	v_rcp_f32_e32 v58, v58
	v_rcp_f32_e32 v59, v59
	v_pk_mul_f32 v[52:53], v[70:71], v[60:61] op_sel_hi:[0,1]
	v_pk_mul_f32 v[48:49], v[48:49], v[52:53]
	v_pk_mul_f32 v[54:55], v[70:71], v[58:59] op_sel_hi:[0,1]
	v_pk_mul_f32 v[50:51], v[50:51], v[54:55]
	v_cvt_pk_bf16_f32 v58, v48, v49
	v_mad_i64_i32 v[48:49], s[0:1], v67, s9, v[112:113]
	v_cvt_pk_bf16_f32 v59, v50, v51
	v_lshl_add_u64 v[48:49], v[48:49], 0, v[114:115]
	global_store_dwordx4 v[48:49], v[56:59], off
	v_fmamk_f32 v48, v236, 0x3a800000, v194
	v_cmp_gt_f32_e32 vcc, s2, v48
	v_mul_f32_e32 v49, 0x4b800000, v48
	s_nop 0
	v_cndmask_b32_e32 v48, v48, v49, vcc
	v_rsq_f32_e32 v48, v48
	s_nop 0
	v_mul_f32_e32 v49, 0x45800000, v48
	v_cndmask_b32_e32 v49, v48, v49, vcc
	v_mul_f32_e32 v48, 0xbfb8aa3b, v49
	v_pk_mul_f32 v[54:55], v[44:45], v[48:49] op_sel_hi:[1,0]
	v_mul_f32_e32 v50, v49, v49
	v_pk_mul_f32 v[52:53], v[46:47], v[48:49] op_sel_hi:[1,0]
	v_exp_f32_e32 v49, v54
	s_nop 0
	v_add_f32_e32 v49, 1.0, v49
	v_rcp_f32_e32 v54, v49
	v_exp_f32_e32 v49, v55
	s_nop 0
	v_add_f32_e32 v49, 1.0, v49
	v_rcp_f32_e32 v55, v49
	v_exp_f32_e32 v49, v52
	v_pk_mul_f32 v[44:45], v[50:51], v[54:55] op_sel_hi:[0,1]
	v_add_f32_e32 v49, 1.0, v49
	v_rcp_f32_e32 v52, v49
	v_exp_f32_e32 v49, v53
	v_pk_mul_f32 v[40:41], v[40:41], v[44:45]
	v_add_f32_e32 v49, 1.0, v49
	v_rcp_f32_e32 v53, v49
	v_cvt_pk_bf16_f32 v44, v41, s0
	v_cvt_pk_bf16_f32 v40, v40, s0
	v_pk_mul_f32 v[46:47], v[50:51], v[52:53] op_sel_hi:[0,1]
	v_pk_mul_f32 v[42:43], v[42:43], v[46:47]
	s_nop 0
	v_cvt_pk_bf16_f32 v41, v42, v43
	v_lshlrev_b32_e32 v42, 16, v44
	v_pk_mul_f32 v[44:45], v[36:37], v[48:49] op_sel_hi:[1,0]
	v_or_b32_sdwa v40, v42, v40 dst_sel:DWORD dst_unused:UNUSED_PAD src0_sel:DWORD src1_sel:WORD_0
	v_pk_mul_f32 v[42:43], v[38:39], v[48:49] op_sel_hi:[1,0]
	v_exp_f32_e32 v44, v44
	v_exp_f32_e32 v45, v45
	v_exp_f32_e32 v42, v42
	v_exp_f32_e32 v43, v43
	v_add_f32_e32 v44, 1.0, v44
	v_add_f32_e32 v45, 1.0, v45
	v_rcp_f32_e32 v44, v44
	v_rcp_f32_e32 v45, v45
	v_add_f32_e32 v42, 1.0, v42
	v_add_f32_e32 v43, 1.0, v43
	v_rcp_f32_e32 v42, v42
	v_rcp_f32_e32 v43, v43
	v_pk_mul_f32 v[36:37], v[50:51], v[44:45] op_sel_hi:[0,1]
	v_pk_mul_f32 v[32:33], v[32:33], v[36:37]
	v_pk_mul_f32 v[38:39], v[50:51], v[42:43] op_sel_hi:[0,1]
	v_pk_mul_f32 v[34:35], v[34:35], v[38:39]
	v_cvt_pk_bf16_f32 v42, v32, v33
	v_mad_i64_i32 v[32:33], s[0:1], v69, s9, v[112:113]
	v_cvt_pk_bf16_f32 v43, v34, v35
	v_lshl_add_u64 v[32:33], v[32:33], 0, v[114:115]
	global_store_dwordx4 v[32:33], v[40:43], off
	v_fmamk_f32 v32, v237, 0x3a800000, v194
	v_cmp_gt_f32_e32 vcc, s2, v32
	v_mul_f32_e32 v33, 0x4b800000, v32
	s_nop 0
	v_cndmask_b32_e32 v32, v32, v33, vcc
	v_rsq_f32_e32 v32, v32
	s_nop 0
	v_mul_f32_e32 v33, 0x45800000, v32
	v_cndmask_b32_e32 v33, v32, v33, vcc
	v_mul_f32_e32 v32, 0xbfb8aa3b, v33
	v_pk_mul_f32 v[38:39], v[28:29], v[32:33] op_sel_hi:[1,0]
	v_mul_f32_e32 v34, v33, v33
	v_pk_mul_f32 v[36:37], v[30:31], v[32:33] op_sel_hi:[1,0]
	v_exp_f32_e32 v33, v38
	s_nop 0
	v_add_f32_e32 v33, 1.0, v33
	v_rcp_f32_e32 v38, v33
	v_exp_f32_e32 v33, v39
	s_nop 0
	v_add_f32_e32 v33, 1.0, v33
	v_rcp_f32_e32 v39, v33
	v_exp_f32_e32 v33, v36
	v_pk_mul_f32 v[28:29], v[34:35], v[38:39] op_sel_hi:[0,1]
	v_add_f32_e32 v33, 1.0, v33
	v_rcp_f32_e32 v36, v33
	v_exp_f32_e32 v33, v37
	v_pk_mul_f32 v[24:25], v[24:25], v[28:29]
	v_add_f32_e32 v33, 1.0, v33
	v_rcp_f32_e32 v37, v33
	v_cvt_pk_bf16_f32 v28, v25, s0
	v_cvt_pk_bf16_f32 v24, v24, s0
	v_pk_mul_f32 v[30:31], v[34:35], v[36:37] op_sel_hi:[0,1]
	v_pk_mul_f32 v[26:27], v[26:27], v[30:31]
	s_nop 0
	v_cvt_pk_bf16_f32 v25, v26, v27
	v_lshlrev_b32_e32 v26, 16, v28
	v_pk_mul_f32 v[28:29], v[20:21], v[32:33] op_sel_hi:[1,0]
	v_or_b32_sdwa v24, v26, v24 dst_sel:DWORD dst_unused:UNUSED_PAD src0_sel:DWORD src1_sel:WORD_0
	v_pk_mul_f32 v[26:27], v[22:23], v[32:33] op_sel_hi:[1,0]
	v_exp_f32_e32 v28, v28
	v_exp_f32_e32 v29, v29
	v_exp_f32_e32 v26, v26
	v_exp_f32_e32 v27, v27
	v_add_f32_e32 v28, 1.0, v28
	v_add_f32_e32 v29, 1.0, v29
	v_rcp_f32_e32 v28, v28
	v_rcp_f32_e32 v29, v29
	v_add_f32_e32 v26, 1.0, v26
	v_add_f32_e32 v27, 1.0, v27
	v_rcp_f32_e32 v26, v26
	v_rcp_f32_e32 v27, v27
	v_pk_mul_f32 v[20:21], v[34:35], v[28:29] op_sel_hi:[0,1]
	v_pk_mul_f32 v[16:17], v[16:17], v[20:21]
	v_pk_mul_f32 v[22:23], v[34:35], v[26:27] op_sel_hi:[0,1]
	v_pk_mul_f32 v[18:19], v[18:19], v[22:23]
	v_cvt_pk_bf16_f32 v26, v16, v17
	v_mad_i64_i32 v[16:17], s[0:1], v66, s9, v[112:113]
	v_cvt_pk_bf16_f32 v27, v18, v19
	v_lshl_add_u64 v[16:17], v[16:17], 0, v[114:115]
	global_store_dwordx4 v[16:17], v[24:27], off
	v_fmamk_f32 v16, v238, 0x3a800000, v194
	v_cmp_gt_f32_e32 vcc, s2, v16
	v_mul_f32_e32 v17, 0x4b800000, v16
	s_nop 0
	v_cndmask_b32_e32 v16, v16, v17, vcc
	v_rsq_f32_e32 v16, v16
	s_nop 0
	v_mul_f32_e32 v17, 0x45800000, v16
	v_cndmask_b32_e32 v17, v16, v17, vcc
	v_mul_f32_e32 v16, 0xbfb8aa3b, v17
	v_pk_mul_f32 v[22:23], v[12:13], v[16:17] op_sel_hi:[1,0]
	v_mul_f32_e32 v18, v17, v17
	v_pk_mul_f32 v[20:21], v[14:15], v[16:17] op_sel_hi:[1,0]
	v_exp_f32_e32 v17, v22
	s_and_b64 vcc, exec, s[4:5]
	v_add_f32_e32 v17, 1.0, v17
	v_rcp_f32_e32 v22, v17
	v_exp_f32_e32 v17, v23
	s_nop 0
	v_add_f32_e32 v17, 1.0, v17
	v_rcp_f32_e32 v23, v17
	v_exp_f32_e32 v17, v20
	v_pk_mul_f32 v[12:13], v[18:19], v[22:23] op_sel_hi:[0,1]
	v_add_f32_e32 v17, 1.0, v17
	v_rcp_f32_e32 v20, v17
	v_exp_f32_e32 v17, v21
	v_pk_mul_f32 v[8:9], v[8:9], v[12:13]
	v_add_f32_e32 v17, 1.0, v17
	v_rcp_f32_e32 v21, v17
	v_cvt_pk_bf16_f32 v12, v9, s0
	v_cvt_pk_bf16_f32 v8, v8, s0
	v_pk_mul_f32 v[14:15], v[18:19], v[20:21] op_sel_hi:[0,1]
	v_pk_mul_f32 v[10:11], v[10:11], v[14:15]
	s_nop 0
	v_cvt_pk_bf16_f32 v9, v10, v11
	v_lshlrev_b32_e32 v10, 16, v12
	v_pk_mul_f32 v[12:13], v[4:5], v[16:17] op_sel_hi:[1,0]
	v_or_b32_sdwa v8, v10, v8 dst_sel:DWORD dst_unused:UNUSED_PAD src0_sel:DWORD src1_sel:WORD_0
	v_pk_mul_f32 v[10:11], v[6:7], v[16:17] op_sel_hi:[1,0]
	v_exp_f32_e32 v12, v12
	v_exp_f32_e32 v13, v13
	v_exp_f32_e32 v10, v10
	v_exp_f32_e32 v11, v11
	v_add_f32_e32 v12, 1.0, v12
	v_add_f32_e32 v13, 1.0, v13
	v_rcp_f32_e32 v12, v12
	v_rcp_f32_e32 v13, v13
	v_add_f32_e32 v10, 1.0, v10
	v_add_f32_e32 v11, 1.0, v11
	v_rcp_f32_e32 v10, v10
	v_rcp_f32_e32 v11, v11
	v_pk_mul_f32 v[4:5], v[18:19], v[12:13] op_sel_hi:[0,1]
	v_pk_mul_f32 v[0:1], v[0:1], v[4:5]
	v_pk_mul_f32 v[6:7], v[18:19], v[10:11] op_sel_hi:[0,1]
	v_pk_mul_f32 v[2:3], v[2:3], v[6:7]
	v_cvt_pk_bf16_f32 v10, v0, v1
	v_mad_i64_i32 v[0:1], s[0:1], v64, s9, v[112:113]
	v_cvt_pk_bf16_f32 v11, v2, v3
	v_lshl_add_u64 v[0:1], v[0:1], 0, v[114:115]
	s_mov_b32 s0, s10
	global_store_dwordx4 v[0:1], v[8:11], off
	s_cbranch_vccz .LBB0_399
	s_waitcnt vmcnt(0)
	s_cmpk_gt_u32 s25, 0xff
	s_cbranch_scc1 .LBB0_406
	s_barrier

.LBB0_1623:
	s_add_u32 s22, s20, 0x100
	s_addc_u32 s23, s21, 0
	s_add_i32 s46, 0, 0x10000
	v_add_u32_e32 v140, s46, v196
	ds_read_b128 v[128:131], v140
	ds_read_b128 v[132:135], v140 offset:1024
	ds_read_b128 v[136:139], v140 offset:2048
	ds_read_b128 v[140:143], v140 offset:3072
	s_cmp_eq_u32 s45, 40
	s_cselect_b32 s27, s7, s23
	s_cselect_b32 s26, s6, s22
	s_cselect_b32 s25, s9, s44
	s_cselect_b32 s24, s8, s33
	v_lshl_add_u64 v[176:177], s[20:21], 0, v[214:215]
	s_add_i32 m0, s34, 0xc000
	ds_read_b128 v[144:147], v198
	ds_read_b128 v[148:151], v198 offset:1024
	ds_read_b128 v[152:155], v198 offset:2048
	ds_read_b128 v[156:159], v198 offset:3072
	ds_read_b128 v[160:163], v198 offset:4096
	ds_read_b128 v[164:167], v198 offset:5120
	ds_read_b128 v[168:171], v198 offset:6144
	ds_read_b128 v[172:175], v198 offset:7168
	global_load_lds_dwordx4 v[176:177], off
	v_lshl_add_u64 v[176:177], s[20:21], 0, v[212:213]
	s_add_i32 m0, s34, 0xe000
	s_nop 0
	global_load_lds_dwordx4 v[176:177], off
	s_waitcnt lgkmcnt(8)
	s_barrier
	s_waitcnt lgkmcnt(0)
	s_setprio 1
	s_waitcnt lgkmcnt(0)
	v_mfma_f32_16x16x32_bf16 v[124:127], v[128:131], v[144:147], v[124:127]
	v_mfma_f32_16x16x32_bf16 v[120:123], v[136:139], v[144:147], v[120:123]
	v_mfma_f32_16x16x32_bf16 v[108:111], v[128:131], v[152:155], v[108:111]
	v_mfma_f32_16x16x32_bf16 v[104:107], v[136:139], v[152:155], v[104:107]
	v_mfma_f32_16x16x32_bf16 v[92:95], v[128:131], v[160:163], v[92:95]
	v_mfma_f32_16x16x32_bf16 v[88:91], v[136:139], v[160:163], v[88:91]
	v_mfma_f32_16x16x32_bf16 v[76:79], v[128:131], v[168:171], v[76:79]
	v_mfma_f32_16x16x32_bf16 v[72:75], v[136:139], v[168:171], v[72:75]
	v_mfma_f32_16x16x32_bf16 v[124:127], v[132:135], v[148:151], v[124:127]
	v_mfma_f32_16x16x32_bf16 v[120:123], v[140:143], v[148:151], v[120:123]
	v_mfma_f32_16x16x32_bf16 v[108:111], v[132:135], v[156:159], v[108:111]
	v_mfma_f32_16x16x32_bf16 v[104:107], v[140:143], v[156:159], v[104:107]
	v_mfma_f32_16x16x32_bf16 v[92:95], v[132:135], v[164:167], v[92:95]
	v_mfma_f32_16x16x32_bf16 v[88:91], v[140:143], v[164:167], v[88:91]
	v_mfma_f32_16x16x32_bf16 v[76:79], v[132:135], v[172:175], v[76:79]
	v_mfma_f32_16x16x32_bf16 v[72:75], v[140:143], v[172:175], v[72:75]
	s_setprio 0
	s_barrier
	s_add_i32 s47, 0, 0x14000
	s_add_i32 s20, s46, s31
	v_add_u32_e32 v188, s47, v196
	v_lshl_add_u64 v[200:201], s[24:25], 0, v[192:193]
	s_mov_b32 m0, s20
	ds_read_b128 v[176:179], v188
	ds_read_b128 v[180:183], v188 offset:1024
	ds_read_b128 v[184:187], v188 offset:2048
	ds_read_b128 v[188:191], v188 offset:3072
	global_load_lds_dwordx4 v[200:201], off
	v_lshl_add_u64 v[216:217], s[24:25], 0, v[210:211]
	s_add_i32 m0, s20, 0x2000
	s_nop 0
	global_load_lds_dwordx4 v[216:217], off
	s_barrier
	s_waitcnt lgkmcnt(0)
	s_setprio 1
	s_waitcnt lgkmcnt(0)
	v_mfma_f32_16x16x32_bf16 v[116:119], v[176:179], v[144:147], v[116:119]
	v_mfma_f32_16x16x32_bf16 v[112:115], v[184:187], v[144:147], v[112:115]
	v_mfma_f32_16x16x32_bf16 v[100:103], v[176:179], v[152:155], v[100:103]
	v_mfma_f32_16x16x32_bf16 v[96:99], v[184:187], v[152:155], v[96:99]
	v_mfma_f32_16x16x32_bf16 v[84:87], v[176:179], v[160:163], v[84:87]
	v_mfma_f32_16x16x32_bf16 v[80:83], v[184:187], v[160:163], v[80:83]
	v_mfma_f32_16x16x32_bf16 v[68:71], v[176:179], v[168:171], v[68:71]
	v_mfma_f32_16x16x32_bf16 v[64:67], v[184:187], v[168:171], v[64:67]
	v_mfma_f32_16x16x32_bf16 v[116:119], v[180:183], v[148:151], v[116:119]
	v_mfma_f32_16x16x32_bf16 v[112:115], v[188:191], v[148:151], v[112:115]
	v_mfma_f32_16x16x32_bf16 v[100:103], v[180:183], v[156:159], v[100:103]
	v_mfma_f32_16x16x32_bf16 v[96:99], v[188:191], v[156:159], v[96:99]
	v_mfma_f32_16x16x32_bf16 v[84:87], v[180:183], v[164:167], v[84:87]
	v_mfma_f32_16x16x32_bf16 v[80:83], v[188:191], v[164:167], v[80:83]
	v_mfma_f32_16x16x32_bf16 v[68:71], v[180:183], v[172:175], v[68:71]
	v_mfma_f32_16x16x32_bf16 v[64:67], v[188:191], v[172:175], v[64:67]
	s_setprio 0
	s_mov_b32 m0, s34
	v_lshl_add_u64 v[218:219], s[26:27], 0, v[206:207]
	s_barrier
	ds_read_b128 v[144:147], v198 offset:16384
	ds_read_b128 v[148:151], v198 offset:17408
	ds_read_b128 v[152:155], v198 offset:18432
	ds_read_b128 v[156:159], v198 offset:19456
	ds_read_b128 v[160:163], v198 offset:20480
	ds_read_b128 v[164:167], v198 offset:21504
	ds_read_b128 v[168:171], v198 offset:22528
	ds_read_b128 v[172:175], v198 offset:23552
	global_load_lds_dwordx4 v[218:219], off
	v_lshl_add_u64 v[220:221], s[26:27], 0, v[208:209]
	s_mov_b32 m0, s35
	s_nop 0
	global_load_lds_dwordx4 v[220:221], off
	s_barrier
	s_waitcnt lgkmcnt(0)
	s_setprio 1
	s_waitcnt lgkmcnt(0)
	v_mfma_f32_16x16x32_bf16 v[60:63], v[128:131], v[144:147], v[60:63]
	v_mfma_f32_16x16x32_bf16 v[56:59], v[136:139], v[144:147], v[56:59]
	v_mfma_f32_16x16x32_bf16 v[44:47], v[128:131], v[152:155], v[44:47]
	v_mfma_f32_16x16x32_bf16 v[40:43], v[136:139], v[152:155], v[40:43]
	v_mfma_f32_16x16x32_bf16 v[28:31], v[128:131], v[160:163], v[28:31]
	v_mfma_f32_16x16x32_bf16 v[24:27], v[136:139], v[160:163], v[24:27]
	v_mfma_f32_16x16x32_bf16 v[12:15], v[128:131], v[168:171], v[12:15]
	v_mfma_f32_16x16x32_bf16 v[8:11], v[136:139], v[168:171], v[8:11]
	v_mfma_f32_16x16x32_bf16 v[60:63], v[132:135], v[148:151], v[60:63]
	v_mfma_f32_16x16x32_bf16 v[56:59], v[140:143], v[148:151], v[56:59]
	v_mfma_f32_16x16x32_bf16 v[44:47], v[132:135], v[156:159], v[44:47]
	v_mfma_f32_16x16x32_bf16 v[40:43], v[140:143], v[156:159], v[40:43]
	v_mfma_f32_16x16x32_bf16 v[28:31], v[132:135], v[164:167], v[28:31]
	v_mfma_f32_16x16x32_bf16 v[24:27], v[140:143], v[164:167], v[24:27]
	v_mfma_f32_16x16x32_bf16 v[12:15], v[132:135], v[172:175], v[12:15]
	v_mfma_f32_16x16x32_bf16 v[8:11], v[140:143], v[172:175], v[8:11]
	s_setprio 0
	s_barrier
	s_add_u32 s20, s24, 0xb0000
	s_addc_u32 s21, s25, 0
	s_add_i32 s46, s47, s31
	s_mov_b32 m0, s46
	s_nop 0
	global_load_lds_dwordx4 v192, s[20:21]
	v_lshl_add_u64 v[128:129], s[20:21], 0, v[210:211]
	s_add_i32 m0, s46, 0x2000
	s_nop 0
	global_load_lds_dwordx4 v[128:129], off
	s_waitcnt vmcnt(6)
	s_barrier
	s_setprio 1
	v_mfma_f32_16x16x32_bf16 v[52:55], v[176:179], v[144:147], v[52:55]
	v_mfma_f32_16x16x32_bf16 v[48:51], v[184:187], v[144:147], v[48:51]
	v_mfma_f32_16x16x32_bf16 v[36:39], v[176:179], v[152:155], v[36:39]
	v_mfma_f32_16x16x32_bf16 v[32:35], v[184:187], v[152:155], v[32:35]
	v_mfma_f32_16x16x32_bf16 v[20:23], v[176:179], v[160:163], v[20:23]
	v_mfma_f32_16x16x32_bf16 v[16:19], v[184:187], v[160:163], v[16:19]
	v_mfma_f32_16x16x32_bf16 v[4:7], v[176:179], v[168:171], v[4:7]
	v_mfma_f32_16x16x32_bf16 v[0:3], v[184:187], v[168:171], v[0:3]
	v_mfma_f32_16x16x32_bf16 v[52:55], v[180:183], v[148:151], v[52:55]
	v_mfma_f32_16x16x32_bf16 v[48:51], v[188:191], v[148:151], v[48:51]
	v_mfma_f32_16x16x32_bf16 v[36:39], v[180:183], v[156:159], v[36:39]
	v_mfma_f32_16x16x32_bf16 v[32:35], v[188:191], v[156:159], v[32:35]
	v_mfma_f32_16x16x32_bf16 v[20:23], v[180:183], v[164:167], v[20:23]
	v_mfma_f32_16x16x32_bf16 v[16:19], v[188:191], v[164:167], v[16:19]
	v_mfma_f32_16x16x32_bf16 v[4:7], v[180:183], v[172:175], v[4:7]
	v_mfma_f32_16x16x32_bf16 v[0:3], v[188:191], v[172:175], v[0:3]
	s_setprio 0
	s_add_i32 s46, 0, 0x18000
	v_add_u32_e32 v140, s46, v196
	s_barrier
	ds_read_b128 v[128:131], v140
	ds_read_b128 v[132:135], v140 offset:1024
	ds_read_b128 v[136:139], v140 offset:2048
	ds_read_b128 v[140:143], v140 offset:3072
	s_add_u32 s20, s26, 0xb0000
	s_addc_u32 s21, s27, 0
	s_mov_b32 m0, s36
	v_lshl_add_u64 v[176:177], s[20:21], 0, v[206:207]
	ds_read_b128 v[144:147], v198 offset:32768
	ds_read_b128 v[148:151], v198 offset:33792
	ds_read_b128 v[152:155], v198 offset:34816
	ds_read_b128 v[156:159], v198 offset:35840
	ds_read_b128 v[160:163], v198 offset:36864
	ds_read_b128 v[164:167], v198 offset:37888
	ds_read_b128 v[168:171], v198 offset:38912
	ds_read_b128 v[172:175], v198 offset:39936
	global_load_lds_dwordx4 v[176:177], off
	v_lshl_add_u64 v[176:177], s[20:21], 0, v[208:209]
	s_mov_b32 m0, s37
	s_nop 0
	global_load_lds_dwordx4 v[176:177], off
	s_waitcnt lgkmcnt(8)
	s_barrier
	s_waitcnt lgkmcnt(0)
	s_setprio 1
	s_waitcnt lgkmcnt(0)
	v_mfma_f32_16x16x32_bf16 v[124:127], v[128:131], v[144:147], v[124:127]
	v_mfma_f32_16x16x32_bf16 v[120:123], v[136:139], v[144:147], v[120:123]
	v_mfma_f32_16x16x32_bf16 v[108:111], v[128:131], v[152:155], v[108:111]
	v_mfma_f32_16x16x32_bf16 v[104:107], v[136:139], v[152:155], v[104:107]
	v_mfma_f32_16x16x32_bf16 v[92:95], v[128:131], v[160:163], v[92:95]
	v_mfma_f32_16x16x32_bf16 v[88:91], v[136:139], v[160:163], v[88:91]
	v_mfma_f32_16x16x32_bf16 v[76:79], v[128:131], v[168:171], v[76:79]
	v_mfma_f32_16x16x32_bf16 v[72:75], v[136:139], v[168:171], v[72:75]
	v_mfma_f32_16x16x32_bf16 v[124:127], v[132:135], v[148:151], v[124:127]
	v_mfma_f32_16x16x32_bf16 v[120:123], v[140:143], v[148:151], v[120:123]
	v_mfma_f32_16x16x32_bf16 v[108:111], v[132:135], v[156:159], v[108:111]
	v_mfma_f32_16x16x32_bf16 v[104:107], v[140:143], v[156:159], v[104:107]
	v_mfma_f32_16x16x32_bf16 v[92:95], v[132:135], v[164:167], v[92:95]
	v_mfma_f32_16x16x32_bf16 v[88:91], v[140:143], v[164:167], v[88:91]
	v_mfma_f32_16x16x32_bf16 v[76:79], v[132:135], v[172:175], v[76:79]
	v_mfma_f32_16x16x32_bf16 v[72:75], v[140:143], v[172:175], v[72:75]
	s_setprio 0
	s_barrier
	s_add_i32 s26, 0, 0x1c000
	s_add_i32 s20, s46, s31
	v_add_u32_e32 v188, s26, v196
	v_lshl_add_u64 v[200:201], v[200:201], 0, s[80:81]
	s_mov_b32 m0, s20
	ds_read_b128 v[176:179], v188
	ds_read_b128 v[180:183], v188 offset:1024
	ds_read_b128 v[184:187], v188 offset:2048
	ds_read_b128 v[188:191], v188 offset:3072
	global_load_lds_dwordx4 v[200:201], off
	v_lshl_add_u64 v[200:201], v[216:217], 0, s[80:81]
	s_add_i32 m0, s20, 0x2000
	s_nop 0
	global_load_lds_dwordx4 v[200:201], off
	s_barrier
	s_waitcnt lgkmcnt(0)
	s_setprio 1
	s_waitcnt lgkmcnt(0)
	v_mfma_f32_16x16x32_bf16 v[116:119], v[176:179], v[144:147], v[116:119]
	v_mfma_f32_16x16x32_bf16 v[112:115], v[184:187], v[144:147], v[112:115]
	v_mfma_f32_16x16x32_bf16 v[100:103], v[176:179], v[152:155], v[100:103]
	v_mfma_f32_16x16x32_bf16 v[96:99], v[184:187], v[152:155], v[96:99]
	v_mfma_f32_16x16x32_bf16 v[84:87], v[176:179], v[160:163], v[84:87]
	v_mfma_f32_16x16x32_bf16 v[80:83], v[184:187], v[160:163], v[80:83]
	v_mfma_f32_16x16x32_bf16 v[68:71], v[176:179], v[168:171], v[68:71]
	v_mfma_f32_16x16x32_bf16 v[64:67], v[184:187], v[168:171], v[64:67]
	v_mfma_f32_16x16x32_bf16 v[116:119], v[180:183], v[148:151], v[116:119]
	v_mfma_f32_16x16x32_bf16 v[112:115], v[188:191], v[148:151], v[112:115]
	v_mfma_f32_16x16x32_bf16 v[100:103], v[180:183], v[156:159], v[100:103]
	v_mfma_f32_16x16x32_bf16 v[96:99], v[188:191], v[156:159], v[96:99]
	v_mfma_f32_16x16x32_bf16 v[84:87], v[180:183], v[164:167], v[84:87]
	v_mfma_f32_16x16x32_bf16 v[80:83], v[188:191], v[164:167], v[80:83]
	v_mfma_f32_16x16x32_bf16 v[68:71], v[180:183], v[172:175], v[68:71]
	v_mfma_f32_16x16x32_bf16 v[64:67], v[188:191], v[172:175], v[64:67]
	s_setprio 0
	s_mov_b32 m0, s38
	v_lshl_add_u64 v[200:201], v[218:219], 0, s[80:81]
	s_barrier
	ds_read_b128 v[144:147], v198 offset:49152
	ds_read_b128 v[148:151], v198 offset:50176
	ds_read_b128 v[152:155], v198 offset:51200
	ds_read_b128 v[156:159], v198 offset:52224
	ds_read_b128 v[160:163], v198 offset:53248
	ds_read_b128 v[164:167], v198 offset:54272
	ds_read_b128 v[168:171], v198 offset:55296
	ds_read_b128 v[172:175], v198 offset:56320
	global_load_lds_dwordx4 v[200:201], off
	v_lshl_add_u64 v[200:201], v[220:221], 0, s[80:81]
	s_mov_b32 m0, s39
	s_nop 0
	global_load_lds_dwordx4 v[200:201], off
	s_barrier
	s_waitcnt lgkmcnt(0)
	s_setprio 1
	s_waitcnt lgkmcnt(0)
	v_mfma_f32_16x16x32_bf16 v[60:63], v[128:131], v[144:147], v[60:63]
	v_mfma_f32_16x16x32_bf16 v[56:59], v[136:139], v[144:147], v[56:59]
	v_mfma_f32_16x16x32_bf16 v[44:47], v[128:131], v[152:155], v[44:47]
	v_mfma_f32_16x16x32_bf16 v[40:43], v[136:139], v[152:155], v[40:43]
	v_mfma_f32_16x16x32_bf16 v[28:31], v[128:131], v[160:163], v[28:31]
	v_mfma_f32_16x16x32_bf16 v[24:27], v[136:139], v[160:163], v[24:27]
	v_mfma_f32_16x16x32_bf16 v[12:15], v[128:131], v[168:171], v[12:15]
	v_mfma_f32_16x16x32_bf16 v[8:11], v[136:139], v[168:171], v[8:11]
	v_mfma_f32_16x16x32_bf16 v[60:63], v[132:135], v[148:151], v[60:63]
	v_mfma_f32_16x16x32_bf16 v[56:59], v[140:143], v[148:151], v[56:59]
	v_mfma_f32_16x16x32_bf16 v[44:47], v[132:135], v[156:159], v[44:47]
	v_mfma_f32_16x16x32_bf16 v[40:43], v[140:143], v[156:159], v[40:43]
	v_mfma_f32_16x16x32_bf16 v[28:31], v[132:135], v[164:167], v[28:31]
	v_mfma_f32_16x16x32_bf16 v[24:27], v[140:143], v[164:167], v[24:27]
	v_mfma_f32_16x16x32_bf16 v[12:15], v[132:135], v[172:175], v[12:15]
	v_mfma_f32_16x16x32_bf16 v[8:11], v[140:143], v[172:175], v[8:11]
	s_setprio 0
	s_barrier
	s_add_u32 s20, s24, 0xb0080
	s_addc_u32 s21, s25, 0
	s_add_i32 s24, s26, s31
	s_mov_b32 m0, s24
	s_nop 0
	global_load_lds_dwordx4 v192, s[20:21]
	v_lshl_add_u64 v[128:129], s[20:21], 0, v[210:211]
	s_add_i32 m0, s24, 0x2000
	s_nop 0
	global_load_lds_dwordx4 v[128:129], off
	s_waitcnt vmcnt(6)
	s_barrier
	s_setprio 1
	v_mfma_f32_16x16x32_bf16 v[52:55], v[176:179], v[144:147], v[52:55]
	v_mfma_f32_16x16x32_bf16 v[48:51], v[184:187], v[144:147], v[48:51]
	v_mfma_f32_16x16x32_bf16 v[36:39], v[176:179], v[152:155], v[36:39]
	v_mfma_f32_16x16x32_bf16 v[32:35], v[184:187], v[152:155], v[32:35]
	v_mfma_f32_16x16x32_bf16 v[20:23], v[176:179], v[160:163], v[20:23]
	v_mfma_f32_16x16x32_bf16 v[16:19], v[184:187], v[160:163], v[16:19]
	v_mfma_f32_16x16x32_bf16 v[4:7], v[176:179], v[168:171], v[4:7]
	v_mfma_f32_16x16x32_bf16 v[0:3], v[184:187], v[168:171], v[0:3]
	v_mfma_f32_16x16x32_bf16 v[52:55], v[180:183], v[148:151], v[52:55]
	v_mfma_f32_16x16x32_bf16 v[48:51], v[188:191], v[148:151], v[48:51]
	v_mfma_f32_16x16x32_bf16 v[36:39], v[180:183], v[156:159], v[36:39]
	v_mfma_f32_16x16x32_bf16 v[32:35], v[188:191], v[156:159], v[32:35]
	v_mfma_f32_16x16x32_bf16 v[20:23], v[180:183], v[164:167], v[20:23]
	v_mfma_f32_16x16x32_bf16 v[16:19], v[188:191], v[164:167], v[16:19]
	v_mfma_f32_16x16x32_bf16 v[4:7], v[180:183], v[172:175], v[4:7]
	v_mfma_f32_16x16x32_bf16 v[0:3], v[188:191], v[172:175], v[0:3]
	s_setprio 0
	s_add_i32 s45, s45, 2
	s_add_u32 s33, s33, 0x100
	s_addc_u32 s44, s44, 0
	s_cmp_gt_u32 s45, 41
	s_mov_b64 s[20:21], s[22:23]
	s_barrier
	s_cbranch_scc0 .LBB0_1623
	v_mov_b32_e32 v128, v252
	s_lshl_b32 s1, s1, 8
	v_readfirstlane_b32 s20, v128
	s_ashr_i32 s21, s20, 2
	s_andn2_b32 s21, s21, 63
	s_add_i32 s21, s21, s1
	s_lshr_b32 s1, s20, 1
	s_and_b32 s1, s1, 0x60
	s_lshl_b32 s0, s0, 8
	v_and_or_b32 v244, v128, 15, s21
	v_lshrrev_b32_e32 v128, 1, v128
	s_or_b32 s0, s1, s0
	v_and_b32_e32 v129, 64, v195
	v_and_or_b32 v216, v128, 24, s0
	v_xor_b32_e32 v128, 16, v195
	v_add_u32_e32 v129, 64, v129
	v_cmp_lt_i32_e32 vcc, v128, v129
	v_ashrrev_i32_e32 v245, 31, v244
	v_lshlrev_b64 v[220:221], 10, v[244:245]
	v_cndmask_b32_e32 v128, v195, v128, vcc
	v_lshlrev_b32_e32 v200, 2, v128
	v_xor_b32_e32 v128, 32, v195
	v_cmp_lt_i32_e32 vcc, v128, v129
	v_ashrrev_i32_e32 v217, 31, v216
	v_or_b32_e32 v218, 0x80, v216
	v_cndmask_b32_e32 v128, v195, v128, vcc
	v_lshlrev_b32_e32 v199, 2, v128
	v_lshl_add_u64 v[128:129], v[220:221], 0, v[216:217]
	v_lshlrev_b64 v[128:129], 1, v[128:129]
	v_lshl_add_u64 v[240:241], s[18:19], 0, v[128:129]
	v_lshl_add_u64 v[246:247], s[10:11], 0, v[128:129]
	global_load_dwordx4 v[188:191], v[240:241], off
	global_load_dwordx4 v[180:183], v[240:241], off offset:256
	global_load_dwordx4 v[184:187], v[246:247], off
	v_ashrrev_i32_e32 v219, 31, v218
	v_lshl_add_u64 v[128:129], v[220:221], 0, v[218:219]
	v_lshl_add_u64 v[242:243], v[128:129], 1, s[10:11]
	v_or_b32_e32 v128, 16, v244
	v_ashrrev_i32_e32 v129, 31, v128
	v_lshlrev_b64 v[128:129], 10, v[128:129]
	v_lshl_add_u64 v[130:131], v[128:129], 0, v[216:217]
	v_lshl_add_u64 v[128:129], v[128:129], 0, v[218:219]
	v_lshl_add_u64 v[236:237], v[128:129], 1, s[10:11]
	v_or_b32_e32 v128, 32, v244
	v_ashrrev_i32_e32 v129, 31, v128
	v_lshlrev_b64 v[130:131], 1, v[130:131]
	v_lshlrev_b64 v[128:129], 10, v[128:129]
	v_lshl_add_u64 v[234:235], s[18:19], 0, v[130:131]
	v_lshl_add_u64 v[238:239], s[10:11], 0, v[130:131]
	v_lshl_add_u64 v[130:131], v[128:129], 0, v[216:217]
	v_lshl_add_u64 v[128:129], v[128:129], 0, v[218:219]
	v_lshl_add_u64 v[230:231], v[128:129], 1, s[10:11]
	v_or_b32_e32 v128, 48, v244
	v_ashrrev_i32_e32 v129, 31, v128
	v_lshlrev_b64 v[130:131], 1, v[130:131]
	v_lshlrev_b64 v[128:129], 10, v[128:129]
	v_lshl_add_u64 v[226:227], s[18:19], 0, v[130:131]
	v_lshl_add_u64 v[232:233], s[10:11], 0, v[130:131]
	v_lshl_add_u64 v[130:131], v[128:129], 0, v[216:217]
	v_lshlrev_b64 v[130:131], 1, v[130:131]
	v_lshl_add_u64 v[132:133], v[128:129], 0, v[218:219]
	v_lshl_add_u64 v[222:223], s[18:19], 0, v[130:131]
	v_lshl_add_u64 v[228:229], s[10:11], 0, v[130:131]
	v_lshl_add_u64 v[224:225], v[132:133], 1, s[10:11]
	global_load_dwordx4 v[176:179], v[242:243], off
	global_load_dwordx4 v[172:175], v[234:235], off
	global_load_dwordx4 v[164:167], v[234:235], off offset:256
	global_load_dwordx4 v[168:171], v[238:239], off
	global_load_dwordx4 v[160:163], v[236:237], off
	global_load_dwordx4 v[156:159], v[226:227], off
	global_load_dwordx4 v[132:135], v[224:225], off
	global_load_dwordx4 v[152:155], v[232:233], off
	global_load_dwordx4 v[144:147], v[230:231], off
	global_load_dwordx4 v[148:151], v[226:227], off offset:256
	global_load_dwordx4 v[136:139], v[228:229], off
	global_load_dwordx4 v[140:143], v[222:223], off
	global_load_dwordx4 v[128:131], v[222:223], off offset:256
	v_cmp_gt_u32_e32 vcc, 16, v195
	s_waitcnt vmcnt(0)
	v_lshlrev_b32_e32 v248, 16, v188
	v_and_b32_e32 v249, 0xffff0000, v188
	v_lshlrev_b32_e32 v250, 16, v184
	v_and_b32_e32 v251, 0xffff0000, v184
	v_lshlrev_b32_e32 v188, 16, v189
	v_and_b32_e32 v189, 0xffff0000, v189
	v_lshlrev_b32_e32 v184, 16, v185
	v_and_b32_e32 v185, 0xffff0000, v185
	v_pk_add_f32 v[248:249], v[248:249], v[250:251]
	v_pk_add_f32 v[184:185], v[188:189], v[184:185]
	v_pk_fma_f32 v[188:189], v[124:125], 0.5, v[248:249] op_sel_hi:[1,0,1]
	v_pk_fma_f32 v[184:185], v[126:127], 0.5, v[184:185] op_sel_hi:[1,0,1]
	v_lshlrev_b32_e32 v124, 16, v190
	v_and_b32_e32 v125, 0xffff0000, v190
	v_lshlrev_b32_e32 v126, 16, v186
	v_and_b32_e32 v127, 0xffff0000, v186
	v_pk_add_f32 v[124:125], v[124:125], v[126:127]
	v_lshlrev_b32_e32 v126, 16, v191
	v_and_b32_e32 v127, 0xffff0000, v191
	v_lshlrev_b32_e32 v186, 16, v187
	v_and_b32_e32 v187, 0xffff0000, v187
	v_pk_add_f32 v[126:127], v[126:127], v[186:187]
	v_pk_fma_f32 v[190:191], v[120:121], 0.5, v[124:125] op_sel_hi:[1,0,1]
	v_cvt_pk_bf16_f32 v120, v188, v189
	v_pk_fma_f32 v[186:187], v[122:123], 0.5, v[126:127] op_sel_hi:[1,0,1]
	v_and_b32_e32 v123, 0xffff0000, v120
	v_lshlrev_b32_e32 v122, 16, v120
	v_pk_add_f32 v[122:123], v[188:189], v[122:123] neg_lo:[0,1] neg_hi:[0,1]
	v_cvt_pk_bf16_f32 v121, v184, v185
	v_cvt_pk_bf16_f32 v124, v122, v123
	v_and_b32_e32 v123, 0xffff0000, v121
	v_lshlrev_b32_e32 v122, 16, v121
	v_pk_add_f32 v[122:123], v[184:185], v[122:123] neg_lo:[0,1] neg_hi:[0,1]
	s_nop 0
	v_cvt_pk_bf16_f32 v125, v122, v123
	v_cvt_pk_bf16_f32 v122, v190, v191
	v_cvt_pk_bf16_f32 v123, v186, v187
	v_and_b32_e32 v127, 0xffff0000, v122
	v_lshlrev_b32_e32 v126, 16, v122
	v_and_b32_e32 v249, 0xffff0000, v123
	v_lshlrev_b32_e32 v248, 16, v123
	v_pk_add_f32 v[126:127], v[190:191], v[126:127] neg_lo:[0,1] neg_hi:[0,1]
	v_pk_add_f32 v[248:249], v[186:187], v[248:249] neg_lo:[0,1] neg_hi:[0,1]
	v_cvt_pk_bf16_f32 v126, v126, v127
	v_cvt_pk_bf16_f32 v127, v248, v249
	global_store_dwordx4 v[240:241], v[120:123], off
	global_store_dwordx4 v[246:247], v[124:127], off
	s_nop 0
	v_pk_mul_f32 v[122:123], v[190:191], v[190:191]
	v_pk_mul_f32 v[120:121], v[186:187], v[186:187]
	v_pk_fma_f32 v[122:123], v[188:189], v[188:189], v[122:123]
	v_pk_fma_f32 v[120:121], v[184:185], v[184:185], v[120:121]
	v_add_f32_e32 v122, v122, v123
	v_add_f32_e32 v120, v120, v122
	v_add_f32_e32 v120, v121, v120
	ds_bpermute_b32 v121, v200, v120
	v_lshl_add_u64 v[184:185], v[244:245], 2, s[14:15]
	s_waitcnt lgkmcnt(0)
	v_add_f32_e32 v120, v120, v121
	ds_bpermute_b32 v121, v199, v120
	s_and_saveexec_b64 s[20:21], vcc
	s_cbranch_execz .LBB0_1626
	s_waitcnt lgkmcnt(0)
	v_add_f32_e32 v120, v120, v121
	global_atomic_add_f32 v[184:185], v120, off

.LBB0_2148:
	s_add_u32 s34, s30, 0xfffc0080
	s_addc_u32 s35, s31, -1
	s_add_i32 s51, 0, 0x10000
	v_add_u32_e32 v146, s51, v148
	ds_read_b128 v[138:141], v146
	ds_read_b128 v[142:145], v146 offset:1024
	ds_read_b128 v[150:153], v146 offset:2048
	ds_read_b128 v[154:157], v146 offset:3072
	s_cmp_eq_u32 s33, 12
	s_cselect_b32 s37, s0, s35
	s_cselect_b32 s36, s1, s34
	s_cselect_b32 s35, s7, s25
	s_cselect_b32 s34, s9, s19
	s_add_i32 m0, s44, 0xc000
	ds_read_b128 v[158:161], v149
	ds_read_b128 v[162:165], v149 offset:1024
	ds_read_b128 v[166:169], v149 offset:2048
	ds_read_b128 v[170:173], v149 offset:3072
	ds_read_b128 v[174:177], v149 offset:4096
	ds_read_b128 v[178:181], v149 offset:5120
	ds_read_b128 v[182:185], v149 offset:6144
	ds_read_b128 v[186:189], v149 offset:7168
	global_load_lds_dwordx4 v134, s[30:31]
	v_lshl_add_u64 v[146:147], s[30:31], 0, v[136:137]
	s_add_i32 m0, s44, 0xe000
	s_nop 0
	global_load_lds_dwordx4 v[146:147], off
	s_waitcnt lgkmcnt(8)
	s_barrier
	s_waitcnt lgkmcnt(0)
	s_setprio 1
	s_waitcnt lgkmcnt(0)
	v_mfma_f32_16x16x32_bf16 v[124:127], v[138:141], v[158:161], v[124:127]
	v_mfma_f32_16x16x32_bf16 v[120:123], v[150:153], v[158:161], v[120:123]
	v_mfma_f32_16x16x32_bf16 v[108:111], v[138:141], v[166:169], v[108:111]
	v_mfma_f32_16x16x32_bf16 v[104:107], v[150:153], v[166:169], v[104:107]
	v_mfma_f32_16x16x32_bf16 v[92:95], v[138:141], v[174:177], v[92:95]
	v_mfma_f32_16x16x32_bf16 v[88:91], v[150:153], v[174:177], v[88:91]
	v_mfma_f32_16x16x32_bf16 v[76:79], v[138:141], v[182:185], v[76:79]
	v_mfma_f32_16x16x32_bf16 v[72:75], v[150:153], v[182:185], v[72:75]
	v_mfma_f32_16x16x32_bf16 v[124:127], v[142:145], v[162:165], v[124:127]
	v_mfma_f32_16x16x32_bf16 v[120:123], v[154:157], v[162:165], v[120:123]
	v_mfma_f32_16x16x32_bf16 v[108:111], v[142:145], v[170:173], v[108:111]
	v_mfma_f32_16x16x32_bf16 v[104:107], v[154:157], v[170:173], v[104:107]
	v_mfma_f32_16x16x32_bf16 v[92:95], v[142:145], v[178:181], v[92:95]
	v_mfma_f32_16x16x32_bf16 v[88:91], v[154:157], v[178:181], v[88:91]
	v_mfma_f32_16x16x32_bf16 v[76:79], v[142:145], v[186:189], v[76:79]
	v_mfma_f32_16x16x32_bf16 v[72:75], v[154:157], v[186:189], v[72:75]
	s_setprio 0
	s_barrier
	s_add_i32 s54, 0, 0x14000
	v_add_u32_e32 v146, s54, v148
	s_add_i32 s51, s51, s43
	ds_read_b128 v[198:201], v146
	ds_read_b128 v[206:209], v146 offset:1024
	ds_read_b128 v[210:213], v146 offset:2048
	ds_read_b128 v[214:217], v146 offset:3072
	v_lshl_add_u64 v[146:147], s[34:35], 0, v[192:193]
	s_mov_b32 m0, s51
	v_lshl_add_u64 v[190:191], s[34:35], 0, v[132:133]
	global_load_lds_dwordx4 v[146:147], off
	s_add_i32 m0, s51, 0x2000
	s_nop 0
	global_load_lds_dwordx4 v[190:191], off
	s_barrier
	s_waitcnt lgkmcnt(0)
	s_setprio 1
	s_waitcnt lgkmcnt(0)
	v_mfma_f32_16x16x32_bf16 v[116:119], v[198:201], v[158:161], v[116:119]
	v_mfma_f32_16x16x32_bf16 v[112:115], v[210:213], v[158:161], v[112:115]
	v_mfma_f32_16x16x32_bf16 v[100:103], v[198:201], v[166:169], v[100:103]
	v_mfma_f32_16x16x32_bf16 v[96:99], v[210:213], v[166:169], v[96:99]
	v_mfma_f32_16x16x32_bf16 v[84:87], v[198:201], v[174:177], v[84:87]
	v_mfma_f32_16x16x32_bf16 v[80:83], v[210:213], v[174:177], v[80:83]
	v_mfma_f32_16x16x32_bf16 v[68:71], v[198:201], v[182:185], v[68:71]
	v_mfma_f32_16x16x32_bf16 v[64:67], v[210:213], v[182:185], v[64:67]
	v_mfma_f32_16x16x32_bf16 v[116:119], v[206:209], v[162:165], v[116:119]
	v_mfma_f32_16x16x32_bf16 v[112:115], v[214:217], v[162:165], v[112:115]
	v_mfma_f32_16x16x32_bf16 v[100:103], v[206:209], v[170:173], v[100:103]
	v_mfma_f32_16x16x32_bf16 v[96:99], v[214:217], v[170:173], v[96:99]
	v_mfma_f32_16x16x32_bf16 v[84:87], v[206:209], v[178:181], v[84:87]
	v_mfma_f32_16x16x32_bf16 v[80:83], v[214:217], v[178:181], v[80:83]
	v_mfma_f32_16x16x32_bf16 v[68:71], v[206:209], v[186:189], v[68:71]
	v_mfma_f32_16x16x32_bf16 v[64:67], v[214:217], v[186:189], v[64:67]
	s_setprio 0
	s_mov_b32 m0, s44
	v_lshl_add_u64 v[218:219], s[36:37], 0, v[128:129]
	s_barrier
	ds_read_b128 v[158:161], v149 offset:16384
	ds_read_b128 v[162:165], v149 offset:17408
	ds_read_b128 v[166:169], v149 offset:18432
	ds_read_b128 v[170:173], v149 offset:19456
	ds_read_b128 v[174:177], v149 offset:20480
	ds_read_b128 v[178:181], v149 offset:21504
	ds_read_b128 v[182:185], v149 offset:22528
	ds_read_b128 v[186:189], v149 offset:23552
	global_load_lds_dwordx4 v[218:219], off
	v_lshl_add_u64 v[220:221], s[36:37], 0, v[130:131]
	s_mov_b32 m0, s45
	s_nop 0
	global_load_lds_dwordx4 v[220:221], off
	s_barrier
	s_waitcnt lgkmcnt(0)
	s_setprio 1
	s_waitcnt lgkmcnt(0)
	v_mfma_f32_16x16x32_bf16 v[60:63], v[138:141], v[158:161], v[60:63]
	v_mfma_f32_16x16x32_bf16 v[56:59], v[150:153], v[158:161], v[56:59]
	v_mfma_f32_16x16x32_bf16 v[44:47], v[138:141], v[166:169], v[44:47]
	v_mfma_f32_16x16x32_bf16 v[40:43], v[150:153], v[166:169], v[40:43]
	v_mfma_f32_16x16x32_bf16 v[28:31], v[138:141], v[174:177], v[28:31]
	v_mfma_f32_16x16x32_bf16 v[24:27], v[150:153], v[174:177], v[24:27]
	v_mfma_f32_16x16x32_bf16 v[12:15], v[138:141], v[182:185], v[12:15]
	v_mfma_f32_16x16x32_bf16 v[8:11], v[150:153], v[182:185], v[8:11]
	v_mfma_f32_16x16x32_bf16 v[60:63], v[142:145], v[162:165], v[60:63]
	v_mfma_f32_16x16x32_bf16 v[56:59], v[154:157], v[162:165], v[56:59]
	v_mfma_f32_16x16x32_bf16 v[44:47], v[142:145], v[170:173], v[44:47]
	v_mfma_f32_16x16x32_bf16 v[40:43], v[154:157], v[170:173], v[40:43]
	v_mfma_f32_16x16x32_bf16 v[28:31], v[142:145], v[178:181], v[28:31]
	v_mfma_f32_16x16x32_bf16 v[24:27], v[154:157], v[178:181], v[24:27]
	v_mfma_f32_16x16x32_bf16 v[12:15], v[142:145], v[186:189], v[12:15]
	v_mfma_f32_16x16x32_bf16 v[8:11], v[154:157], v[186:189], v[8:11]
	s_setprio 0
	s_barrier
	s_add_u32 s52, s34, 0x40000
	s_addc_u32 s53, s35, 0
	s_add_i32 s51, s54, s43
	s_mov_b32 m0, s51
	s_nop 0
	global_load_lds_dwordx4 v192, s[52:53]
	v_lshl_add_u64 v[138:139], s[52:53], 0, v[132:133]
	s_add_i32 m0, s51, 0x2000
	s_nop 0
	global_load_lds_dwordx4 v[138:139], off
	s_waitcnt vmcnt(6)
	s_barrier
	s_setprio 1
	v_mfma_f32_16x16x32_bf16 v[52:55], v[198:201], v[158:161], v[52:55]
	v_mfma_f32_16x16x32_bf16 v[48:51], v[210:213], v[158:161], v[48:51]
	v_mfma_f32_16x16x32_bf16 v[36:39], v[198:201], v[166:169], v[36:39]
	v_mfma_f32_16x16x32_bf16 v[32:35], v[210:213], v[166:169], v[32:35]
	v_mfma_f32_16x16x32_bf16 v[20:23], v[198:201], v[174:177], v[20:23]
	v_mfma_f32_16x16x32_bf16 v[16:19], v[210:213], v[174:177], v[16:19]
	v_mfma_f32_16x16x32_bf16 v[4:7], v[198:201], v[182:185], v[4:7]
	v_mfma_f32_16x16x32_bf16 v[0:3], v[210:213], v[182:185], v[0:3]
	v_mfma_f32_16x16x32_bf16 v[52:55], v[206:209], v[162:165], v[52:55]
	v_mfma_f32_16x16x32_bf16 v[48:51], v[214:217], v[162:165], v[48:51]
	v_mfma_f32_16x16x32_bf16 v[36:39], v[206:209], v[170:173], v[36:39]
	v_mfma_f32_16x16x32_bf16 v[32:35], v[214:217], v[170:173], v[32:35]
	v_mfma_f32_16x16x32_bf16 v[20:23], v[206:209], v[178:181], v[20:23]
	v_mfma_f32_16x16x32_bf16 v[16:19], v[214:217], v[178:181], v[16:19]
	v_mfma_f32_16x16x32_bf16 v[4:7], v[206:209], v[186:189], v[4:7]
	v_mfma_f32_16x16x32_bf16 v[0:3], v[214:217], v[186:189], v[0:3]
	s_setprio 0
	s_add_i32 s51, 0, 0x18000
	v_add_u32_e32 v154, s51, v148
	s_barrier
	ds_read_b128 v[138:141], v154
	ds_read_b128 v[142:145], v154 offset:1024
	ds_read_b128 v[150:153], v154 offset:2048
	ds_read_b128 v[154:157], v154 offset:3072
	s_add_u32 s36, s36, 0x40000
	s_addc_u32 s37, s37, 0
	s_mov_b32 m0, s46
	ds_read_b128 v[158:161], v149 offset:32768
	ds_read_b128 v[162:165], v149 offset:33792
	ds_read_b128 v[166:169], v149 offset:34816
	ds_read_b128 v[170:173], v149 offset:35840
	ds_read_b128 v[174:177], v149 offset:36864
	ds_read_b128 v[178:181], v149 offset:37888
	ds_read_b128 v[182:185], v149 offset:38912
	ds_read_b128 v[186:189], v149 offset:39936
	global_load_lds_dwordx4 v128, s[36:37]
	v_lshl_add_u64 v[198:199], s[36:37], 0, v[130:131]
	s_mov_b32 m0, s47
	s_nop 0
	global_load_lds_dwordx4 v[198:199], off
	s_waitcnt lgkmcnt(8)
	s_barrier
	s_waitcnt lgkmcnt(0)
	s_setprio 1
	s_waitcnt lgkmcnt(0)
	v_mfma_f32_16x16x32_bf16 v[124:127], v[138:141], v[158:161], v[124:127]
	v_mfma_f32_16x16x32_bf16 v[120:123], v[150:153], v[158:161], v[120:123]
	v_mfma_f32_16x16x32_bf16 v[108:111], v[138:141], v[166:169], v[108:111]
	v_mfma_f32_16x16x32_bf16 v[104:107], v[150:153], v[166:169], v[104:107]
	v_mfma_f32_16x16x32_bf16 v[92:95], v[138:141], v[174:177], v[92:95]
	v_mfma_f32_16x16x32_bf16 v[88:91], v[150:153], v[174:177], v[88:91]
	v_mfma_f32_16x16x32_bf16 v[76:79], v[138:141], v[182:185], v[76:79]
	v_mfma_f32_16x16x32_bf16 v[72:75], v[150:153], v[182:185], v[72:75]
	v_mfma_f32_16x16x32_bf16 v[124:127], v[142:145], v[162:165], v[124:127]
	v_mfma_f32_16x16x32_bf16 v[120:123], v[154:157], v[162:165], v[120:123]
	v_mfma_f32_16x16x32_bf16 v[108:111], v[142:145], v[170:173], v[108:111]
	v_mfma_f32_16x16x32_bf16 v[104:107], v[154:157], v[170:173], v[104:107]
	v_mfma_f32_16x16x32_bf16 v[92:95], v[142:145], v[178:181], v[92:95]
	v_mfma_f32_16x16x32_bf16 v[88:91], v[154:157], v[178:181], v[88:91]
	v_mfma_f32_16x16x32_bf16 v[76:79], v[142:145], v[186:189], v[76:79]
	v_mfma_f32_16x16x32_bf16 v[72:75], v[154:157], v[186:189], v[72:75]
	s_setprio 0
	s_barrier
	s_add_i32 s36, 0, 0x1c000
	s_add_i32 s37, s51, s43
	v_add_u32_e32 v196, s36, v148
	v_lshl_add_u64 v[146:147], v[146:147], 0, s[80:81]
	s_mov_b32 m0, s37
	ds_read_b128 v[198:201], v196
	ds_read_b128 v[206:209], v196 offset:1024
	ds_read_b128 v[210:213], v196 offset:2048
	ds_read_b128 v[214:217], v196 offset:3072
	global_load_lds_dwordx4 v[146:147], off
	v_lshl_add_u64 v[146:147], v[190:191], 0, s[80:81]
	s_add_i32 m0, s37, 0x2000
	s_nop 0
	global_load_lds_dwordx4 v[146:147], off
	s_barrier
	s_waitcnt lgkmcnt(0)
	s_setprio 1
	s_waitcnt lgkmcnt(0)
	v_mfma_f32_16x16x32_bf16 v[116:119], v[198:201], v[158:161], v[116:119]
	v_mfma_f32_16x16x32_bf16 v[112:115], v[210:213], v[158:161], v[112:115]
	v_mfma_f32_16x16x32_bf16 v[100:103], v[198:201], v[166:169], v[100:103]
	v_mfma_f32_16x16x32_bf16 v[96:99], v[210:213], v[166:169], v[96:99]
	v_mfma_f32_16x16x32_bf16 v[84:87], v[198:201], v[174:177], v[84:87]
	v_mfma_f32_16x16x32_bf16 v[80:83], v[210:213], v[174:177], v[80:83]
	v_mfma_f32_16x16x32_bf16 v[68:71], v[198:201], v[182:185], v[68:71]
	v_mfma_f32_16x16x32_bf16 v[64:67], v[210:213], v[182:185], v[64:67]
	v_mfma_f32_16x16x32_bf16 v[116:119], v[206:209], v[162:165], v[116:119]
	v_mfma_f32_16x16x32_bf16 v[112:115], v[214:217], v[162:165], v[112:115]
	v_mfma_f32_16x16x32_bf16 v[100:103], v[206:209], v[170:173], v[100:103]
	v_mfma_f32_16x16x32_bf16 v[96:99], v[214:217], v[170:173], v[96:99]
	v_mfma_f32_16x16x32_bf16 v[84:87], v[206:209], v[178:181], v[84:87]
	v_mfma_f32_16x16x32_bf16 v[80:83], v[214:217], v[178:181], v[80:83]
	v_mfma_f32_16x16x32_bf16 v[68:71], v[206:209], v[186:189], v[68:71]
	v_mfma_f32_16x16x32_bf16 v[64:67], v[214:217], v[186:189], v[64:67]
	s_setprio 0
	s_mov_b32 m0, s48
	v_lshl_add_u64 v[146:147], v[218:219], 0, s[80:81]
	s_barrier
	ds_read_b128 v[158:161], v149 offset:49152
	ds_read_b128 v[162:165], v149 offset:50176
	ds_read_b128 v[166:169], v149 offset:51200
	ds_read_b128 v[170:173], v149 offset:52224
	ds_read_b128 v[174:177], v149 offset:53248
	ds_read_b128 v[178:181], v149 offset:54272
	ds_read_b128 v[182:185], v149 offset:55296
	ds_read_b128 v[186:189], v149 offset:56320
	global_load_lds_dwordx4 v[146:147], off
	v_lshl_add_u64 v[146:147], v[220:221], 0, s[80:81]
	s_mov_b32 m0, s49
	s_nop 0
	global_load_lds_dwordx4 v[146:147], off
	s_barrier
	s_waitcnt lgkmcnt(0)
	s_setprio 1
	s_waitcnt lgkmcnt(0)
	v_mfma_f32_16x16x32_bf16 v[60:63], v[138:141], v[158:161], v[60:63]
	v_mfma_f32_16x16x32_bf16 v[56:59], v[150:153], v[158:161], v[56:59]
	v_mfma_f32_16x16x32_bf16 v[44:47], v[138:141], v[166:169], v[44:47]
	v_mfma_f32_16x16x32_bf16 v[40:43], v[150:153], v[166:169], v[40:43]
	v_mfma_f32_16x16x32_bf16 v[28:31], v[138:141], v[174:177], v[28:31]
	v_mfma_f32_16x16x32_bf16 v[24:27], v[150:153], v[174:177], v[24:27]
	v_mfma_f32_16x16x32_bf16 v[12:15], v[138:141], v[182:185], v[12:15]
	v_mfma_f32_16x16x32_bf16 v[8:11], v[150:153], v[182:185], v[8:11]
	v_mfma_f32_16x16x32_bf16 v[60:63], v[142:145], v[162:165], v[60:63]
	v_mfma_f32_16x16x32_bf16 v[56:59], v[154:157], v[162:165], v[56:59]
	v_mfma_f32_16x16x32_bf16 v[44:47], v[142:145], v[170:173], v[44:47]
	v_mfma_f32_16x16x32_bf16 v[40:43], v[154:157], v[170:173], v[40:43]
	v_mfma_f32_16x16x32_bf16 v[28:31], v[142:145], v[178:181], v[28:31]
	v_mfma_f32_16x16x32_bf16 v[24:27], v[154:157], v[178:181], v[24:27]
	v_mfma_f32_16x16x32_bf16 v[12:15], v[142:145], v[186:189], v[12:15]
	v_mfma_f32_16x16x32_bf16 v[8:11], v[154:157], v[186:189], v[8:11]
	s_setprio 0
	s_barrier
	s_add_u32 s34, s34, 0x40080
	s_addc_u32 s35, s35, 0
	s_add_i32 s36, s36, s43
	s_mov_b32 m0, s36
	s_nop 0
	global_load_lds_dwordx4 v192, s[34:35]
	v_lshl_add_u64 v[138:139], s[34:35], 0, v[132:133]
	s_add_i32 m0, s36, 0x2000
	s_nop 0
	global_load_lds_dwordx4 v[138:139], off
	s_waitcnt vmcnt(6)
	s_barrier
	s_setprio 1
	v_mfma_f32_16x16x32_bf16 v[52:55], v[198:201], v[158:161], v[52:55]
	v_mfma_f32_16x16x32_bf16 v[48:51], v[210:213], v[158:161], v[48:51]
	v_mfma_f32_16x16x32_bf16 v[36:39], v[198:201], v[166:169], v[36:39]
	v_mfma_f32_16x16x32_bf16 v[32:35], v[210:213], v[166:169], v[32:35]
	v_mfma_f32_16x16x32_bf16 v[20:23], v[198:201], v[174:177], v[20:23]
	v_mfma_f32_16x16x32_bf16 v[16:19], v[210:213], v[174:177], v[16:19]
	v_mfma_f32_16x16x32_bf16 v[4:7], v[198:201], v[182:185], v[4:7]
	v_mfma_f32_16x16x32_bf16 v[0:3], v[210:213], v[182:185], v[0:3]
	v_mfma_f32_16x16x32_bf16 v[52:55], v[206:209], v[162:165], v[52:55]
	v_mfma_f32_16x16x32_bf16 v[48:51], v[214:217], v[162:165], v[48:51]
	v_mfma_f32_16x16x32_bf16 v[36:39], v[206:209], v[170:173], v[36:39]
	v_mfma_f32_16x16x32_bf16 v[32:35], v[214:217], v[170:173], v[32:35]
	v_mfma_f32_16x16x32_bf16 v[20:23], v[206:209], v[178:181], v[20:23]
	v_mfma_f32_16x16x32_bf16 v[16:19], v[214:217], v[178:181], v[16:19]
	v_mfma_f32_16x16x32_bf16 v[4:7], v[206:209], v[186:189], v[4:7]
	v_mfma_f32_16x16x32_bf16 v[0:3], v[214:217], v[186:189], v[0:3]
	s_setprio 0
	s_add_i32 s33, s33, 2
	s_add_u32 s30, s30, 0x100
	s_addc_u32 s31, s31, 0
	s_add_u32 s19, s19, 0x100
	s_addc_u32 s25, s25, 0
	s_cmp_gt_u32 s33, 13
	s_barrier
	s_cbranch_scc0 .LBB0_2148
	v_mov_b32_e32 v138, v252
	s_lshl_b32 s1, s8, 8
	v_readfirstlane_b32 s0, v138
	s_ashr_i32 s7, s0, 2
	s_andn2_b32 s7, s7, 63
	s_add_i32 s7, s7, s1
	v_and_or_b32 v140, v138, 15, s7
	v_ashrrev_i32_e32 v141, 31, v140
	v_lshl_add_u64 v[142:143], v[140:141], 2, s[14:15]
	global_load_dword v139, v[142:143], off
	global_load_dword v153, v[142:143], off offset:64
	global_load_dword v152, v[142:143], off offset:128
	global_load_dword v151, v[142:143], off offset:192
	s_lshl_b32 s1, s6, 8
	s_lshr_b32 s0, s0, 1
	s_and_b32 s0, s0, 0x60
	v_lshrrev_b32_e32 v138, 1, v138
	s_or_b32 s0, s0, s1
	v_and_or_b32 v138, v138, 24, s0
	v_mad_i64_i32 v[154:155], s[0:1], v140, s55, 0
	v_cmp_gt_i32_e32 vcc, s55, v138
	s_waitcnt vmcnt(0)
	v_fmamk_f32 v139, v139, 0x3a800000, v194
	v_mul_f32_e32 v144, 0x4b800000, v139
	v_cmp_gt_f32_e64 s[6:7], s2, v139
	s_nop 1
	v_cndmask_b32_e64 v139, v139, v144, s[6:7]
	v_rsq_f32_e32 v144, v139
	v_ashrrev_i32_e32 v139, 31, v138
	v_mul_f32_e32 v145, 0x45800000, v144
	v_cndmask_b32_e64 v144, v144, v145, s[6:7]
	v_pk_mul_f32 v[126:127], v[126:127], v[144:145] op_sel_hi:[1,0]
	v_pk_mul_f32 v[124:125], v[124:125], v[144:145] op_sel_hi:[1,0]
	v_pk_mul_f32 v[146:147], v[122:123], v[144:145] op_sel_hi:[1,0]
	v_pk_mul_f32 v[120:121], v[120:121], v[144:145] op_sel_hi:[1,0]
	v_lshl_add_u64 v[122:123], v[154:155], 1, s[12:13]
	s_and_saveexec_b64 s[6:7], vcc
	s_cbranch_execz .LBB0_2151
	v_cvt_pk_bf16_f32 v150, v125, v127
	v_cvt_pk_bf16_f32 v145, v124, v126
	v_and_b32_e32 v154, 0xffff0000, v150
	v_lshlrev_b32_e32 v150, 16, v150
	v_or_b32_sdwa v155, v154, v145 dst_sel:DWORD dst_unused:UNUSED_PAD src0_sel:DWORD src1_sel:WORD_1
	v_or_b32_sdwa v154, v150, v145 dst_sel:DWORD dst_unused:UNUSED_PAD src0_sel:DWORD src1_sel:WORD_0
	v_cvt_pk_bf16_f32 v150, v121, v147
	v_cvt_pk_bf16_f32 v145, v120, v146
	v_and_b32_e32 v156, 0xffff0000, v150
	v_lshlrev_b32_e32 v150, 16, v150
	v_lshl_add_u64 v[158:159], v[138:139], 1, v[122:123]
	v_or_b32_sdwa v157, v156, v145 dst_sel:DWORD dst_unused:UNUSED_PAD src0_sel:DWORD src1_sel:WORD_1
	v_or_b32_sdwa v156, v150, v145 dst_sel:DWORD dst_unused:UNUSED_PAD src0_sel:DWORD src1_sel:WORD_0
	global_store_dwordx4 v[158:159], v[154:157], off

.LBB0_2292:
	s_add_u32 s8, s12, 0x100
	s_addc_u32 s9, s13, 0
	s_add_i32 s53, 0, 0x10000
	v_add_u32_e32 v140, s53, v196
	ds_read_b128 v[128:131], v140
	ds_read_b128 v[132:135], v140 offset:1024
	ds_read_b128 v[136:139], v140 offset:2048
	ds_read_b128 v[140:143], v140 offset:3072
	s_cmp_eq_u32 s52, 2
	s_cselect_b32 s15, s31, s9
	s_cselect_b32 s14, s30, s8
	s_cselect_b32 s11, s35, s51
	s_cselect_b32 s10, s34, s33
	v_lshl_add_u64 v[176:177], s[12:13], 0, v[190:191]
	s_add_i32 m0, s42, 0xc000
	ds_read_b128 v[144:147], v198
	ds_read_b128 v[148:151], v198 offset:1024
	ds_read_b128 v[152:155], v198 offset:2048
	ds_read_b128 v[156:159], v198 offset:3072
	ds_read_b128 v[160:163], v198 offset:4096
	ds_read_b128 v[164:167], v198 offset:5120
	ds_read_b128 v[168:171], v198 offset:6144
	ds_read_b128 v[172:175], v198 offset:7168
	global_load_lds_dwordx4 v[176:177], off
	v_lshl_add_u64 v[176:177], s[12:13], 0, v[206:207]
	s_add_i32 m0, s42, 0xe000
	s_nop 0
	global_load_lds_dwordx4 v[176:177], off
	s_waitcnt lgkmcnt(8)
	s_barrier
	s_waitcnt lgkmcnt(0)
	s_setprio 1
	s_waitcnt lgkmcnt(0)
	v_mfma_f32_16x16x32_bf16 v[124:127], v[128:131], v[144:147], v[124:127]
	v_mfma_f32_16x16x32_bf16 v[120:123], v[136:139], v[144:147], v[120:123]
	v_mfma_f32_16x16x32_bf16 v[108:111], v[128:131], v[152:155], v[108:111]
	v_mfma_f32_16x16x32_bf16 v[104:107], v[136:139], v[152:155], v[104:107]
	v_mfma_f32_16x16x32_bf16 v[92:95], v[128:131], v[160:163], v[92:95]
	v_mfma_f32_16x16x32_bf16 v[88:91], v[136:139], v[160:163], v[88:91]
	v_mfma_f32_16x16x32_bf16 v[76:79], v[128:131], v[168:171], v[76:79]
	v_mfma_f32_16x16x32_bf16 v[72:75], v[136:139], v[168:171], v[72:75]
	v_mfma_f32_16x16x32_bf16 v[124:127], v[132:135], v[148:151], v[124:127]
	v_mfma_f32_16x16x32_bf16 v[120:123], v[140:143], v[148:151], v[120:123]
	v_mfma_f32_16x16x32_bf16 v[108:111], v[132:135], v[156:159], v[108:111]
	v_mfma_f32_16x16x32_bf16 v[104:107], v[140:143], v[156:159], v[104:107]
	v_mfma_f32_16x16x32_bf16 v[92:95], v[132:135], v[164:167], v[92:95]
	v_mfma_f32_16x16x32_bf16 v[88:91], v[140:143], v[164:167], v[88:91]
	v_mfma_f32_16x16x32_bf16 v[76:79], v[132:135], v[172:175], v[76:79]
	v_mfma_f32_16x16x32_bf16 v[72:75], v[140:143], v[172:175], v[72:75]
	s_setprio 0
	s_barrier
	s_add_i32 s54, 0, 0x14000
	v_add_u32_e32 v184, s54, v196
	s_add_i32 s12, s53, s41
	ds_read_b128 v[176:179], v184
	ds_read_b128 v[180:183], v184 offset:1024
	ds_read_b128 v[208:211], v184 offset:2048
	ds_read_b128 v[212:215], v184 offset:3072
	v_lshl_add_u64 v[184:185], s[10:11], 0, v[186:187]
	s_mov_b32 m0, s12
	v_lshl_add_u64 v[200:201], s[10:11], 0, v[188:189]
	global_load_lds_dwordx4 v[184:185], off
	s_add_i32 m0, s12, 0x2000
	s_nop 0
	global_load_lds_dwordx4 v[200:201], off
	s_barrier
	s_waitcnt lgkmcnt(0)
	s_setprio 1
	s_waitcnt lgkmcnt(0)
	v_mfma_f32_16x16x32_bf16 v[116:119], v[176:179], v[144:147], v[116:119]
	v_mfma_f32_16x16x32_bf16 v[112:115], v[208:211], v[144:147], v[112:115]
	v_mfma_f32_16x16x32_bf16 v[100:103], v[176:179], v[152:155], v[100:103]
	v_mfma_f32_16x16x32_bf16 v[96:99], v[208:211], v[152:155], v[96:99]
	v_mfma_f32_16x16x32_bf16 v[84:87], v[176:179], v[160:163], v[84:87]
	v_mfma_f32_16x16x32_bf16 v[80:83], v[208:211], v[160:163], v[80:83]
	v_mfma_f32_16x16x32_bf16 v[68:71], v[176:179], v[168:171], v[68:71]
	v_mfma_f32_16x16x32_bf16 v[64:67], v[208:211], v[168:171], v[64:67]
	v_mfma_f32_16x16x32_bf16 v[116:119], v[180:183], v[148:151], v[116:119]
	v_mfma_f32_16x16x32_bf16 v[112:115], v[212:215], v[148:151], v[112:115]
	v_mfma_f32_16x16x32_bf16 v[100:103], v[180:183], v[156:159], v[100:103]
	v_mfma_f32_16x16x32_bf16 v[96:99], v[212:215], v[156:159], v[96:99]
	v_mfma_f32_16x16x32_bf16 v[84:87], v[180:183], v[164:167], v[84:87]
	v_mfma_f32_16x16x32_bf16 v[80:83], v[212:215], v[164:167], v[80:83]
	v_mfma_f32_16x16x32_bf16 v[68:71], v[180:183], v[172:175], v[68:71]
	v_mfma_f32_16x16x32_bf16 v[64:67], v[212:215], v[172:175], v[64:67]
	s_setprio 0
	s_mov_b32 m0, s42
	v_lshl_add_u64 v[216:217], s[14:15], 0, v[186:187]
	s_barrier
	ds_read_b128 v[144:147], v198 offset:16384
	ds_read_b128 v[148:151], v198 offset:17408
	ds_read_b128 v[152:155], v198 offset:18432
	ds_read_b128 v[156:159], v198 offset:19456
	ds_read_b128 v[160:163], v198 offset:20480
	ds_read_b128 v[164:167], v198 offset:21504
	ds_read_b128 v[168:171], v198 offset:22528
	ds_read_b128 v[172:175], v198 offset:23552
	global_load_lds_dwordx4 v[216:217], off
	v_lshl_add_u64 v[218:219], s[14:15], 0, v[188:189]
	s_mov_b32 m0, s43
	s_nop 0
	global_load_lds_dwordx4 v[218:219], off
	s_barrier
	s_waitcnt lgkmcnt(0)
	s_setprio 1
	s_waitcnt lgkmcnt(0)
	v_mfma_f32_16x16x32_bf16 v[60:63], v[128:131], v[144:147], v[60:63]
	v_mfma_f32_16x16x32_bf16 v[56:59], v[136:139], v[144:147], v[56:59]
	v_mfma_f32_16x16x32_bf16 v[44:47], v[128:131], v[152:155], v[44:47]
	v_mfma_f32_16x16x32_bf16 v[40:43], v[136:139], v[152:155], v[40:43]
	v_mfma_f32_16x16x32_bf16 v[28:31], v[128:131], v[160:163], v[28:31]
	v_mfma_f32_16x16x32_bf16 v[24:27], v[136:139], v[160:163], v[24:27]
	v_mfma_f32_16x16x32_bf16 v[12:15], v[128:131], v[168:171], v[12:15]
	v_mfma_f32_16x16x32_bf16 v[8:11], v[136:139], v[168:171], v[8:11]
	v_mfma_f32_16x16x32_bf16 v[60:63], v[132:135], v[148:151], v[60:63]
	v_mfma_f32_16x16x32_bf16 v[56:59], v[140:143], v[148:151], v[56:59]
	v_mfma_f32_16x16x32_bf16 v[44:47], v[132:135], v[156:159], v[44:47]
	v_mfma_f32_16x16x32_bf16 v[40:43], v[140:143], v[156:159], v[40:43]
	v_mfma_f32_16x16x32_bf16 v[28:31], v[132:135], v[164:167], v[28:31]
	v_mfma_f32_16x16x32_bf16 v[24:27], v[140:143], v[164:167], v[24:27]
	v_mfma_f32_16x16x32_bf16 v[12:15], v[132:135], v[172:175], v[12:15]
	v_mfma_f32_16x16x32_bf16 v[8:11], v[140:143], v[172:175], v[8:11]
	s_setprio 0
	s_barrier
	s_add_u32 s12, s10, 0x18000
	s_addc_u32 s13, s11, 0
	s_add_i32 s53, s54, s41
	s_mov_b32 m0, s53
	s_nop 0
	global_load_lds_dwordx4 v186, s[12:13]
	v_lshl_add_u64 v[128:129], s[12:13], 0, v[188:189]
	s_add_i32 m0, s53, 0x2000
	s_nop 0
	global_load_lds_dwordx4 v[128:129], off
	s_waitcnt vmcnt(6)
	s_barrier
	s_setprio 1
	v_mfma_f32_16x16x32_bf16 v[52:55], v[176:179], v[144:147], v[52:55]
	v_mfma_f32_16x16x32_bf16 v[48:51], v[208:211], v[144:147], v[48:51]
	v_mfma_f32_16x16x32_bf16 v[36:39], v[176:179], v[152:155], v[36:39]
	v_mfma_f32_16x16x32_bf16 v[32:35], v[208:211], v[152:155], v[32:35]
	v_mfma_f32_16x16x32_bf16 v[20:23], v[176:179], v[160:163], v[20:23]
	v_mfma_f32_16x16x32_bf16 v[16:19], v[208:211], v[160:163], v[16:19]
	v_mfma_f32_16x16x32_bf16 v[4:7], v[176:179], v[168:171], v[4:7]
	v_mfma_f32_16x16x32_bf16 v[0:3], v[208:211], v[168:171], v[0:3]
	v_mfma_f32_16x16x32_bf16 v[52:55], v[180:183], v[148:151], v[52:55]
	v_mfma_f32_16x16x32_bf16 v[48:51], v[212:215], v[148:151], v[48:51]
	v_mfma_f32_16x16x32_bf16 v[36:39], v[180:183], v[156:159], v[36:39]
	v_mfma_f32_16x16x32_bf16 v[32:35], v[212:215], v[156:159], v[32:35]
	v_mfma_f32_16x16x32_bf16 v[20:23], v[180:183], v[164:167], v[20:23]
	v_mfma_f32_16x16x32_bf16 v[16:19], v[212:215], v[164:167], v[16:19]
	v_mfma_f32_16x16x32_bf16 v[4:7], v[180:183], v[172:175], v[4:7]
	v_mfma_f32_16x16x32_bf16 v[0:3], v[212:215], v[172:175], v[0:3]
	s_setprio 0
	s_add_i32 s53, 0, 0x18000
	v_add_u32_e32 v140, s53, v196
	s_barrier
	ds_read_b128 v[128:131], v140
	ds_read_b128 v[132:135], v140 offset:1024
	ds_read_b128 v[136:139], v140 offset:2048
	ds_read_b128 v[140:143], v140 offset:3072
	s_add_u32 s12, s14, 0x18000
	s_addc_u32 s13, s15, 0
	s_mov_b32 m0, s44
	v_lshl_add_u64 v[176:177], s[12:13], 0, v[186:187]
	ds_read_b128 v[144:147], v198 offset:32768
	ds_read_b128 v[148:151], v198 offset:33792
	ds_read_b128 v[152:155], v198 offset:34816
	ds_read_b128 v[156:159], v198 offset:35840
	ds_read_b128 v[160:163], v198 offset:36864
	ds_read_b128 v[164:167], v198 offset:37888
	ds_read_b128 v[168:171], v198 offset:38912
	ds_read_b128 v[172:175], v198 offset:39936
	global_load_lds_dwordx4 v[176:177], off
	v_lshl_add_u64 v[176:177], s[12:13], 0, v[188:189]
	s_mov_b32 m0, s45
	s_nop 0
	global_load_lds_dwordx4 v[176:177], off
	s_waitcnt lgkmcnt(8)
	s_barrier
	s_waitcnt lgkmcnt(0)
	s_setprio 1
	s_waitcnt lgkmcnt(0)
	v_mfma_f32_16x16x32_bf16 v[124:127], v[128:131], v[144:147], v[124:127]
	v_mfma_f32_16x16x32_bf16 v[120:123], v[136:139], v[144:147], v[120:123]
	v_mfma_f32_16x16x32_bf16 v[108:111], v[128:131], v[152:155], v[108:111]
	v_mfma_f32_16x16x32_bf16 v[104:107], v[136:139], v[152:155], v[104:107]
	v_mfma_f32_16x16x32_bf16 v[92:95], v[128:131], v[160:163], v[92:95]
	v_mfma_f32_16x16x32_bf16 v[88:91], v[136:139], v[160:163], v[88:91]
	v_mfma_f32_16x16x32_bf16 v[76:79], v[128:131], v[168:171], v[76:79]
	v_mfma_f32_16x16x32_bf16 v[72:75], v[136:139], v[168:171], v[72:75]
	v_mfma_f32_16x16x32_bf16 v[124:127], v[132:135], v[148:151], v[124:127]
	v_mfma_f32_16x16x32_bf16 v[120:123], v[140:143], v[148:151], v[120:123]
	v_mfma_f32_16x16x32_bf16 v[108:111], v[132:135], v[156:159], v[108:111]
	v_mfma_f32_16x16x32_bf16 v[104:107], v[140:143], v[156:159], v[104:107]
	v_mfma_f32_16x16x32_bf16 v[92:95], v[132:135], v[164:167], v[92:95]
	v_mfma_f32_16x16x32_bf16 v[88:91], v[140:143], v[164:167], v[88:91]
	v_mfma_f32_16x16x32_bf16 v[76:79], v[132:135], v[172:175], v[76:79]
	v_mfma_f32_16x16x32_bf16 v[72:75], v[140:143], v[172:175], v[72:75]
	s_setprio 0
	s_barrier
	s_add_i32 s12, 0, 0x1c000
	s_add_i32 s13, s53, s41
	v_add_u32_e32 v192, s12, v196
	v_lshl_add_u64 v[184:185], v[184:185], 0, s[80:81]
	s_mov_b32 m0, s13
	ds_read_b128 v[176:179], v192
	ds_read_b128 v[180:183], v192 offset:1024
	ds_read_b128 v[208:211], v192 offset:2048
	ds_read_b128 v[212:215], v192 offset:3072
	global_load_lds_dwordx4 v[184:185], off
	v_lshl_add_u64 v[184:185], v[200:201], 0, s[80:81]
	s_add_i32 m0, s13, 0x2000
	s_nop 0
	global_load_lds_dwordx4 v[184:185], off
	s_barrier
	s_waitcnt lgkmcnt(0)
	s_setprio 1
	s_waitcnt lgkmcnt(0)
	v_mfma_f32_16x16x32_bf16 v[116:119], v[176:179], v[144:147], v[116:119]
	v_mfma_f32_16x16x32_bf16 v[112:115], v[208:211], v[144:147], v[112:115]
	v_mfma_f32_16x16x32_bf16 v[100:103], v[176:179], v[152:155], v[100:103]
	v_mfma_f32_16x16x32_bf16 v[96:99], v[208:211], v[152:155], v[96:99]
	v_mfma_f32_16x16x32_bf16 v[84:87], v[176:179], v[160:163], v[84:87]
	v_mfma_f32_16x16x32_bf16 v[80:83], v[208:211], v[160:163], v[80:83]
	v_mfma_f32_16x16x32_bf16 v[68:71], v[176:179], v[168:171], v[68:71]
	v_mfma_f32_16x16x32_bf16 v[64:67], v[208:211], v[168:171], v[64:67]
	v_mfma_f32_16x16x32_bf16 v[116:119], v[180:183], v[148:151], v[116:119]
	v_mfma_f32_16x16x32_bf16 v[112:115], v[212:215], v[148:151], v[112:115]
	v_mfma_f32_16x16x32_bf16 v[100:103], v[180:183], v[156:159], v[100:103]
	v_mfma_f32_16x16x32_bf16 v[96:99], v[212:215], v[156:159], v[96:99]
	v_mfma_f32_16x16x32_bf16 v[84:87], v[180:183], v[164:167], v[84:87]
	v_mfma_f32_16x16x32_bf16 v[80:83], v[212:215], v[164:167], v[80:83]
	v_mfma_f32_16x16x32_bf16 v[68:71], v[180:183], v[172:175], v[68:71]
	v_mfma_f32_16x16x32_bf16 v[64:67], v[212:215], v[172:175], v[64:67]
	s_setprio 0
	s_mov_b32 m0, s46
	v_lshl_add_u64 v[184:185], v[216:217], 0, s[80:81]
	s_barrier
	ds_read_b128 v[144:147], v198 offset:49152
	ds_read_b128 v[148:151], v198 offset:50176
	ds_read_b128 v[152:155], v198 offset:51200
	ds_read_b128 v[156:159], v198 offset:52224
	ds_read_b128 v[160:163], v198 offset:53248
	ds_read_b128 v[164:167], v198 offset:54272
	ds_read_b128 v[168:171], v198 offset:55296
	ds_read_b128 v[172:175], v198 offset:56320
	global_load_lds_dwordx4 v[184:185], off
	v_lshl_add_u64 v[184:185], v[218:219], 0, s[80:81]
	s_mov_b32 m0, s47
	s_nop 0
	global_load_lds_dwordx4 v[184:185], off
	s_barrier
	s_waitcnt lgkmcnt(0)
	s_setprio 1
	s_waitcnt lgkmcnt(0)
	v_mfma_f32_16x16x32_bf16 v[60:63], v[128:131], v[144:147], v[60:63]
	v_mfma_f32_16x16x32_bf16 v[56:59], v[136:139], v[144:147], v[56:59]
	v_mfma_f32_16x16x32_bf16 v[44:47], v[128:131], v[152:155], v[44:47]
	v_mfma_f32_16x16x32_bf16 v[40:43], v[136:139], v[152:155], v[40:43]
	v_mfma_f32_16x16x32_bf16 v[28:31], v[128:131], v[160:163], v[28:31]
	v_mfma_f32_16x16x32_bf16 v[24:27], v[136:139], v[160:163], v[24:27]
	v_mfma_f32_16x16x32_bf16 v[12:15], v[128:131], v[168:171], v[12:15]
	v_mfma_f32_16x16x32_bf16 v[8:11], v[136:139], v[168:171], v[8:11]
	v_mfma_f32_16x16x32_bf16 v[60:63], v[132:135], v[148:151], v[60:63]
	v_mfma_f32_16x16x32_bf16 v[56:59], v[140:143], v[148:151], v[56:59]
	v_mfma_f32_16x16x32_bf16 v[44:47], v[132:135], v[156:159], v[44:47]
	v_mfma_f32_16x16x32_bf16 v[40:43], v[140:143], v[156:159], v[40:43]
	v_mfma_f32_16x16x32_bf16 v[28:31], v[132:135], v[164:167], v[28:31]
	v_mfma_f32_16x16x32_bf16 v[24:27], v[140:143], v[164:167], v[24:27]
	v_mfma_f32_16x16x32_bf16 v[12:15], v[132:135], v[172:175], v[12:15]
	v_mfma_f32_16x16x32_bf16 v[8:11], v[140:143], v[172:175], v[8:11]
	s_setprio 0
	s_barrier
	s_add_u32 s10, s10, 0x18080
	s_addc_u32 s11, s11, 0
	s_add_i32 s12, s12, s41
	s_mov_b32 m0, s12
	s_nop 0
	global_load_lds_dwordx4 v186, s[10:11]
	v_lshl_add_u64 v[128:129], s[10:11], 0, v[188:189]
	s_add_i32 m0, s12, 0x2000
	s_nop 0
	global_load_lds_dwordx4 v[128:129], off
	s_waitcnt vmcnt(6)
	s_barrier
	s_setprio 1
	v_mfma_f32_16x16x32_bf16 v[52:55], v[176:179], v[144:147], v[52:55]
	v_mfma_f32_16x16x32_bf16 v[48:51], v[208:211], v[144:147], v[48:51]
	v_mfma_f32_16x16x32_bf16 v[36:39], v[176:179], v[152:155], v[36:39]
	v_mfma_f32_16x16x32_bf16 v[32:35], v[208:211], v[152:155], v[32:35]
	v_mfma_f32_16x16x32_bf16 v[20:23], v[176:179], v[160:163], v[20:23]
	v_mfma_f32_16x16x32_bf16 v[16:19], v[208:211], v[160:163], v[16:19]
	v_mfma_f32_16x16x32_bf16 v[4:7], v[176:179], v[168:171], v[4:7]
	v_mfma_f32_16x16x32_bf16 v[0:3], v[208:211], v[168:171], v[0:3]
	v_mfma_f32_16x16x32_bf16 v[52:55], v[180:183], v[148:151], v[52:55]
	v_mfma_f32_16x16x32_bf16 v[48:51], v[212:215], v[148:151], v[48:51]
	v_mfma_f32_16x16x32_bf16 v[36:39], v[180:183], v[156:159], v[36:39]
	v_mfma_f32_16x16x32_bf16 v[32:35], v[212:215], v[156:159], v[32:35]
	v_mfma_f32_16x16x32_bf16 v[20:23], v[180:183], v[164:167], v[20:23]
	v_mfma_f32_16x16x32_bf16 v[16:19], v[212:215], v[164:167], v[16:19]
	v_mfma_f32_16x16x32_bf16 v[4:7], v[180:183], v[172:175], v[4:7]
	v_mfma_f32_16x16x32_bf16 v[0:3], v[212:215], v[172:175], v[0:3]
	s_setprio 0
	s_add_i32 s52, s52, 2
	s_add_u32 s33, s33, 0x100
	s_addc_u32 s51, s51, 0
	s_cmp_gt_u32 s52, 3
	s_mov_b64 s[12:13], s[8:9]
	s_barrier
	s_cbranch_scc0 .LBB0_2292
	v_mov_b32_e32 v128, v252
	s_lshl_b32 s1, s1, 8
	v_readfirstlane_b32 s8, v128
	s_ashr_i32 s9, s8, 2
	s_andn2_b32 s9, s9, 63
	s_add_i32 s9, s9, s1
	v_and_or_b32 v208, v128, 15, s9
	v_ashrrev_i32_e32 v209, 31, v208
	v_lshl_add_u64 v[210:211], v[208:209], 2, s[26:27]
	global_load_dword v225, v[210:211], off
	s_lshr_b32 s1, s8, 1
	s_and_b32 s1, s1, 0x60
	s_lshl_b32 s0, s0, 8
	v_lshrrev_b32_e32 v128, 2, v128
	s_or_b32 s0, s1, s0
	s_movk_i32 s1, 0x1fcf
	v_and_b32_e32 v226, 12, v128
	v_and_or_b32 v128, v208, s1, 16
	s_movk_i32 s1, 0x4000
	v_cmp_gt_i32_e32 vcc, s1, v208
	s_mul_hi_i32 s1, s0, 0x2aaaaaab
	s_lshr_b32 s8, s1, 31
	s_lshr_b32 s1, s1, 4
	s_add_i32 s1, s1, s8
	s_mulk_i32 s1, 0x60
	v_add_u32_e32 v129, 0x7ffc000, v208
	s_sub_i32 s1, s0, s1
	v_lshlrev_b32_e32 v199, 1, v226
	v_cndmask_b32_e32 v128, v129, v128, vcc
	s_cmp_eq_u32 s1, 64
	v_lshl_or_b32 v192, v128, 5, v199
	s_cselect_b64 s[10:11], -1, 0
	v_lshl_add_u64 v[128:129], v[192:193], 2, s[28:29]
	v_mov_b32_e32 v160, 0
	s_and_b64 vcc, exec, s[10:11]
	v_mov_b32_e32 v178, 0
	v_mov_b32_e32 v218, 0
	v_mov_b32_e32 v179, 0
	v_mov_b32_e32 v219, 0
	v_mov_b32_e32 v182, 0
	v_mov_b32_e32 v220, 0
	v_mov_b32_e32 v183, 0
	v_mov_b32_e32 v221, 0
	s_cbranch_vccz .LBB0_2295
	global_load_dwordx4 v[178:181], v[128:129], off
	global_load_dwordx4 v[182:185], v[128:129], off offset:16
	s_waitcnt vmcnt(0)
	v_mov_b32_e32 v218, v179
	v_mov_b32_e32 v179, v180
	v_mov_b32_e32 v219, v181
	v_mov_b32_e32 v220, v183
	v_mov_b32_e32 v183, v184
	v_mov_b32_e32 v221, v185

.LBB0_2484:
	s_add_u32 s34, s30, 0xfffe0080
	s_addc_u32 s35, s31, -1
	s_add_i32 s53, 0, 0x10000
	v_add_u32_e32 v140, s53, v196
	ds_read_b128 v[128:131], v140
	ds_read_b128 v[132:135], v140 offset:1024
	ds_read_b128 v[136:139], v140 offset:2048
	ds_read_b128 v[140:143], v140 offset:3072
	s_cmp_eq_u32 s52, 4
	s_cselect_b32 s37, s0, s35
	s_cselect_b32 s36, s1, s34
	s_cselect_b32 s35, s15, s33
	s_cselect_b32 s34, s21, s27
	v_lshl_add_u64 v[176:177], s[30:31], 0, v[212:213]
	s_add_i32 m0, s29, 0xc000
	ds_read_b128 v[144:147], v198
	ds_read_b128 v[148:151], v198 offset:1024
	ds_read_b128 v[152:155], v198 offset:2048
	ds_read_b128 v[156:159], v198 offset:3072
	ds_read_b128 v[160:163], v198 offset:4096
	ds_read_b128 v[164:167], v198 offset:5120
	ds_read_b128 v[168:171], v198 offset:6144
	ds_read_b128 v[172:175], v198 offset:7168
	global_load_lds_dwordx4 v[176:177], off
	v_lshl_add_u64 v[176:177], s[30:31], 0, v[214:215]
	s_add_i32 m0, s29, 0xe000
	s_nop 0
	global_load_lds_dwordx4 v[176:177], off
	s_waitcnt lgkmcnt(8)
	s_barrier
	s_waitcnt lgkmcnt(0)
	s_setprio 1
	s_waitcnt lgkmcnt(0)
	v_mfma_f32_16x16x32_bf16 v[124:127], v[128:131], v[144:147], v[124:127]
	v_mfma_f32_16x16x32_bf16 v[120:123], v[136:139], v[144:147], v[120:123]
	v_mfma_f32_16x16x32_bf16 v[108:111], v[128:131], v[152:155], v[108:111]
	v_mfma_f32_16x16x32_bf16 v[104:107], v[136:139], v[152:155], v[104:107]
	v_mfma_f32_16x16x32_bf16 v[92:95], v[128:131], v[160:163], v[92:95]
	v_mfma_f32_16x16x32_bf16 v[88:91], v[136:139], v[160:163], v[88:91]
	v_mfma_f32_16x16x32_bf16 v[76:79], v[128:131], v[168:171], v[76:79]
	v_mfma_f32_16x16x32_bf16 v[72:75], v[136:139], v[168:171], v[72:75]
	v_mfma_f32_16x16x32_bf16 v[124:127], v[132:135], v[148:151], v[124:127]
	v_mfma_f32_16x16x32_bf16 v[120:123], v[140:143], v[148:151], v[120:123]
	v_mfma_f32_16x16x32_bf16 v[108:111], v[132:135], v[156:159], v[108:111]
	v_mfma_f32_16x16x32_bf16 v[104:107], v[140:143], v[156:159], v[104:107]
	v_mfma_f32_16x16x32_bf16 v[92:95], v[132:135], v[164:167], v[92:95]
	v_mfma_f32_16x16x32_bf16 v[88:91], v[140:143], v[164:167], v[88:91]
	v_mfma_f32_16x16x32_bf16 v[76:79], v[132:135], v[172:175], v[76:79]
	v_mfma_f32_16x16x32_bf16 v[72:75], v[140:143], v[172:175], v[72:75]
	s_setprio 0
	s_barrier
	s_add_i32 s56, 0, 0x14000
	s_add_i32 s53, s53, s45
	v_add_u32_e32 v188, s56, v196
	v_lshl_add_u64 v[200:201], s[34:35], 0, v[192:193]
	s_mov_b32 m0, s53
	ds_read_b128 v[176:179], v188
	ds_read_b128 v[180:183], v188 offset:1024
	ds_read_b128 v[184:187], v188 offset:2048
	ds_read_b128 v[188:191], v188 offset:3072
	global_load_lds_dwordx4 v[200:201], off
	v_lshl_add_u64 v[202:203], s[34:35], 0, v[210:211]
	s_add_i32 m0, s53, 0x2000
	s_nop 0
	global_load_lds_dwordx4 v[202:203], off
	s_barrier
	s_waitcnt lgkmcnt(0)
	s_setprio 1
	s_waitcnt lgkmcnt(0)
	v_mfma_f32_16x16x32_bf16 v[116:119], v[176:179], v[144:147], v[116:119]
	v_mfma_f32_16x16x32_bf16 v[112:115], v[184:187], v[144:147], v[112:115]
	v_mfma_f32_16x16x32_bf16 v[100:103], v[176:179], v[152:155], v[100:103]
	v_mfma_f32_16x16x32_bf16 v[96:99], v[184:187], v[152:155], v[96:99]
	v_mfma_f32_16x16x32_bf16 v[84:87], v[176:179], v[160:163], v[84:87]
	v_mfma_f32_16x16x32_bf16 v[80:83], v[184:187], v[160:163], v[80:83]
	v_mfma_f32_16x16x32_bf16 v[68:71], v[176:179], v[168:171], v[68:71]
	v_mfma_f32_16x16x32_bf16 v[64:67], v[184:187], v[168:171], v[64:67]
	v_mfma_f32_16x16x32_bf16 v[116:119], v[180:183], v[148:151], v[116:119]
	v_mfma_f32_16x16x32_bf16 v[112:115], v[188:191], v[148:151], v[112:115]
	v_mfma_f32_16x16x32_bf16 v[100:103], v[180:183], v[156:159], v[100:103]
	v_mfma_f32_16x16x32_bf16 v[96:99], v[188:191], v[156:159], v[96:99]
	v_mfma_f32_16x16x32_bf16 v[84:87], v[180:183], v[164:167], v[84:87]
	v_mfma_f32_16x16x32_bf16 v[80:83], v[188:191], v[164:167], v[80:83]
	v_mfma_f32_16x16x32_bf16 v[68:71], v[180:183], v[172:175], v[68:71]
	v_mfma_f32_16x16x32_bf16 v[64:67], v[188:191], v[172:175], v[64:67]
	s_setprio 0
	s_mov_b32 m0, s29
	v_lshl_add_u64 v[204:205], s[36:37], 0, v[206:207]
	s_barrier
	ds_read_b128 v[144:147], v198 offset:16384
	ds_read_b128 v[148:151], v198 offset:17408
	ds_read_b128 v[152:155], v198 offset:18432
	ds_read_b128 v[156:159], v198 offset:19456
	ds_read_b128 v[160:163], v198 offset:20480
	ds_read_b128 v[164:167], v198 offset:21504
	ds_read_b128 v[168:171], v198 offset:22528
	ds_read_b128 v[172:175], v198 offset:23552
	global_load_lds_dwordx4 v[204:205], off
	v_lshl_add_u64 v[216:217], s[36:37], 0, v[208:209]
	s_mov_b32 m0, s46
	s_nop 0
	global_load_lds_dwordx4 v[216:217], off
	s_barrier
	s_waitcnt lgkmcnt(0)
	s_setprio 1
	s_waitcnt lgkmcnt(0)
	v_mfma_f32_16x16x32_bf16 v[60:63], v[128:131], v[144:147], v[60:63]
	v_mfma_f32_16x16x32_bf16 v[56:59], v[136:139], v[144:147], v[56:59]
	v_mfma_f32_16x16x32_bf16 v[44:47], v[128:131], v[152:155], v[44:47]
	v_mfma_f32_16x16x32_bf16 v[40:43], v[136:139], v[152:155], v[40:43]
	v_mfma_f32_16x16x32_bf16 v[28:31], v[128:131], v[160:163], v[28:31]
	v_mfma_f32_16x16x32_bf16 v[24:27], v[136:139], v[160:163], v[24:27]
	v_mfma_f32_16x16x32_bf16 v[12:15], v[128:131], v[168:171], v[12:15]
	v_mfma_f32_16x16x32_bf16 v[8:11], v[136:139], v[168:171], v[8:11]
	v_mfma_f32_16x16x32_bf16 v[60:63], v[132:135], v[148:151], v[60:63]
	v_mfma_f32_16x16x32_bf16 v[56:59], v[140:143], v[148:151], v[56:59]
	v_mfma_f32_16x16x32_bf16 v[44:47], v[132:135], v[156:159], v[44:47]
	v_mfma_f32_16x16x32_bf16 v[40:43], v[140:143], v[156:159], v[40:43]
	v_mfma_f32_16x16x32_bf16 v[28:31], v[132:135], v[164:167], v[28:31]
	v_mfma_f32_16x16x32_bf16 v[24:27], v[140:143], v[164:167], v[24:27]
	v_mfma_f32_16x16x32_bf16 v[12:15], v[132:135], v[172:175], v[12:15]
	v_mfma_f32_16x16x32_bf16 v[8:11], v[140:143], v[172:175], v[8:11]
	s_setprio 0
	s_barrier
	s_add_u32 s54, s34, 0x20000
	s_addc_u32 s55, s35, 0
	s_add_i32 s53, s56, s45
	s_mov_b32 m0, s53
	s_nop 0
	global_load_lds_dwordx4 v192, s[54:55]
	v_lshl_add_u64 v[128:129], s[54:55], 0, v[210:211]
	s_add_i32 m0, s53, 0x2000
	s_nop 0
	global_load_lds_dwordx4 v[128:129], off
	s_waitcnt vmcnt(6)
	s_barrier
	s_setprio 1
	v_mfma_f32_16x16x32_bf16 v[52:55], v[176:179], v[144:147], v[52:55]
	v_mfma_f32_16x16x32_bf16 v[48:51], v[184:187], v[144:147], v[48:51]
	v_mfma_f32_16x16x32_bf16 v[36:39], v[176:179], v[152:155], v[36:39]
	v_mfma_f32_16x16x32_bf16 v[32:35], v[184:187], v[152:155], v[32:35]
	v_mfma_f32_16x16x32_bf16 v[20:23], v[176:179], v[160:163], v[20:23]
	v_mfma_f32_16x16x32_bf16 v[16:19], v[184:187], v[160:163], v[16:19]
	v_mfma_f32_16x16x32_bf16 v[4:7], v[176:179], v[168:171], v[4:7]
	v_mfma_f32_16x16x32_bf16 v[0:3], v[184:187], v[168:171], v[0:3]
	v_mfma_f32_16x16x32_bf16 v[52:55], v[180:183], v[148:151], v[52:55]
	v_mfma_f32_16x16x32_bf16 v[48:51], v[188:191], v[148:151], v[48:51]
	v_mfma_f32_16x16x32_bf16 v[36:39], v[180:183], v[156:159], v[36:39]
	v_mfma_f32_16x16x32_bf16 v[32:35], v[188:191], v[156:159], v[32:35]
	v_mfma_f32_16x16x32_bf16 v[20:23], v[180:183], v[164:167], v[20:23]
	v_mfma_f32_16x16x32_bf16 v[16:19], v[188:191], v[164:167], v[16:19]
	v_mfma_f32_16x16x32_bf16 v[4:7], v[180:183], v[172:175], v[4:7]
	v_mfma_f32_16x16x32_bf16 v[0:3], v[188:191], v[172:175], v[0:3]
	s_setprio 0
	s_add_i32 s53, 0, 0x18000
	v_add_u32_e32 v140, s53, v196
	s_barrier
	ds_read_b128 v[128:131], v140
	ds_read_b128 v[132:135], v140 offset:1024
	ds_read_b128 v[136:139], v140 offset:2048
	ds_read_b128 v[140:143], v140 offset:3072
	s_add_u32 s36, s36, 0x20000
	s_addc_u32 s37, s37, 0
	s_mov_b32 m0, s47
	v_lshl_add_u64 v[176:177], s[36:37], 0, v[206:207]
	ds_read_b128 v[144:147], v198 offset:32768
	ds_read_b128 v[148:151], v198 offset:33792
	ds_read_b128 v[152:155], v198 offset:34816
	ds_read_b128 v[156:159], v198 offset:35840
	ds_read_b128 v[160:163], v198 offset:36864
	ds_read_b128 v[164:167], v198 offset:37888
	ds_read_b128 v[168:171], v198 offset:38912
	ds_read_b128 v[172:175], v198 offset:39936
	global_load_lds_dwordx4 v[176:177], off
	v_lshl_add_u64 v[176:177], s[36:37], 0, v[208:209]
	s_mov_b32 m0, s48
	s_nop 0
	global_load_lds_dwordx4 v[176:177], off
	s_waitcnt lgkmcnt(8)
	s_barrier
	s_waitcnt lgkmcnt(0)
	s_setprio 1
	s_waitcnt lgkmcnt(0)
	v_mfma_f32_16x16x32_bf16 v[124:127], v[128:131], v[144:147], v[124:127]
	v_mfma_f32_16x16x32_bf16 v[120:123], v[136:139], v[144:147], v[120:123]
	v_mfma_f32_16x16x32_bf16 v[108:111], v[128:131], v[152:155], v[108:111]
	v_mfma_f32_16x16x32_bf16 v[104:107], v[136:139], v[152:155], v[104:107]
	v_mfma_f32_16x16x32_bf16 v[92:95], v[128:131], v[160:163], v[92:95]
	v_mfma_f32_16x16x32_bf16 v[88:91], v[136:139], v[160:163], v[88:91]
	v_mfma_f32_16x16x32_bf16 v[76:79], v[128:131], v[168:171], v[76:79]
	v_mfma_f32_16x16x32_bf16 v[72:75], v[136:139], v[168:171], v[72:75]
	v_mfma_f32_16x16x32_bf16 v[124:127], v[132:135], v[148:151], v[124:127]
	v_mfma_f32_16x16x32_bf16 v[120:123], v[140:143], v[148:151], v[120:123]
	v_mfma_f32_16x16x32_bf16 v[108:111], v[132:135], v[156:159], v[108:111]
	v_mfma_f32_16x16x32_bf16 v[104:107], v[140:143], v[156:159], v[104:107]
	v_mfma_f32_16x16x32_bf16 v[92:95], v[132:135], v[164:167], v[92:95]
	v_mfma_f32_16x16x32_bf16 v[88:91], v[140:143], v[164:167], v[88:91]
	v_mfma_f32_16x16x32_bf16 v[76:79], v[132:135], v[172:175], v[76:79]
	v_mfma_f32_16x16x32_bf16 v[72:75], v[140:143], v[172:175], v[72:75]
	s_setprio 0
	s_barrier
	s_add_i32 s36, 0, 0x1c000
	s_add_i32 s37, s53, s45
	v_add_u32_e32 v188, s36, v196
	v_lshl_add_u64 v[200:201], v[200:201], 0, s[80:81]
	s_mov_b32 m0, s37
	ds_read_b128 v[176:179], v188
	ds_read_b128 v[180:183], v188 offset:1024
	ds_read_b128 v[184:187], v188 offset:2048
	ds_read_b128 v[188:191], v188 offset:3072
	global_load_lds_dwordx4 v[200:201], off
	v_lshl_add_u64 v[200:201], v[202:203], 0, s[80:81]
	s_add_i32 m0, s37, 0x2000
	s_nop 0
	global_load_lds_dwordx4 v[200:201], off
	s_barrier
	s_waitcnt lgkmcnt(0)
	s_setprio 1
	s_waitcnt lgkmcnt(0)
	v_mfma_f32_16x16x32_bf16 v[116:119], v[176:179], v[144:147], v[116:119]
	v_mfma_f32_16x16x32_bf16 v[112:115], v[184:187], v[144:147], v[112:115]
	v_mfma_f32_16x16x32_bf16 v[100:103], v[176:179], v[152:155], v[100:103]
	v_mfma_f32_16x16x32_bf16 v[96:99], v[184:187], v[152:155], v[96:99]
	v_mfma_f32_16x16x32_bf16 v[84:87], v[176:179], v[160:163], v[84:87]
	v_mfma_f32_16x16x32_bf16 v[80:83], v[184:187], v[160:163], v[80:83]
	v_mfma_f32_16x16x32_bf16 v[68:71], v[176:179], v[168:171], v[68:71]
	v_mfma_f32_16x16x32_bf16 v[64:67], v[184:187], v[168:171], v[64:67]
	v_mfma_f32_16x16x32_bf16 v[116:119], v[180:183], v[148:151], v[116:119]
	v_mfma_f32_16x16x32_bf16 v[112:115], v[188:191], v[148:151], v[112:115]
	v_mfma_f32_16x16x32_bf16 v[100:103], v[180:183], v[156:159], v[100:103]
	v_mfma_f32_16x16x32_bf16 v[96:99], v[188:191], v[156:159], v[96:99]
	v_mfma_f32_16x16x32_bf16 v[84:87], v[180:183], v[164:167], v[84:87]
	v_mfma_f32_16x16x32_bf16 v[80:83], v[188:191], v[164:167], v[80:83]
	v_mfma_f32_16x16x32_bf16 v[68:71], v[180:183], v[172:175], v[68:71]
	v_mfma_f32_16x16x32_bf16 v[64:67], v[188:191], v[172:175], v[64:67]
	s_setprio 0
	s_mov_b32 m0, s49
	v_lshl_add_u64 v[200:201], v[204:205], 0, s[80:81]
	s_barrier
	ds_read_b128 v[144:147], v198 offset:49152
	ds_read_b128 v[148:151], v198 offset:50176
	ds_read_b128 v[152:155], v198 offset:51200
	ds_read_b128 v[156:159], v198 offset:52224
	ds_read_b128 v[160:163], v198 offset:53248
	ds_read_b128 v[164:167], v198 offset:54272
	ds_read_b128 v[168:171], v198 offset:55296
	ds_read_b128 v[172:175], v198 offset:56320
	global_load_lds_dwordx4 v[200:201], off
	v_lshl_add_u64 v[200:201], v[216:217], 0, s[80:81]
	s_mov_b32 m0, s50
	s_nop 0
	global_load_lds_dwordx4 v[200:201], off
	s_barrier
	s_waitcnt lgkmcnt(0)
	s_setprio 1
	s_waitcnt lgkmcnt(0)
	v_mfma_f32_16x16x32_bf16 v[60:63], v[128:131], v[144:147], v[60:63]
	v_mfma_f32_16x16x32_bf16 v[56:59], v[136:139], v[144:147], v[56:59]
	v_mfma_f32_16x16x32_bf16 v[44:47], v[128:131], v[152:155], v[44:47]
	v_mfma_f32_16x16x32_bf16 v[40:43], v[136:139], v[152:155], v[40:43]
	v_mfma_f32_16x16x32_bf16 v[28:31], v[128:131], v[160:163], v[28:31]
	v_mfma_f32_16x16x32_bf16 v[24:27], v[136:139], v[160:163], v[24:27]
	v_mfma_f32_16x16x32_bf16 v[12:15], v[128:131], v[168:171], v[12:15]
	v_mfma_f32_16x16x32_bf16 v[8:11], v[136:139], v[168:171], v[8:11]
	v_mfma_f32_16x16x32_bf16 v[60:63], v[132:135], v[148:151], v[60:63]
	v_mfma_f32_16x16x32_bf16 v[56:59], v[140:143], v[148:151], v[56:59]
	v_mfma_f32_16x16x32_bf16 v[44:47], v[132:135], v[156:159], v[44:47]
	v_mfma_f32_16x16x32_bf16 v[40:43], v[140:143], v[156:159], v[40:43]
	v_mfma_f32_16x16x32_bf16 v[28:31], v[132:135], v[164:167], v[28:31]
	v_mfma_f32_16x16x32_bf16 v[24:27], v[140:143], v[164:167], v[24:27]
	v_mfma_f32_16x16x32_bf16 v[12:15], v[132:135], v[172:175], v[12:15]
	v_mfma_f32_16x16x32_bf16 v[8:11], v[140:143], v[172:175], v[8:11]
	s_setprio 0
	s_barrier
	s_add_u32 s34, s34, 0x20080
	s_addc_u32 s35, s35, 0
	s_add_i32 s36, s36, s45
	s_mov_b32 m0, s36
	s_nop 0
	global_load_lds_dwordx4 v192, s[34:35]
	v_lshl_add_u64 v[128:129], s[34:35], 0, v[210:211]
	s_add_i32 m0, s36, 0x2000
	s_nop 0
	global_load_lds_dwordx4 v[128:129], off
	s_waitcnt vmcnt(6)
	s_barrier
	s_setprio 1
	v_mfma_f32_16x16x32_bf16 v[52:55], v[176:179], v[144:147], v[52:55]
	v_mfma_f32_16x16x32_bf16 v[48:51], v[184:187], v[144:147], v[48:51]
	v_mfma_f32_16x16x32_bf16 v[36:39], v[176:179], v[152:155], v[36:39]
	v_mfma_f32_16x16x32_bf16 v[32:35], v[184:187], v[152:155], v[32:35]
	v_mfma_f32_16x16x32_bf16 v[20:23], v[176:179], v[160:163], v[20:23]
	v_mfma_f32_16x16x32_bf16 v[16:19], v[184:187], v[160:163], v[16:19]
	v_mfma_f32_16x16x32_bf16 v[4:7], v[176:179], v[168:171], v[4:7]
	v_mfma_f32_16x16x32_bf16 v[0:3], v[184:187], v[168:171], v[0:3]
	v_mfma_f32_16x16x32_bf16 v[52:55], v[180:183], v[148:151], v[52:55]
	v_mfma_f32_16x16x32_bf16 v[48:51], v[188:191], v[148:151], v[48:51]
	v_mfma_f32_16x16x32_bf16 v[36:39], v[180:183], v[156:159], v[36:39]
	v_mfma_f32_16x16x32_bf16 v[32:35], v[188:191], v[156:159], v[32:35]
	v_mfma_f32_16x16x32_bf16 v[20:23], v[180:183], v[164:167], v[20:23]
	v_mfma_f32_16x16x32_bf16 v[16:19], v[188:191], v[164:167], v[16:19]
	v_mfma_f32_16x16x32_bf16 v[4:7], v[180:183], v[172:175], v[4:7]
	v_mfma_f32_16x16x32_bf16 v[0:3], v[188:191], v[172:175], v[0:3]
	s_setprio 0
	s_add_i32 s52, s52, 2
	s_add_u32 s30, s30, 0x100
	s_addc_u32 s31, s31, 0
	s_add_u32 s27, s27, 0x100
	s_addc_u32 s33, s33, 0
	s_cmp_gt_u32 s52, 5
	s_barrier
	s_cbranch_scc0 .LBB0_2484
	v_mov_b32_e32 v128, v252
	s_lshl_b32 s1, s28, 8
	v_readfirstlane_b32 s0, v128
	s_ashr_i32 s15, s0, 2
	s_andn2_b32 s15, s15, 63
	s_lshr_b32 s0, s0, 1
	s_add_i32 s15, s15, s1
	s_and_b32 s0, s0, 0x60
	s_lshl_b32 s1, s26, 8
	v_and_or_b32 v218, v128, 15, s15
	v_lshrrev_b32_e32 v128, 1, v128
	s_or_b32 s0, s0, s1
	v_and_b32_e32 v129, 64, v195
	v_and_or_b32 v216, v128, 24, s0
	v_xor_b32_e32 v128, 16, v195
	v_add_u32_e32 v129, 64, v129
	v_cmp_lt_i32_e32 vcc, v128, v129
	v_ashrrev_i32_e32 v219, 31, v218
	v_ashrrev_i32_e32 v217, 31, v216
	v_cndmask_b32_e32 v128, v195, v128, vcc
	v_lshlrev_b32_e32 v200, 2, v128
	v_xor_b32_e32 v128, 32, v195
	v_cmp_lt_i32_e32 vcc, v128, v129
	v_or_b32_e32 v220, 0x80, v216
	v_ashrrev_i32_e32 v221, 31, v220
	v_cndmask_b32_e32 v128, v195, v128, vcc
	v_lshlrev_b32_e32 v199, 2, v128
	v_lshlrev_b64 v[128:129], 10, v[218:219]
	v_lshl_add_u64 v[130:131], v[128:129], 0, v[216:217]
	v_lshlrev_b64 v[130:131], 1, v[130:131]
	v_lshl_add_u64 v[246:247], s[8:9], 0, v[130:131]
	v_lshl_add_u64 v[250:251], s[10:11], 0, v[130:131]
	global_load_dwordx4 v[188:191], v[246:247], off
	global_load_dwordx4 v[180:183], v[246:247], off offset:256
	global_load_dwordx4 v[184:187], v[250:251], off
	v_or_b32_e32 v242, 16, v218
	v_lshl_add_u64 v[128:129], v[128:129], 0, v[220:221]
	v_ashrrev_i32_e32 v243, 31, v242
	v_lshl_add_u64 v[248:249], v[128:129], 1, s[10:11]
	v_lshlrev_b64 v[128:129], 10, v[242:243]
	v_or_b32_e32 v234, 32, v218
	v_lshl_add_u64 v[130:131], v[128:129], 0, v[216:217]
	v_lshl_add_u64 v[128:129], v[128:129], 0, v[220:221]
	v_ashrrev_i32_e32 v235, 31, v234
	v_lshlrev_b64 v[130:131], 1, v[130:131]
	v_lshl_add_u64 v[240:241], v[128:129], 1, s[10:11]
	v_lshlrev_b64 v[128:129], 10, v[234:235]
	v_or_b32_e32 v226, 48, v218
	v_lshl_add_u64 v[238:239], s[8:9], 0, v[130:131]
	v_lshl_add_u64 v[244:245], s[10:11], 0, v[130:131]
	v_lshl_add_u64 v[130:131], v[128:129], 0, v[216:217]
	v_lshl_add_u64 v[128:129], v[128:129], 0, v[220:221]
	v_ashrrev_i32_e32 v227, 31, v226
	v_lshlrev_b64 v[130:131], 1, v[130:131]
	v_lshl_add_u64 v[232:233], v[128:129], 1, s[10:11]
	v_lshlrev_b64 v[128:129], 10, v[226:227]
	v_lshl_add_u64 v[228:229], s[8:9], 0, v[130:131]
	v_lshl_add_u64 v[236:237], s[10:11], 0, v[130:131]
	v_lshl_add_u64 v[130:131], v[128:129], 0, v[216:217]
	v_lshlrev_b64 v[130:131], 1, v[130:131]
	v_lshl_add_u64 v[132:133], v[128:129], 0, v[220:221]
	v_lshl_add_u64 v[222:223], s[8:9], 0, v[130:131]
	v_lshl_add_u64 v[230:231], s[10:11], 0, v[130:131]
	v_lshl_add_u64 v[224:225], v[132:133], 1, s[10:11]
	global_load_dwordx4 v[176:179], v[248:249], off
	global_load_dwordx4 v[172:175], v[238:239], off
	global_load_dwordx4 v[164:167], v[238:239], off offset:256
	global_load_dwordx4 v[168:171], v[244:245], off
	global_load_dwordx4 v[160:163], v[240:241], off
	global_load_dwordx4 v[156:159], v[228:229], off
	global_load_dwordx4 v[132:135], v[224:225], off
	global_load_dwordx4 v[152:155], v[236:237], off
	global_load_dwordx4 v[144:147], v[232:233], off
	global_load_dwordx4 v[148:151], v[228:229], off offset:256
	global_load_dwordx4 v[136:139], v[230:231], off
	global_load_dwordx4 v[140:143], v[222:223], off
	global_load_dwordx4 v[128:131], v[222:223], off offset:256
	v_cmp_gt_u32_e32 vcc, 16, v195
	s_waitcnt vmcnt(0)
	v_lshlrev_b32_e32 v202, 16, v188
	v_and_b32_e32 v203, 0xffff0000, v188
	v_lshlrev_b32_e32 v204, 16, v184
	v_and_b32_e32 v205, 0xffff0000, v184
	v_lshlrev_b32_e32 v188, 16, v189
	v_and_b32_e32 v189, 0xffff0000, v189
	v_lshlrev_b32_e32 v184, 16, v185
	v_and_b32_e32 v185, 0xffff0000, v185
	v_pk_add_f32 v[202:203], v[202:203], v[204:205]
	v_pk_add_f32 v[184:185], v[188:189], v[184:185]
	v_pk_add_f32 v[188:189], v[124:125], v[202:203]
	v_pk_add_f32 v[184:185], v[126:127], v[184:185]
	v_lshlrev_b32_e32 v124, 16, v190
	v_and_b32_e32 v125, 0xffff0000, v190
	v_lshlrev_b32_e32 v126, 16, v186
	v_and_b32_e32 v127, 0xffff0000, v186
	v_pk_add_f32 v[124:125], v[124:125], v[126:127]
	v_lshlrev_b32_e32 v126, 16, v191
	v_and_b32_e32 v127, 0xffff0000, v191
	v_lshlrev_b32_e32 v186, 16, v187
	v_and_b32_e32 v187, 0xffff0000, v187
	v_pk_add_f32 v[126:127], v[126:127], v[186:187]
	v_pk_add_f32 v[190:191], v[120:121], v[124:125]
	v_cvt_pk_bf16_f32 v120, v188, v189
	v_pk_add_f32 v[186:187], v[122:123], v[126:127]
	v_and_b32_e32 v123, 0xffff0000, v120
	v_lshlrev_b32_e32 v122, 16, v120
	v_pk_add_f32 v[122:123], v[188:189], v[122:123] neg_lo:[0,1] neg_hi:[0,1]
	v_cvt_pk_bf16_f32 v121, v184, v185
	v_cvt_pk_bf16_f32 v124, v122, v123
	v_and_b32_e32 v123, 0xffff0000, v121
	v_lshlrev_b32_e32 v122, 16, v121
	v_pk_add_f32 v[122:123], v[184:185], v[122:123] neg_lo:[0,1] neg_hi:[0,1]
	s_nop 0
	v_cvt_pk_bf16_f32 v125, v122, v123
	v_cvt_pk_bf16_f32 v122, v190, v191
	v_cvt_pk_bf16_f32 v123, v186, v187
	v_and_b32_e32 v127, 0xffff0000, v122
	v_lshlrev_b32_e32 v126, 16, v122
	v_and_b32_e32 v203, 0xffff0000, v123
	v_lshlrev_b32_e32 v202, 16, v123
	v_pk_add_f32 v[126:127], v[190:191], v[126:127] neg_lo:[0,1] neg_hi:[0,1]
	v_pk_add_f32 v[202:203], v[186:187], v[202:203] neg_lo:[0,1] neg_hi:[0,1]
	v_cvt_pk_bf16_f32 v126, v126, v127
	v_cvt_pk_bf16_f32 v127, v202, v203
	global_store_dwordx4 v[246:247], v[120:123], off
	global_store_dwordx4 v[250:251], v[124:127], off
	s_nop 0
	v_pk_mul_f32 v[122:123], v[190:191], v[190:191]
	v_pk_mul_f32 v[120:121], v[186:187], v[186:187]
	v_pk_fma_f32 v[122:123], v[188:189], v[188:189], v[122:123]
	v_pk_fma_f32 v[120:121], v[184:185], v[184:185], v[120:121]
	v_add_f32_e32 v122, v122, v123
	v_add_f32_e32 v120, v120, v122
	v_add_f32_e32 v120, v121, v120
	ds_bpermute_b32 v121, v200, v120
	s_waitcnt lgkmcnt(0)
	v_add_f32_e32 v122, v120, v121
	ds_bpermute_b32 v123, v199, v122
	v_lshl_add_u64 v[120:121], v[218:219], 2, s[12:13]
	s_and_saveexec_b64 s[26:27], vcc
	s_cbranch_execz .LBB0_2487
	s_waitcnt lgkmcnt(0)
	v_add_f32_e32 v122, v122, v123
	global_atomic_add_f32 v[120:121], v122, off

.LBB0_2804:
	s_add_u32 s20, s18, 0xfffc0080
	s_addc_u32 s21, s19, -1
	s_add_i32 s42, 0, 0x10000
	v_add_u32_e32 v150, s42, v151
	ds_read_b128 v[138:141], v150
	ds_read_b128 v[142:145], v150 offset:1024
	ds_read_b128 v[146:149], v150 offset:2048
	ds_read_b128 v[154:157], v150 offset:3072
	s_cmp_eq_u32 s41, 12
	s_cselect_b32 s23, s9, s21
	s_cselect_b32 s22, s33, s20
	s_cselect_b32 s21, s11, s40
	s_cselect_b32 s20, s38, s39
	s_add_i32 m0, s17, 0xc000
	ds_read_b128 v[158:161], v152
	ds_read_b128 v[162:165], v152 offset:1024
	ds_read_b128 v[166:169], v152 offset:2048
	ds_read_b128 v[170:173], v152 offset:3072
	ds_read_b128 v[174:177], v152 offset:4096
	ds_read_b128 v[178:181], v152 offset:5120
	ds_read_b128 v[182:185], v152 offset:6144
	ds_read_b128 v[186:189], v152 offset:7168
	global_load_lds_dwordx4 v136, s[18:19]
	s_add_i32 m0, s17, 0xe000
	s_nop 0
	global_load_lds_dwordx4 v134, s[18:19]
	s_waitcnt lgkmcnt(8)
	s_barrier
	s_waitcnt lgkmcnt(0)
	s_setprio 1
	s_waitcnt lgkmcnt(0)
	v_mfma_f32_16x16x32_bf16 v[124:127], v[138:141], v[158:161], v[124:127]
	v_mfma_f32_16x16x32_bf16 v[116:119], v[146:149], v[158:161], v[116:119]
	v_mfma_f32_16x16x32_bf16 v[108:111], v[138:141], v[166:169], v[108:111]
	v_mfma_f32_16x16x32_bf16 v[100:103], v[146:149], v[166:169], v[100:103]
	v_mfma_f32_16x16x32_bf16 v[92:95], v[138:141], v[174:177], v[92:95]
	v_mfma_f32_16x16x32_bf16 v[84:87], v[146:149], v[174:177], v[84:87]
	v_mfma_f32_16x16x32_bf16 v[76:79], v[138:141], v[182:185], v[76:79]
	v_mfma_f32_16x16x32_bf16 v[68:71], v[146:149], v[182:185], v[68:71]
	v_mfma_f32_16x16x32_bf16 v[124:127], v[142:145], v[162:165], v[124:127]
	v_mfma_f32_16x16x32_bf16 v[116:119], v[154:157], v[162:165], v[116:119]
	v_mfma_f32_16x16x32_bf16 v[108:111], v[142:145], v[170:173], v[108:111]
	v_mfma_f32_16x16x32_bf16 v[100:103], v[154:157], v[170:173], v[100:103]
	v_mfma_f32_16x16x32_bf16 v[92:95], v[142:145], v[178:181], v[92:95]
	v_mfma_f32_16x16x32_bf16 v[84:87], v[154:157], v[178:181], v[84:87]
	v_mfma_f32_16x16x32_bf16 v[76:79], v[142:145], v[186:189], v[76:79]
	v_mfma_f32_16x16x32_bf16 v[68:71], v[154:157], v[186:189], v[68:71]
	s_setprio 0
	s_barrier
	s_add_i32 s44, 0, 0x14000
	s_add_i32 s42, s42, s28
	v_add_u32_e32 v150, s44, v151
	v_lshl_add_u64 v[190:191], s[20:21], 0, v[192:193]
	s_mov_b32 m0, s42
	ds_read_b128 v[198:201], v150
	ds_read_b128 v[206:209], v150 offset:1024
	ds_read_b128 v[210:213], v150 offset:2048
	ds_read_b128 v[214:217], v150 offset:3072
	global_load_lds_dwordx4 v[190:191], off
	v_lshl_add_u64 v[202:203], s[20:21], 0, v[128:129]
	s_add_i32 m0, s42, 0x2000
	s_nop 0
	global_load_lds_dwordx4 v[202:203], off
	s_barrier
	s_waitcnt lgkmcnt(0)
	s_setprio 1
	s_waitcnt lgkmcnt(0)
	v_mfma_f32_16x16x32_bf16 v[120:123], v[198:201], v[158:161], v[120:123]
	v_mfma_f32_16x16x32_bf16 v[112:115], v[210:213], v[158:161], v[112:115]
	v_mfma_f32_16x16x32_bf16 v[104:107], v[198:201], v[166:169], v[104:107]
	v_mfma_f32_16x16x32_bf16 v[96:99], v[210:213], v[166:169], v[96:99]
	v_mfma_f32_16x16x32_bf16 v[88:91], v[198:201], v[174:177], v[88:91]
	v_mfma_f32_16x16x32_bf16 v[80:83], v[210:213], v[174:177], v[80:83]
	v_mfma_f32_16x16x32_bf16 v[72:75], v[198:201], v[182:185], v[72:75]
	v_mfma_f32_16x16x32_bf16 v[64:67], v[210:213], v[182:185], v[64:67]
	v_mfma_f32_16x16x32_bf16 v[120:123], v[206:209], v[162:165], v[120:123]
	v_mfma_f32_16x16x32_bf16 v[112:115], v[214:217], v[162:165], v[112:115]
	v_mfma_f32_16x16x32_bf16 v[104:107], v[206:209], v[170:173], v[104:107]
	v_mfma_f32_16x16x32_bf16 v[96:99], v[214:217], v[170:173], v[96:99]
	v_mfma_f32_16x16x32_bf16 v[88:91], v[206:209], v[178:181], v[88:91]
	v_mfma_f32_16x16x32_bf16 v[80:83], v[214:217], v[178:181], v[80:83]
	v_mfma_f32_16x16x32_bf16 v[72:75], v[206:209], v[186:189], v[72:75]
	v_mfma_f32_16x16x32_bf16 v[64:67], v[214:217], v[186:189], v[64:67]
	s_setprio 0
	s_mov_b32 m0, s17
	v_lshl_add_u64 v[204:205], s[22:23], 0, v[132:133]
	s_barrier
	ds_read_b128 v[158:161], v152 offset:16384
	ds_read_b128 v[162:165], v152 offset:17408
	ds_read_b128 v[166:169], v152 offset:18432
	ds_read_b128 v[170:173], v152 offset:19456
	ds_read_b128 v[174:177], v152 offset:20480
	ds_read_b128 v[178:181], v152 offset:21504
	ds_read_b128 v[182:185], v152 offset:22528
	ds_read_b128 v[186:189], v152 offset:23552
	global_load_lds_dwordx4 v[204:205], off
	v_lshl_add_u64 v[218:219], s[22:23], 0, v[130:131]
	s_mov_b32 m0, s29
	s_nop 0
	global_load_lds_dwordx4 v[218:219], off
	s_barrier
	s_waitcnt lgkmcnt(0)
	s_setprio 1
	s_waitcnt lgkmcnt(0)
	v_mfma_f32_16x16x32_bf16 v[60:63], v[138:141], v[158:161], v[60:63]
	v_mfma_f32_16x16x32_bf16 v[52:55], v[146:149], v[158:161], v[52:55]
	v_mfma_f32_16x16x32_bf16 v[44:47], v[138:141], v[166:169], v[44:47]
	v_mfma_f32_16x16x32_bf16 v[36:39], v[146:149], v[166:169], v[36:39]
	v_mfma_f32_16x16x32_bf16 v[28:31], v[138:141], v[174:177], v[28:31]
	v_mfma_f32_16x16x32_bf16 v[20:23], v[146:149], v[174:177], v[20:23]
	v_mfma_f32_16x16x32_bf16 v[12:15], v[138:141], v[182:185], v[12:15]
	v_mfma_f32_16x16x32_bf16 v[4:7], v[146:149], v[182:185], v[4:7]
	v_mfma_f32_16x16x32_bf16 v[60:63], v[142:145], v[162:165], v[60:63]
	v_mfma_f32_16x16x32_bf16 v[52:55], v[154:157], v[162:165], v[52:55]
	v_mfma_f32_16x16x32_bf16 v[44:47], v[142:145], v[170:173], v[44:47]
	v_mfma_f32_16x16x32_bf16 v[36:39], v[154:157], v[170:173], v[36:39]
	v_mfma_f32_16x16x32_bf16 v[28:31], v[142:145], v[178:181], v[28:31]
	v_mfma_f32_16x16x32_bf16 v[20:23], v[154:157], v[178:181], v[20:23]
	v_mfma_f32_16x16x32_bf16 v[12:15], v[142:145], v[186:189], v[12:15]
	v_mfma_f32_16x16x32_bf16 v[4:7], v[154:157], v[186:189], v[4:7]
	s_setprio 0
	s_barrier
	s_add_u32 s42, s20, 0x40000
	s_addc_u32 s43, s21, 0
	s_add_i32 s44, s44, s28
	v_lshl_add_u64 v[138:139], s[42:43], 0, v[192:193]
	s_mov_b32 m0, s44
	s_nop 0
	global_load_lds_dwordx4 v[138:139], off
	v_lshl_add_u64 v[138:139], s[42:43], 0, v[128:129]
	s_add_i32 m0, s44, 0x2000
	s_nop 0
	global_load_lds_dwordx4 v[138:139], off
	s_waitcnt vmcnt(6)
	s_barrier
	s_setprio 1
	v_mfma_f32_16x16x32_bf16 v[56:59], v[198:201], v[158:161], v[56:59]
	v_mfma_f32_16x16x32_bf16 v[48:51], v[210:213], v[158:161], v[48:51]
	v_mfma_f32_16x16x32_bf16 v[40:43], v[198:201], v[166:169], v[40:43]
	v_mfma_f32_16x16x32_bf16 v[32:35], v[210:213], v[166:169], v[32:35]
	v_mfma_f32_16x16x32_bf16 v[24:27], v[198:201], v[174:177], v[24:27]
	v_mfma_f32_16x16x32_bf16 v[16:19], v[210:213], v[174:177], v[16:19]
	v_mfma_f32_16x16x32_bf16 v[8:11], v[198:201], v[182:185], v[8:11]
	v_mfma_f32_16x16x32_bf16 v[0:3], v[210:213], v[182:185], v[0:3]
	v_mfma_f32_16x16x32_bf16 v[56:59], v[206:209], v[162:165], v[56:59]
	v_mfma_f32_16x16x32_bf16 v[48:51], v[214:217], v[162:165], v[48:51]
	v_mfma_f32_16x16x32_bf16 v[40:43], v[206:209], v[170:173], v[40:43]
	v_mfma_f32_16x16x32_bf16 v[32:35], v[214:217], v[170:173], v[32:35]
	v_mfma_f32_16x16x32_bf16 v[24:27], v[206:209], v[178:181], v[24:27]
	v_mfma_f32_16x16x32_bf16 v[16:19], v[214:217], v[178:181], v[16:19]
	v_mfma_f32_16x16x32_bf16 v[8:11], v[206:209], v[186:189], v[8:11]
	v_mfma_f32_16x16x32_bf16 v[0:3], v[214:217], v[186:189], v[0:3]
	s_setprio 0
	s_add_i32 s42, 0, 0x18000
	v_add_u32_e32 v150, s42, v151
	s_barrier
	ds_read_b128 v[138:141], v150
	ds_read_b128 v[142:145], v150 offset:1024
	ds_read_b128 v[146:149], v150 offset:2048
	ds_read_b128 v[154:157], v150 offset:3072
	s_add_u32 s22, s22, 0x40000
	s_addc_u32 s23, s23, 0
	s_mov_b32 m0, s30
	ds_read_b128 v[158:161], v152 offset:32768
	ds_read_b128 v[162:165], v152 offset:33792
	ds_read_b128 v[166:169], v152 offset:34816
	ds_read_b128 v[170:173], v152 offset:35840
	ds_read_b128 v[174:177], v152 offset:36864
	ds_read_b128 v[178:181], v152 offset:37888
	ds_read_b128 v[182:185], v152 offset:38912
	ds_read_b128 v[186:189], v152 offset:39936
	global_load_lds_dwordx4 v132, s[22:23]
	v_lshl_add_u64 v[198:199], s[22:23], 0, v[130:131]
	s_mov_b32 m0, s31
	s_nop 0
	global_load_lds_dwordx4 v[198:199], off
	s_waitcnt lgkmcnt(8)
	s_barrier
	s_waitcnt lgkmcnt(0)
	s_setprio 1
	s_waitcnt lgkmcnt(0)
	v_mfma_f32_16x16x32_bf16 v[124:127], v[138:141], v[158:161], v[124:127]
	v_mfma_f32_16x16x32_bf16 v[116:119], v[146:149], v[158:161], v[116:119]
	v_mfma_f32_16x16x32_bf16 v[108:111], v[138:141], v[166:169], v[108:111]
	v_mfma_f32_16x16x32_bf16 v[100:103], v[146:149], v[166:169], v[100:103]
	v_mfma_f32_16x16x32_bf16 v[92:95], v[138:141], v[174:177], v[92:95]
	v_mfma_f32_16x16x32_bf16 v[84:87], v[146:149], v[174:177], v[84:87]
	v_mfma_f32_16x16x32_bf16 v[76:79], v[138:141], v[182:185], v[76:79]
	v_mfma_f32_16x16x32_bf16 v[68:71], v[146:149], v[182:185], v[68:71]
	v_mfma_f32_16x16x32_bf16 v[124:127], v[142:145], v[162:165], v[124:127]
	v_mfma_f32_16x16x32_bf16 v[116:119], v[154:157], v[162:165], v[116:119]
	v_mfma_f32_16x16x32_bf16 v[108:111], v[142:145], v[170:173], v[108:111]
	v_mfma_f32_16x16x32_bf16 v[100:103], v[154:157], v[170:173], v[100:103]
	v_mfma_f32_16x16x32_bf16 v[92:95], v[142:145], v[178:181], v[92:95]
	v_mfma_f32_16x16x32_bf16 v[84:87], v[154:157], v[178:181], v[84:87]
	v_mfma_f32_16x16x32_bf16 v[76:79], v[142:145], v[186:189], v[76:79]
	v_mfma_f32_16x16x32_bf16 v[68:71], v[154:157], v[186:189], v[68:71]
	s_setprio 0
	s_barrier
	s_add_i32 s22, 0, 0x1c000
	s_add_i32 s23, s42, s28
	v_add_u32_e32 v150, s22, v151
	v_lshl_add_u64 v[190:191], v[190:191], 0, s[80:81]
	s_mov_b32 m0, s23
	ds_read_b128 v[198:201], v150
	ds_read_b128 v[206:209], v150 offset:1024
	ds_read_b128 v[210:213], v150 offset:2048
	ds_read_b128 v[214:217], v150 offset:3072
	global_load_lds_dwordx4 v[190:191], off
	v_lshl_add_u64 v[190:191], v[202:203], 0, s[80:81]
	s_add_i32 m0, s23, 0x2000
	s_nop 0
	global_load_lds_dwordx4 v[190:191], off
	s_barrier
	s_waitcnt lgkmcnt(0)
	s_setprio 1
	s_waitcnt lgkmcnt(0)
	v_mfma_f32_16x16x32_bf16 v[120:123], v[198:201], v[158:161], v[120:123]
	v_mfma_f32_16x16x32_bf16 v[112:115], v[210:213], v[158:161], v[112:115]
	v_mfma_f32_16x16x32_bf16 v[104:107], v[198:201], v[166:169], v[104:107]
	v_mfma_f32_16x16x32_bf16 v[96:99], v[210:213], v[166:169], v[96:99]
	v_mfma_f32_16x16x32_bf16 v[88:91], v[198:201], v[174:177], v[88:91]
	v_mfma_f32_16x16x32_bf16 v[80:83], v[210:213], v[174:177], v[80:83]
	v_mfma_f32_16x16x32_bf16 v[72:75], v[198:201], v[182:185], v[72:75]
	v_mfma_f32_16x16x32_bf16 v[64:67], v[210:213], v[182:185], v[64:67]
	v_mfma_f32_16x16x32_bf16 v[120:123], v[206:209], v[162:165], v[120:123]
	v_mfma_f32_16x16x32_bf16 v[112:115], v[214:217], v[162:165], v[112:115]
	v_mfma_f32_16x16x32_bf16 v[104:107], v[206:209], v[170:173], v[104:107]
	v_mfma_f32_16x16x32_bf16 v[96:99], v[214:217], v[170:173], v[96:99]
	v_mfma_f32_16x16x32_bf16 v[88:91], v[206:209], v[178:181], v[88:91]
	v_mfma_f32_16x16x32_bf16 v[80:83], v[214:217], v[178:181], v[80:83]
	v_mfma_f32_16x16x32_bf16 v[72:75], v[206:209], v[186:189], v[72:75]
	v_mfma_f32_16x16x32_bf16 v[64:67], v[214:217], v[186:189], v[64:67]
	s_setprio 0
	s_mov_b32 m0, s34
	v_lshl_add_u64 v[190:191], v[204:205], 0, s[80:81]
	s_barrier
	ds_read_b128 v[158:161], v152 offset:49152
	ds_read_b128 v[162:165], v152 offset:50176
	ds_read_b128 v[166:169], v152 offset:51200
	ds_read_b128 v[170:173], v152 offset:52224
	ds_read_b128 v[174:177], v152 offset:53248
	ds_read_b128 v[178:181], v152 offset:54272
	ds_read_b128 v[182:185], v152 offset:55296
	ds_read_b128 v[186:189], v152 offset:56320
	global_load_lds_dwordx4 v[190:191], off
	v_lshl_add_u64 v[190:191], v[218:219], 0, s[80:81]
	s_mov_b32 m0, s35
	s_nop 0
	global_load_lds_dwordx4 v[190:191], off
	s_barrier
	s_waitcnt lgkmcnt(0)
	s_setprio 1
	s_waitcnt lgkmcnt(0)
	v_mfma_f32_16x16x32_bf16 v[60:63], v[138:141], v[158:161], v[60:63]
	v_mfma_f32_16x16x32_bf16 v[52:55], v[146:149], v[158:161], v[52:55]
	v_mfma_f32_16x16x32_bf16 v[44:47], v[138:141], v[166:169], v[44:47]
	v_mfma_f32_16x16x32_bf16 v[36:39], v[146:149], v[166:169], v[36:39]
	v_mfma_f32_16x16x32_bf16 v[28:31], v[138:141], v[174:177], v[28:31]
	v_mfma_f32_16x16x32_bf16 v[20:23], v[146:149], v[174:177], v[20:23]
	v_mfma_f32_16x16x32_bf16 v[12:15], v[138:141], v[182:185], v[12:15]
	v_mfma_f32_16x16x32_bf16 v[4:7], v[146:149], v[182:185], v[4:7]
	v_mfma_f32_16x16x32_bf16 v[60:63], v[142:145], v[162:165], v[60:63]
	v_mfma_f32_16x16x32_bf16 v[52:55], v[154:157], v[162:165], v[52:55]
	v_mfma_f32_16x16x32_bf16 v[44:47], v[142:145], v[170:173], v[44:47]
	v_mfma_f32_16x16x32_bf16 v[36:39], v[154:157], v[170:173], v[36:39]
	v_mfma_f32_16x16x32_bf16 v[28:31], v[142:145], v[178:181], v[28:31]
	v_mfma_f32_16x16x32_bf16 v[20:23], v[154:157], v[178:181], v[20:23]
	v_mfma_f32_16x16x32_bf16 v[12:15], v[142:145], v[186:189], v[12:15]
	v_mfma_f32_16x16x32_bf16 v[4:7], v[154:157], v[186:189], v[4:7]
	s_setprio 0
	s_barrier
	s_add_u32 s20, s20, 0x40080
	s_addc_u32 s21, s21, 0
	s_add_i32 s22, s22, s28
	v_lshl_add_u64 v[138:139], s[20:21], 0, v[192:193]
	s_mov_b32 m0, s22
	s_nop 0
	global_load_lds_dwordx4 v[138:139], off
	v_lshl_add_u64 v[138:139], s[20:21], 0, v[128:129]
	s_add_i32 m0, s22, 0x2000
	s_nop 0
	global_load_lds_dwordx4 v[138:139], off
	s_waitcnt vmcnt(6)
	s_barrier
	s_setprio 1
	v_mfma_f32_16x16x32_bf16 v[56:59], v[198:201], v[158:161], v[56:59]
	v_mfma_f32_16x16x32_bf16 v[48:51], v[210:213], v[158:161], v[48:51]
	v_mfma_f32_16x16x32_bf16 v[40:43], v[198:201], v[166:169], v[40:43]
	v_mfma_f32_16x16x32_bf16 v[32:35], v[210:213], v[166:169], v[32:35]
	v_mfma_f32_16x16x32_bf16 v[24:27], v[198:201], v[174:177], v[24:27]
	v_mfma_f32_16x16x32_bf16 v[16:19], v[210:213], v[174:177], v[16:19]
	v_mfma_f32_16x16x32_bf16 v[8:11], v[198:201], v[182:185], v[8:11]
	v_mfma_f32_16x16x32_bf16 v[0:3], v[210:213], v[182:185], v[0:3]
	v_mfma_f32_16x16x32_bf16 v[56:59], v[206:209], v[162:165], v[56:59]
	v_mfma_f32_16x16x32_bf16 v[48:51], v[214:217], v[162:165], v[48:51]
	v_mfma_f32_16x16x32_bf16 v[40:43], v[206:209], v[170:173], v[40:43]
	v_mfma_f32_16x16x32_bf16 v[32:35], v[214:217], v[170:173], v[32:35]
	v_mfma_f32_16x16x32_bf16 v[24:27], v[206:209], v[178:181], v[24:27]
	v_mfma_f32_16x16x32_bf16 v[16:19], v[214:217], v[178:181], v[16:19]
	v_mfma_f32_16x16x32_bf16 v[8:11], v[206:209], v[186:189], v[8:11]
	v_mfma_f32_16x16x32_bf16 v[0:3], v[214:217], v[186:189], v[0:3]
	s_setprio 0
	s_add_i32 s41, s41, 2
	s_add_u32 s39, s39, 0x100
	s_addc_u32 s40, s40, 0
	s_add_u32 s18, s18, 0x100
	s_addc_u32 s19, s19, 0
	s_cmp_gt_u32 s41, 13
	s_barrier
	s_cbranch_scc0 .LBB0_2804
	v_mov_b32_e32 v139, v252
	s_lshl_b32 s11, s16, 8
	v_readfirstlane_b32 s9, v139
	s_ashr_i32 s16, s9, 2
	s_andn2_b32 s16, s16, 63
	s_lshr_b32 s9, s9, 1
	s_add_i32 s16, s16, s11
	s_lshl_b32 s11, s37, 7
	s_and_b32 s9, s9, 0x60
	v_and_or_b32 v138, v139, 15, s16
	s_or_b32 s9, s9, s11
	v_lshrrev_b32_e32 v139, 1, v139
	v_and_or_b32 v148, v139, 24, s9
	v_ashrrev_i32_e32 v139, 31, v138
	v_lshl_add_u64 v[140:141], v[138:139], 2, s[6:7]
	v_or_b32_e32 v146, 16, v138
	v_ashrrev_i32_e32 v147, 31, v146
	v_lshl_add_u64 v[142:143], v[146:147], 2, s[6:7]
	v_or_b32_e32 v144, 32, v138
	v_ashrrev_i32_e32 v145, 31, v144
	v_lshl_add_u64 v[142:143], v[144:145], 2, s[6:7]
	v_or_b32_e32 v142, 48, v138
	v_ashrrev_i32_e32 v143, 31, v142
	v_lshl_add_u64 v[154:155], v[142:143], 2, s[6:7]
	v_pk_mul_f32 v[120:121], v[124:125], v[120:121]
	v_pk_mul_f32 v[122:123], v[126:127], v[122:123]
	v_pk_mul_f32 v[112:113], v[116:117], v[112:113]
	v_pk_mul_f32 v[114:115], v[118:119], v[114:115]
	v_ashrrev_i32_e32 v149, 31, v148
	s_movk_i32 s9, 0x1600
	v_pk_mul_f32 v[104:105], v[108:109], v[104:105]
	v_pk_mul_f32 v[106:107], v[110:111], v[106:107]
	v_pk_mul_f32 v[96:97], v[100:101], v[96:97]
	v_pk_mul_f32 v[98:99], v[102:103], v[98:99]
	v_pk_mul_f32 v[88:89], v[92:93], v[88:89]
	v_pk_mul_f32 v[90:91], v[94:95], v[90:91]
	v_pk_mul_f32 v[80:81], v[84:85], v[80:81]
	v_pk_mul_f32 v[82:83], v[86:87], v[82:83]
	v_pk_mul_f32 v[72:73], v[76:77], v[72:73]
	v_pk_mul_f32 v[74:75], v[78:79], v[74:75]
	v_pk_mul_f32 v[64:65], v[68:69], v[64:65]
	v_pk_mul_f32 v[66:67], v[70:71], v[66:67]
	v_pk_mul_f32 v[56:57], v[60:61], v[56:57]
	v_pk_mul_f32 v[58:59], v[62:63], v[58:59]
	v_pk_mul_f32 v[48:49], v[52:53], v[48:49]
	v_pk_mul_f32 v[50:51], v[54:55], v[50:51]
	v_pk_mul_f32 v[40:41], v[44:45], v[40:41]
	v_pk_mul_f32 v[42:43], v[46:47], v[42:43]
	v_pk_mul_f32 v[32:33], v[36:37], v[32:33]
	v_pk_mul_f32 v[34:35], v[38:39], v[34:35]
	v_pk_mul_f32 v[24:25], v[28:29], v[24:25]
	v_pk_mul_f32 v[26:27], v[30:31], v[26:27]
	v_pk_mul_f32 v[16:17], v[20:21], v[16:17]
	v_pk_mul_f32 v[18:19], v[22:23], v[18:19]
	v_pk_mul_f32 v[8:9], v[12:13], v[8:9]
	v_pk_mul_f32 v[10:11], v[14:15], v[10:11]
	v_pk_mul_f32 v[0:1], v[4:5], v[0:1]
	v_pk_mul_f32 v[2:3], v[6:7], v[2:3]
	s_mov_b32 s37, s10
	s_mov_b32 s16, s8
	s_mov_b64 s[20:21], s[12:13]
	v_fmamk_f32 v143, v231, 0x3a800000, v194
	v_cmp_gt_f32_e32 vcc, s2, v143
	v_mul_f32_e32 v150, 0x4b800000, v143
	s_nop 0
	v_cndmask_b32_e32 v143, v143, v150, vcc
	v_rsq_f32_e32 v143, v143
	s_nop 0
	v_mul_f32_e32 v150, 0x45800000, v143
	v_cndmask_b32_e32 v143, v143, v150, vcc
	v_mul_f32_e32 v154, 0xbfb8aa3b, v143
	v_pk_mul_f32 v[158:159], v[124:125], v[154:155] op_sel_hi:[1,0]
	v_mul_f32_e32 v150, v143, v143
	v_exp_f32_e32 v143, v158
	v_pk_mul_f32 v[156:157], v[126:127], v[154:155] op_sel_hi:[1,0]
	v_add_f32_e32 v143, 1.0, v143
	v_rcp_f32_e32 v158, v143
	v_exp_f32_e32 v143, v159
	s_nop 0
	v_add_f32_e32 v143, 1.0, v143
	v_rcp_f32_e32 v159, v143
	v_exp_f32_e32 v143, v156
	v_pk_mul_f32 v[124:125], v[150:151], v[158:159] op_sel_hi:[0,1]
	v_add_f32_e32 v143, 1.0, v143
	v_rcp_f32_e32 v156, v143
	v_exp_f32_e32 v143, v157
	v_pk_mul_f32 v[120:121], v[120:121], v[124:125]
	v_add_f32_e32 v143, 1.0, v143
	v_rcp_f32_e32 v157, v143
	v_cvt_pk_bf16_f32 v124, v121, s0
	v_cvt_pk_bf16_f32 v120, v120, s0
	v_pk_mul_f32 v[126:127], v[150:151], v[156:157] op_sel_hi:[0,1]
	v_pk_mul_f32 v[122:123], v[122:123], v[126:127]
	s_nop 0
	v_cvt_pk_bf16_f32 v121, v122, v123
	v_lshlrev_b32_e32 v122, 16, v124
	v_pk_mul_f32 v[124:125], v[116:117], v[154:155] op_sel_hi:[1,0]
	v_or_b32_sdwa v120, v122, v120 dst_sel:DWORD dst_unused:UNUSED_PAD src0_sel:DWORD src1_sel:WORD_0
	v_pk_mul_f32 v[122:123], v[118:119], v[154:155] op_sel_hi:[1,0]
	v_exp_f32_e32 v124, v124
	v_exp_f32_e32 v125, v125
	v_exp_f32_e32 v122, v122
	v_exp_f32_e32 v123, v123
	v_add_f32_e32 v124, 1.0, v124
	v_add_f32_e32 v125, 1.0, v125
	v_rcp_f32_e32 v124, v124
	v_rcp_f32_e32 v125, v125
	v_add_f32_e32 v122, 1.0, v122
	v_add_f32_e32 v123, 1.0, v123
	v_rcp_f32_e32 v122, v122
	v_rcp_f32_e32 v123, v123
	v_pk_mul_f32 v[116:117], v[150:151], v[124:125] op_sel_hi:[0,1]
	v_pk_mul_f32 v[112:113], v[112:113], v[116:117]
	v_pk_mul_f32 v[118:119], v[150:151], v[122:123] op_sel_hi:[0,1]
	v_pk_mul_f32 v[114:115], v[114:115], v[118:119]
	v_cvt_pk_bf16_f32 v122, v112, v113
	v_mov_b64_e32 v[112:113], s[4:5]
	v_cvt_pk_bf16_f32 v123, v114, v115
	v_mad_i64_i32 v[116:117], s[18:19], v138, s9, v[112:113]
	v_lshlrev_b64 v[114:115], 1, v[148:149]
	v_lshl_add_u64 v[116:117], v[116:117], 0, v[114:115]
	global_store_dwordx4 v[116:117], v[120:123], off
	v_fmamk_f32 v116, v232, 0x3a800000, v194
	v_cmp_gt_f32_e32 vcc, s2, v116
	v_mul_f32_e32 v117, 0x4b800000, v116
	s_nop 0
	v_cndmask_b32_e32 v116, v116, v117, vcc
	v_rsq_f32_e32 v116, v116
	s_nop 0
	v_mul_f32_e32 v117, 0x45800000, v116
	v_cndmask_b32_e32 v116, v116, v117, vcc
	v_mul_f32_e32 v118, 0xbfb8aa3b, v116
	v_pk_mul_f32 v[122:123], v[108:109], v[118:119] op_sel_hi:[1,0]
	v_pk_mul_f32 v[120:121], v[110:111], v[118:119] op_sel_hi:[1,0]
	v_exp_f32_e32 v117, v122
	v_mul_f32_e32 v116, v116, v116
	v_add_f32_e32 v117, 1.0, v117
	v_rcp_f32_e32 v122, v117
	v_exp_f32_e32 v117, v123
	s_nop 0
	v_add_f32_e32 v117, 1.0, v117
	v_rcp_f32_e32 v123, v117
	v_exp_f32_e32 v117, v120
	s_nop 0
	v_add_f32_e32 v117, 1.0, v117
	v_rcp_f32_e32 v120, v117
	v_exp_f32_e32 v117, v121
	s_nop 0
	v_add_f32_e32 v117, 1.0, v117
	v_rcp_f32_e32 v121, v117
	v_pk_mul_f32 v[108:109], v[116:117], v[122:123] op_sel_hi:[0,1]
	v_pk_mul_f32 v[104:105], v[104:105], v[108:109]
	v_pk_mul_f32 v[110:111], v[116:117], v[120:121] op_sel_hi:[0,1]
	v_pk_mul_f32 v[106:107], v[106:107], v[110:111]
	v_cvt_pk_bf16_f32 v108, v105, s0
	v_cvt_pk_bf16_f32 v104, v104, s0
	v_cvt_pk_bf16_f32 v105, v106, v107
	v_lshlrev_b32_e32 v106, 16, v108
	v_pk_mul_f32 v[108:109], v[100:101], v[118:119] op_sel_hi:[1,0]
	v_or_b32_sdwa v104, v106, v104 dst_sel:DWORD dst_unused:UNUSED_PAD src0_sel:DWORD src1_sel:WORD_0
	v_pk_mul_f32 v[106:107], v[102:103], v[118:119] op_sel_hi:[1,0]
	v_exp_f32_e32 v108, v108
	v_exp_f32_e32 v109, v109
	v_exp_f32_e32 v106, v106
	v_exp_f32_e32 v107, v107
	v_add_f32_e32 v108, 1.0, v108
	v_add_f32_e32 v109, 1.0, v109
	v_rcp_f32_e32 v108, v108
	v_rcp_f32_e32 v109, v109
	v_add_f32_e32 v106, 1.0, v106
	v_add_f32_e32 v107, 1.0, v107
	v_rcp_f32_e32 v106, v106
	v_rcp_f32_e32 v107, v107
	v_pk_mul_f32 v[100:101], v[116:117], v[108:109] op_sel_hi:[0,1]
	v_pk_mul_f32 v[96:97], v[96:97], v[100:101]
	v_pk_mul_f32 v[102:103], v[116:117], v[106:107] op_sel_hi:[0,1]
	v_pk_mul_f32 v[98:99], v[98:99], v[102:103]
	v_cvt_pk_bf16_f32 v106, v96, v97
	v_mad_i64_i32 v[96:97], s[18:19], v146, s9, v[112:113]
	v_cvt_pk_bf16_f32 v107, v98, v99
	v_lshl_add_u64 v[96:97], v[96:97], 0, v[114:115]
	global_store_dwordx4 v[96:97], v[104:107], off
	v_fmamk_f32 v96, v233, 0x3a800000, v194
	v_cmp_gt_f32_e32 vcc, s2, v96
	v_mul_f32_e32 v97, 0x4b800000, v96
	s_nop 0
	v_cndmask_b32_e32 v96, v96, v97, vcc
	v_rsq_f32_e32 v96, v96
	s_nop 0
	v_mul_f32_e32 v97, 0x45800000, v96
	v_cndmask_b32_e32 v97, v96, v97, vcc
	v_mul_f32_e32 v96, 0xbfb8aa3b, v97
	v_pk_mul_f32 v[102:103], v[92:93], v[96:97] op_sel_hi:[1,0]
	v_mul_f32_e32 v98, v97, v97
	v_pk_mul_f32 v[100:101], v[94:95], v[96:97] op_sel_hi:[1,0]
	v_exp_f32_e32 v97, v102
	s_nop 0
	v_add_f32_e32 v97, 1.0, v97
	v_rcp_f32_e32 v102, v97
	v_exp_f32_e32 v97, v103
	s_nop 0
	v_add_f32_e32 v97, 1.0, v97
	v_rcp_f32_e32 v103, v97
	v_exp_f32_e32 v97, v100
	v_pk_mul_f32 v[92:93], v[98:99], v[102:103] op_sel_hi:[0,1]
	v_add_f32_e32 v97, 1.0, v97
	v_rcp_f32_e32 v100, v97
	v_exp_f32_e32 v97, v101
	v_pk_mul_f32 v[88:89], v[88:89], v[92:93]
	v_add_f32_e32 v97, 1.0, v97
	v_rcp_f32_e32 v101, v97
	v_cvt_pk_bf16_f32 v92, v89, s0
	v_cvt_pk_bf16_f32 v88, v88, s0
	v_pk_mul_f32 v[94:95], v[98:99], v[100:101] op_sel_hi:[0,1]
	v_pk_mul_f32 v[90:91], v[90:91], v[94:95]
	s_nop 0
	v_cvt_pk_bf16_f32 v89, v90, v91
	v_lshlrev_b32_e32 v90, 16, v92
	v_pk_mul_f32 v[92:93], v[84:85], v[96:97] op_sel_hi:[1,0]
	v_or_b32_sdwa v88, v90, v88 dst_sel:DWORD dst_unused:UNUSED_PAD src0_sel:DWORD src1_sel:WORD_0
	v_pk_mul_f32 v[90:91], v[86:87], v[96:97] op_sel_hi:[1,0]
	v_exp_f32_e32 v92, v92
	v_exp_f32_e32 v93, v93
	v_exp_f32_e32 v90, v90
	v_exp_f32_e32 v91, v91
	v_add_f32_e32 v92, 1.0, v92
	v_add_f32_e32 v93, 1.0, v93
	v_rcp_f32_e32 v92, v92
	v_rcp_f32_e32 v93, v93
	v_add_f32_e32 v90, 1.0, v90
	v_add_f32_e32 v91, 1.0, v91
	v_rcp_f32_e32 v90, v90
	v_rcp_f32_e32 v91, v91
	v_pk_mul_f32 v[84:85], v[98:99], v[92:93] op_sel_hi:[0,1]
	v_pk_mul_f32 v[80:81], v[80:81], v[84:85]
	v_pk_mul_f32 v[86:87], v[98:99], v[90:91] op_sel_hi:[0,1]
	v_pk_mul_f32 v[82:83], v[82:83], v[86:87]
	v_cvt_pk_bf16_f32 v90, v80, v81
	v_mad_i64_i32 v[80:81], s[18:19], v144, s9, v[112:113]
	v_cvt_pk_bf16_f32 v91, v82, v83
	v_lshl_add_u64 v[80:81], v[80:81], 0, v[114:115]
	global_store_dwordx4 v[80:81], v[88:91], off
	v_fmamk_f32 v80, v234, 0x3a800000, v194
	v_cmp_gt_f32_e32 vcc, s2, v80
	v_mul_f32_e32 v81, 0x4b800000, v80
	s_nop 0
	v_cndmask_b32_e32 v80, v80, v81, vcc
	v_rsq_f32_e32 v80, v80
	s_nop 0
	v_mul_f32_e32 v81, 0x45800000, v80
	v_cndmask_b32_e32 v81, v80, v81, vcc
	v_mul_f32_e32 v80, 0xbfb8aa3b, v81
	v_pk_mul_f32 v[86:87], v[76:77], v[80:81] op_sel_hi:[1,0]
	v_mul_f32_e32 v82, v81, v81
	v_pk_mul_f32 v[84:85], v[78:79], v[80:81] op_sel_hi:[1,0]
	v_exp_f32_e32 v81, v86
	s_nop 0
	v_add_f32_e32 v81, 1.0, v81
	v_rcp_f32_e32 v86, v81
	v_exp_f32_e32 v81, v87
	s_nop 0
	v_add_f32_e32 v81, 1.0, v81
	v_rcp_f32_e32 v87, v81
	v_exp_f32_e32 v81, v84
	v_pk_mul_f32 v[76:77], v[82:83], v[86:87] op_sel_hi:[0,1]
	v_add_f32_e32 v81, 1.0, v81
	v_rcp_f32_e32 v84, v81
	v_exp_f32_e32 v81, v85
	v_pk_mul_f32 v[72:73], v[72:73], v[76:77]
	v_add_f32_e32 v81, 1.0, v81
	v_rcp_f32_e32 v85, v81
	v_cvt_pk_bf16_f32 v76, v73, s0
	v_cvt_pk_bf16_f32 v72, v72, s0
	v_pk_mul_f32 v[78:79], v[82:83], v[84:85] op_sel_hi:[0,1]
	v_pk_mul_f32 v[74:75], v[74:75], v[78:79]
	s_nop 0
	v_cvt_pk_bf16_f32 v73, v74, v75
	v_lshlrev_b32_e32 v74, 16, v76
	v_pk_mul_f32 v[76:77], v[68:69], v[80:81] op_sel_hi:[1,0]
	v_or_b32_sdwa v72, v74, v72 dst_sel:DWORD dst_unused:UNUSED_PAD src0_sel:DWORD src1_sel:WORD_0
	v_pk_mul_f32 v[74:75], v[70:71], v[80:81] op_sel_hi:[1,0]
	v_exp_f32_e32 v76, v76
	v_exp_f32_e32 v77, v77
	v_exp_f32_e32 v74, v74
	v_exp_f32_e32 v75, v75
	v_add_f32_e32 v76, 1.0, v76
	v_add_f32_e32 v77, 1.0, v77
	v_rcp_f32_e32 v76, v76
	v_rcp_f32_e32 v77, v77
	v_add_f32_e32 v74, 1.0, v74
	v_add_f32_e32 v75, 1.0, v75
	v_rcp_f32_e32 v74, v74
	v_rcp_f32_e32 v75, v75
	v_pk_mul_f32 v[68:69], v[82:83], v[76:77] op_sel_hi:[0,1]
	v_pk_mul_f32 v[64:65], v[64:65], v[68:69]
	v_add_u32_e32 v69, 0x90, v138
	v_pk_mul_f32 v[70:71], v[82:83], v[74:75] op_sel_hi:[0,1]
	v_pk_mul_f32 v[66:67], v[66:67], v[70:71]
	v_cvt_pk_bf16_f32 v74, v64, v65
	v_mad_i64_i32 v[64:65], s[18:19], v142, s9, v[112:113]
	v_cvt_pk_bf16_f32 v75, v66, v67
	v_lshl_add_u64 v[64:65], v[64:65], 0, v[114:115]
	global_store_dwordx4 v[64:65], v[72:75], off
	v_add_u32_e32 v67, 0x80, v138
	v_add_u32_e32 v66, 0xa0, v138
	v_add_u32_e32 v64, 0xb0, v138
	v_fmamk_f32 v68, v235, 0x3a800000, v194
	v_cmp_gt_f32_e32 vcc, s2, v68
	v_mul_f32_e32 v70, 0x4b800000, v68
	s_nop 0
	v_cndmask_b32_e32 v68, v68, v70, vcc
	v_rsq_f32_e32 v68, v68
	s_nop 0
	v_mul_f32_e32 v70, 0x45800000, v68
	v_cndmask_b32_e32 v70, v68, v70, vcc
	v_mul_f32_e32 v68, 0xbfb8aa3b, v70
	v_pk_mul_f32 v[74:75], v[60:61], v[68:69] op_sel_hi:[1,0]
	v_pk_mul_f32 v[72:73], v[62:63], v[68:69] op_sel_hi:[1,0]
	v_exp_f32_e32 v74, v74
	v_exp_f32_e32 v75, v75
	v_exp_f32_e32 v72, v72
	v_exp_f32_e32 v73, v73
	v_add_f32_e32 v74, 1.0, v74
	v_add_f32_e32 v75, 1.0, v75
	v_rcp_f32_e32 v74, v74
	v_rcp_f32_e32 v75, v75
	v_add_f32_e32 v72, 1.0, v72
	v_add_f32_e32 v73, 1.0, v73
	v_rcp_f32_e32 v72, v72
	v_rcp_f32_e32 v73, v73
	v_mul_f32_e32 v70, v70, v70
	v_pk_mul_f32 v[60:61], v[70:71], v[74:75] op_sel_hi:[0,1]
	v_pk_mul_f32 v[56:57], v[56:57], v[60:61]
	v_pk_mul_f32 v[62:63], v[70:71], v[72:73] op_sel_hi:[0,1]
	v_pk_mul_f32 v[58:59], v[58:59], v[62:63]
	v_cvt_pk_bf16_f32 v60, v57, s0
	v_cvt_pk_bf16_f32 v56, v56, s0
	v_cvt_pk_bf16_f32 v57, v58, v59
	v_lshlrev_b32_e32 v58, 16, v60
	v_pk_mul_f32 v[60:61], v[52:53], v[68:69] op_sel_hi:[1,0]
	v_or_b32_sdwa v56, v58, v56 dst_sel:DWORD dst_unused:UNUSED_PAD src0_sel:DWORD src1_sel:WORD_0
	v_pk_mul_f32 v[58:59], v[54:55], v[68:69] op_sel_hi:[1,0]
	v_exp_f32_e32 v60, v60
	v_exp_f32_e32 v61, v61
	v_exp_f32_e32 v58, v58
	v_exp_f32_e32 v59, v59
	v_add_f32_e32 v60, 1.0, v60
	v_add_f32_e32 v61, 1.0, v61
	v_rcp_f32_e32 v60, v60
	v_rcp_f32_e32 v61, v61
	v_add_f32_e32 v58, 1.0, v58
	v_add_f32_e32 v59, 1.0, v59
	v_rcp_f32_e32 v58, v58
	v_rcp_f32_e32 v59, v59
	v_pk_mul_f32 v[52:53], v[70:71], v[60:61] op_sel_hi:[0,1]
	v_pk_mul_f32 v[48:49], v[48:49], v[52:53]
	v_pk_mul_f32 v[54:55], v[70:71], v[58:59] op_sel_hi:[0,1]
	v_pk_mul_f32 v[50:51], v[50:51], v[54:55]
	v_cvt_pk_bf16_f32 v58, v48, v49
	v_mad_i64_i32 v[48:49], s[18:19], v67, s9, v[112:113]
	v_cvt_pk_bf16_f32 v59, v50, v51
	v_lshl_add_u64 v[48:49], v[48:49], 0, v[114:115]
	global_store_dwordx4 v[48:49], v[56:59], off
	v_fmamk_f32 v48, v236, 0x3a800000, v194
	v_cmp_gt_f32_e32 vcc, s2, v48
	v_mul_f32_e32 v49, 0x4b800000, v48
	s_nop 0
	v_cndmask_b32_e32 v48, v48, v49, vcc
	v_rsq_f32_e32 v48, v48
	s_nop 0
	v_mul_f32_e32 v49, 0x45800000, v48
	v_cndmask_b32_e32 v49, v48, v49, vcc
	v_mul_f32_e32 v48, 0xbfb8aa3b, v49
	v_pk_mul_f32 v[54:55], v[44:45], v[48:49] op_sel_hi:[1,0]
	v_mul_f32_e32 v50, v49, v49
	v_pk_mul_f32 v[52:53], v[46:47], v[48:49] op_sel_hi:[1,0]
	v_exp_f32_e32 v49, v54
	s_nop 0
	v_add_f32_e32 v49, 1.0, v49
	v_rcp_f32_e32 v54, v49
	v_exp_f32_e32 v49, v55
	s_nop 0
	v_add_f32_e32 v49, 1.0, v49
	v_rcp_f32_e32 v55, v49
	v_exp_f32_e32 v49, v52
	v_pk_mul_f32 v[44:45], v[50:51], v[54:55] op_sel_hi:[0,1]
	v_add_f32_e32 v49, 1.0, v49
	v_rcp_f32_e32 v52, v49
	v_exp_f32_e32 v49, v53
	v_pk_mul_f32 v[40:41], v[40:41], v[44:45]
	v_add_f32_e32 v49, 1.0, v49
	v_rcp_f32_e32 v53, v49
	v_cvt_pk_bf16_f32 v44, v41, s0
	v_cvt_pk_bf16_f32 v40, v40, s0
	v_pk_mul_f32 v[46:47], v[50:51], v[52:53] op_sel_hi:[0,1]
	v_pk_mul_f32 v[42:43], v[42:43], v[46:47]
	s_nop 0
	v_cvt_pk_bf16_f32 v41, v42, v43
	v_lshlrev_b32_e32 v42, 16, v44
	v_pk_mul_f32 v[44:45], v[36:37], v[48:49] op_sel_hi:[1,0]
	v_or_b32_sdwa v40, v42, v40 dst_sel:DWORD dst_unused:UNUSED_PAD src0_sel:DWORD src1_sel:WORD_0
	v_pk_mul_f32 v[42:43], v[38:39], v[48:49] op_sel_hi:[1,0]
	v_exp_f32_e32 v44, v44
	v_exp_f32_e32 v45, v45
	v_exp_f32_e32 v42, v42
	v_exp_f32_e32 v43, v43
	v_add_f32_e32 v44, 1.0, v44
	v_add_f32_e32 v45, 1.0, v45
	v_rcp_f32_e32 v44, v44
	v_rcp_f32_e32 v45, v45
	v_add_f32_e32 v42, 1.0, v42
	v_add_f32_e32 v43, 1.0, v43
	v_rcp_f32_e32 v42, v42
	v_rcp_f32_e32 v43, v43
	v_pk_mul_f32 v[36:37], v[50:51], v[44:45] op_sel_hi:[0,1]
	v_pk_mul_f32 v[32:33], v[32:33], v[36:37]
	v_pk_mul_f32 v[38:39], v[50:51], v[42:43] op_sel_hi:[0,1]
	v_pk_mul_f32 v[34:35], v[34:35], v[38:39]
	v_cvt_pk_bf16_f32 v42, v32, v33
	v_mad_i64_i32 v[32:33], s[18:19], v69, s9, v[112:113]
	v_cvt_pk_bf16_f32 v43, v34, v35
	v_lshl_add_u64 v[32:33], v[32:33], 0, v[114:115]
	global_store_dwordx4 v[32:33], v[40:43], off
	v_fmamk_f32 v32, v237, 0x3a800000, v194
	v_cmp_gt_f32_e32 vcc, s2, v32
	v_mul_f32_e32 v33, 0x4b800000, v32
	s_nop 0
	v_cndmask_b32_e32 v32, v32, v33, vcc
	v_rsq_f32_e32 v32, v32
	s_nop 0
	v_mul_f32_e32 v33, 0x45800000, v32
	v_cndmask_b32_e32 v33, v32, v33, vcc
	v_mul_f32_e32 v32, 0xbfb8aa3b, v33
	v_pk_mul_f32 v[38:39], v[28:29], v[32:33] op_sel_hi:[1,0]
	v_mul_f32_e32 v34, v33, v33
	v_pk_mul_f32 v[36:37], v[30:31], v[32:33] op_sel_hi:[1,0]
	v_exp_f32_e32 v33, v38
	s_nop 0
	v_add_f32_e32 v33, 1.0, v33
	v_rcp_f32_e32 v38, v33
	v_exp_f32_e32 v33, v39
	s_nop 0
	v_add_f32_e32 v33, 1.0, v33
	v_rcp_f32_e32 v39, v33
	v_exp_f32_e32 v33, v36
	v_pk_mul_f32 v[28:29], v[34:35], v[38:39] op_sel_hi:[0,1]
	v_add_f32_e32 v33, 1.0, v33
	v_rcp_f32_e32 v36, v33
	v_exp_f32_e32 v33, v37
	v_pk_mul_f32 v[24:25], v[24:25], v[28:29]
	v_add_f32_e32 v33, 1.0, v33
	v_rcp_f32_e32 v37, v33
	v_cvt_pk_bf16_f32 v28, v25, s0
	v_cvt_pk_bf16_f32 v24, v24, s0
	v_pk_mul_f32 v[30:31], v[34:35], v[36:37] op_sel_hi:[0,1]
	v_pk_mul_f32 v[26:27], v[26:27], v[30:31]
	s_nop 0
	v_cvt_pk_bf16_f32 v25, v26, v27
	v_lshlrev_b32_e32 v26, 16, v28
	v_pk_mul_f32 v[28:29], v[20:21], v[32:33] op_sel_hi:[1,0]
	v_or_b32_sdwa v24, v26, v24 dst_sel:DWORD dst_unused:UNUSED_PAD src0_sel:DWORD src1_sel:WORD_0
	v_pk_mul_f32 v[26:27], v[22:23], v[32:33] op_sel_hi:[1,0]
	v_exp_f32_e32 v28, v28
	v_exp_f32_e32 v29, v29
	v_exp_f32_e32 v26, v26
	v_exp_f32_e32 v27, v27
	v_add_f32_e32 v28, 1.0, v28
	v_add_f32_e32 v29, 1.0, v29
	v_rcp_f32_e32 v28, v28
	v_rcp_f32_e32 v29, v29
	v_add_f32_e32 v26, 1.0, v26
	v_add_f32_e32 v27, 1.0, v27
	v_rcp_f32_e32 v26, v26
	v_rcp_f32_e32 v27, v27
	v_pk_mul_f32 v[20:21], v[34:35], v[28:29] op_sel_hi:[0,1]
	v_pk_mul_f32 v[16:17], v[16:17], v[20:21]
	v_pk_mul_f32 v[22:23], v[34:35], v[26:27] op_sel_hi:[0,1]
	v_pk_mul_f32 v[18:19], v[18:19], v[22:23]
	v_cvt_pk_bf16_f32 v26, v16, v17
	v_mad_i64_i32 v[16:17], s[18:19], v66, s9, v[112:113]
	v_cvt_pk_bf16_f32 v27, v18, v19
	v_lshl_add_u64 v[16:17], v[16:17], 0, v[114:115]
	global_store_dwordx4 v[16:17], v[24:27], off
	v_fmamk_f32 v16, v238, 0x3a800000, v194
	v_cmp_gt_f32_e32 vcc, s2, v16
	v_mul_f32_e32 v17, 0x4b800000, v16
	s_nop 0
	v_cndmask_b32_e32 v16, v16, v17, vcc
	v_rsq_f32_e32 v16, v16
	s_nop 0
	v_mul_f32_e32 v17, 0x45800000, v16
	v_cndmask_b32_e32 v17, v16, v17, vcc
	v_mul_f32_e32 v16, 0xbfb8aa3b, v17
	v_pk_mul_f32 v[22:23], v[12:13], v[16:17] op_sel_hi:[1,0]
	v_mul_f32_e32 v18, v17, v17
	v_pk_mul_f32 v[20:21], v[14:15], v[16:17] op_sel_hi:[1,0]
	v_exp_f32_e32 v17, v22
	s_and_b64 vcc, exec, s[0:1]
	v_add_f32_e32 v17, 1.0, v17
	v_rcp_f32_e32 v22, v17
	v_exp_f32_e32 v17, v23
	s_nop 0
	v_add_f32_e32 v17, 1.0, v17
	v_rcp_f32_e32 v23, v17
	v_exp_f32_e32 v17, v20
	v_pk_mul_f32 v[12:13], v[18:19], v[22:23] op_sel_hi:[0,1]
	v_add_f32_e32 v17, 1.0, v17
	v_rcp_f32_e32 v20, v17
	v_exp_f32_e32 v17, v21
	v_pk_mul_f32 v[8:9], v[8:9], v[12:13]
	v_add_f32_e32 v17, 1.0, v17
	v_rcp_f32_e32 v21, v17
	v_cvt_pk_bf16_f32 v12, v9, s0
	v_cvt_pk_bf16_f32 v8, v8, s0
	v_pk_mul_f32 v[14:15], v[18:19], v[20:21] op_sel_hi:[0,1]
	v_pk_mul_f32 v[10:11], v[10:11], v[14:15]
	s_nop 0
	v_cvt_pk_bf16_f32 v9, v10, v11
	v_lshlrev_b32_e32 v10, 16, v12
	v_pk_mul_f32 v[12:13], v[4:5], v[16:17] op_sel_hi:[1,0]
	v_or_b32_sdwa v8, v10, v8 dst_sel:DWORD dst_unused:UNUSED_PAD src0_sel:DWORD src1_sel:WORD_0
	v_pk_mul_f32 v[10:11], v[6:7], v[16:17] op_sel_hi:[1,0]
	v_exp_f32_e32 v12, v12
	v_exp_f32_e32 v13, v13
	v_exp_f32_e32 v10, v10
	v_exp_f32_e32 v11, v11
	v_add_f32_e32 v12, 1.0, v12
	v_add_f32_e32 v13, 1.0, v13
	v_rcp_f32_e32 v12, v12
	v_rcp_f32_e32 v13, v13
	v_add_f32_e32 v10, 1.0, v10
	v_add_f32_e32 v11, 1.0, v11
	v_rcp_f32_e32 v10, v10
	v_rcp_f32_e32 v11, v11
	v_pk_mul_f32 v[4:5], v[18:19], v[12:13] op_sel_hi:[0,1]
	v_pk_mul_f32 v[0:1], v[0:1], v[4:5]
	v_pk_mul_f32 v[6:7], v[18:19], v[10:11] op_sel_hi:[0,1]
	v_pk_mul_f32 v[2:3], v[2:3], v[6:7]
	v_cvt_pk_bf16_f32 v10, v0, v1
	v_mad_i64_i32 v[0:1], s[18:19], v64, s9, v[112:113]
	v_cvt_pk_bf16_f32 v11, v2, v3
	v_lshl_add_u64 v[0:1], v[0:1], 0, v[114:115]
	s_mov_b64 s[18:19], s[14:15]
	global_store_dwordx4 v[0:1], v[8:11], off
	s_cbranch_vccz .LBB0_2801
	s_waitcnt vmcnt(0)
	s_cmpk_gt_u32 s25, 0xff
	s_cbranch_scc1 .LBB0_2808
	s_barrier

.LBB0_3618:
	s_add_u32 s20, s18, 0x100
	s_addc_u32 s21, s19, 0
	s_add_i32 s45, 0, 0x10000
	v_add_u32_e32 v140, s45, v196
	ds_read_b128 v[128:131], v140
	ds_read_b128 v[132:135], v140 offset:1024
	ds_read_b128 v[136:139], v140 offset:2048
	ds_read_b128 v[140:143], v140 offset:3072
	s_cmp_eq_u32 s44, 40
	s_cselect_b32 s25, s5, s21
	s_cselect_b32 s24, s4, s20
	s_cselect_b32 s23, s7, s43
	s_cselect_b32 s22, s6, s33
	v_lshl_add_u64 v[176:177], s[18:19], 0, v[214:215]
	s_add_i32 m0, s30, 0xc000
	ds_read_b128 v[144:147], v198
	ds_read_b128 v[148:151], v198 offset:1024
	ds_read_b128 v[152:155], v198 offset:2048
	ds_read_b128 v[156:159], v198 offset:3072
	ds_read_b128 v[160:163], v198 offset:4096
	ds_read_b128 v[164:167], v198 offset:5120
	ds_read_b128 v[168:171], v198 offset:6144
	ds_read_b128 v[172:175], v198 offset:7168
	global_load_lds_dwordx4 v[176:177], off
	v_lshl_add_u64 v[176:177], s[18:19], 0, v[212:213]
	s_add_i32 m0, s30, 0xe000
	s_nop 0
	global_load_lds_dwordx4 v[176:177], off
	s_waitcnt lgkmcnt(8)
	s_barrier
	s_waitcnt lgkmcnt(0)
	s_setprio 1
	s_waitcnt lgkmcnt(0)
	v_mfma_f32_16x16x32_bf16 v[124:127], v[128:131], v[144:147], v[124:127]
	v_mfma_f32_16x16x32_bf16 v[120:123], v[136:139], v[144:147], v[120:123]
	v_mfma_f32_16x16x32_bf16 v[108:111], v[128:131], v[152:155], v[108:111]
	v_mfma_f32_16x16x32_bf16 v[104:107], v[136:139], v[152:155], v[104:107]
	v_mfma_f32_16x16x32_bf16 v[92:95], v[128:131], v[160:163], v[92:95]
	v_mfma_f32_16x16x32_bf16 v[88:91], v[136:139], v[160:163], v[88:91]
	v_mfma_f32_16x16x32_bf16 v[76:79], v[128:131], v[168:171], v[76:79]
	v_mfma_f32_16x16x32_bf16 v[72:75], v[136:139], v[168:171], v[72:75]
	v_mfma_f32_16x16x32_bf16 v[124:127], v[132:135], v[148:151], v[124:127]
	v_mfma_f32_16x16x32_bf16 v[120:123], v[140:143], v[148:151], v[120:123]
	v_mfma_f32_16x16x32_bf16 v[108:111], v[132:135], v[156:159], v[108:111]
	v_mfma_f32_16x16x32_bf16 v[104:107], v[140:143], v[156:159], v[104:107]
	v_mfma_f32_16x16x32_bf16 v[92:95], v[132:135], v[164:167], v[92:95]
	v_mfma_f32_16x16x32_bf16 v[88:91], v[140:143], v[164:167], v[88:91]
	v_mfma_f32_16x16x32_bf16 v[76:79], v[132:135], v[172:175], v[76:79]
	v_mfma_f32_16x16x32_bf16 v[72:75], v[140:143], v[172:175], v[72:75]
	s_setprio 0
	s_barrier
	s_add_i32 s46, 0, 0x14000
	s_add_i32 s18, s45, s29
	v_add_u32_e32 v188, s46, v196
	v_lshl_add_u64 v[200:201], s[22:23], 0, v[192:193]
	s_mov_b32 m0, s18
	ds_read_b128 v[176:179], v188
	ds_read_b128 v[180:183], v188 offset:1024
	ds_read_b128 v[184:187], v188 offset:2048
	ds_read_b128 v[188:191], v188 offset:3072
	global_load_lds_dwordx4 v[200:201], off
	v_lshl_add_u64 v[202:203], s[22:23], 0, v[210:211]
	s_add_i32 m0, s18, 0x2000
	s_nop 0
	global_load_lds_dwordx4 v[202:203], off
	s_barrier
	s_waitcnt lgkmcnt(0)
	s_setprio 1
	s_waitcnt lgkmcnt(0)
	v_mfma_f32_16x16x32_bf16 v[116:119], v[176:179], v[144:147], v[116:119]
	v_mfma_f32_16x16x32_bf16 v[112:115], v[184:187], v[144:147], v[112:115]
	v_mfma_f32_16x16x32_bf16 v[100:103], v[176:179], v[152:155], v[100:103]
	v_mfma_f32_16x16x32_bf16 v[96:99], v[184:187], v[152:155], v[96:99]
	v_mfma_f32_16x16x32_bf16 v[84:87], v[176:179], v[160:163], v[84:87]
	v_mfma_f32_16x16x32_bf16 v[80:83], v[184:187], v[160:163], v[80:83]
	v_mfma_f32_16x16x32_bf16 v[68:71], v[176:179], v[168:171], v[68:71]
	v_mfma_f32_16x16x32_bf16 v[64:67], v[184:187], v[168:171], v[64:67]
	v_mfma_f32_16x16x32_bf16 v[116:119], v[180:183], v[148:151], v[116:119]
	v_mfma_f32_16x16x32_bf16 v[112:115], v[188:191], v[148:151], v[112:115]
	v_mfma_f32_16x16x32_bf16 v[100:103], v[180:183], v[156:159], v[100:103]
	v_mfma_f32_16x16x32_bf16 v[96:99], v[188:191], v[156:159], v[96:99]
	v_mfma_f32_16x16x32_bf16 v[84:87], v[180:183], v[164:167], v[84:87]
	v_mfma_f32_16x16x32_bf16 v[80:83], v[188:191], v[164:167], v[80:83]
	v_mfma_f32_16x16x32_bf16 v[68:71], v[180:183], v[172:175], v[68:71]
	v_mfma_f32_16x16x32_bf16 v[64:67], v[188:191], v[172:175], v[64:67]
	s_setprio 0
	s_mov_b32 m0, s30
	v_lshl_add_u64 v[204:205], s[24:25], 0, v[206:207]
	s_barrier
	ds_read_b128 v[144:147], v198 offset:16384
	ds_read_b128 v[148:151], v198 offset:17408
	ds_read_b128 v[152:155], v198 offset:18432
	ds_read_b128 v[156:159], v198 offset:19456
	ds_read_b128 v[160:163], v198 offset:20480
	ds_read_b128 v[164:167], v198 offset:21504
	ds_read_b128 v[168:171], v198 offset:22528
	ds_read_b128 v[172:175], v198 offset:23552
	global_load_lds_dwordx4 v[204:205], off
	v_lshl_add_u64 v[216:217], s[24:25], 0, v[208:209]
	s_mov_b32 m0, s31
	s_nop 0
	global_load_lds_dwordx4 v[216:217], off
	s_barrier
	s_waitcnt lgkmcnt(0)
	s_setprio 1
	s_waitcnt lgkmcnt(0)
	v_mfma_f32_16x16x32_bf16 v[60:63], v[128:131], v[144:147], v[60:63]
	v_mfma_f32_16x16x32_bf16 v[56:59], v[136:139], v[144:147], v[56:59]
	v_mfma_f32_16x16x32_bf16 v[44:47], v[128:131], v[152:155], v[44:47]
	v_mfma_f32_16x16x32_bf16 v[40:43], v[136:139], v[152:155], v[40:43]
	v_mfma_f32_16x16x32_bf16 v[28:31], v[128:131], v[160:163], v[28:31]
	v_mfma_f32_16x16x32_bf16 v[24:27], v[136:139], v[160:163], v[24:27]
	v_mfma_f32_16x16x32_bf16 v[12:15], v[128:131], v[168:171], v[12:15]
	v_mfma_f32_16x16x32_bf16 v[8:11], v[136:139], v[168:171], v[8:11]
	v_mfma_f32_16x16x32_bf16 v[60:63], v[132:135], v[148:151], v[60:63]
	v_mfma_f32_16x16x32_bf16 v[56:59], v[140:143], v[148:151], v[56:59]
	v_mfma_f32_16x16x32_bf16 v[44:47], v[132:135], v[156:159], v[44:47]
	v_mfma_f32_16x16x32_bf16 v[40:43], v[140:143], v[156:159], v[40:43]
	v_mfma_f32_16x16x32_bf16 v[28:31], v[132:135], v[164:167], v[28:31]
	v_mfma_f32_16x16x32_bf16 v[24:27], v[140:143], v[164:167], v[24:27]
	v_mfma_f32_16x16x32_bf16 v[12:15], v[132:135], v[172:175], v[12:15]
	v_mfma_f32_16x16x32_bf16 v[8:11], v[140:143], v[172:175], v[8:11]
	s_setprio 0
	s_barrier
	s_add_u32 s18, s22, 0xb0000
	s_addc_u32 s19, s23, 0
	s_add_i32 s45, s46, s29
	s_mov_b32 m0, s45
	s_nop 0
	global_load_lds_dwordx4 v192, s[18:19]
	v_lshl_add_u64 v[128:129], s[18:19], 0, v[210:211]
	s_add_i32 m0, s45, 0x2000
	s_nop 0
	global_load_lds_dwordx4 v[128:129], off
	s_waitcnt vmcnt(6)
	s_barrier
	s_setprio 1
	v_mfma_f32_16x16x32_bf16 v[52:55], v[176:179], v[144:147], v[52:55]
	v_mfma_f32_16x16x32_bf16 v[48:51], v[184:187], v[144:147], v[48:51]
	v_mfma_f32_16x16x32_bf16 v[36:39], v[176:179], v[152:155], v[36:39]
	v_mfma_f32_16x16x32_bf16 v[32:35], v[184:187], v[152:155], v[32:35]
	v_mfma_f32_16x16x32_bf16 v[20:23], v[176:179], v[160:163], v[20:23]
	v_mfma_f32_16x16x32_bf16 v[16:19], v[184:187], v[160:163], v[16:19]
	v_mfma_f32_16x16x32_bf16 v[4:7], v[176:179], v[168:171], v[4:7]
	v_mfma_f32_16x16x32_bf16 v[0:3], v[184:187], v[168:171], v[0:3]
	v_mfma_f32_16x16x32_bf16 v[52:55], v[180:183], v[148:151], v[52:55]
	v_mfma_f32_16x16x32_bf16 v[48:51], v[188:191], v[148:151], v[48:51]
	v_mfma_f32_16x16x32_bf16 v[36:39], v[180:183], v[156:159], v[36:39]
	v_mfma_f32_16x16x32_bf16 v[32:35], v[188:191], v[156:159], v[32:35]
	v_mfma_f32_16x16x32_bf16 v[20:23], v[180:183], v[164:167], v[20:23]
	v_mfma_f32_16x16x32_bf16 v[16:19], v[188:191], v[164:167], v[16:19]
	v_mfma_f32_16x16x32_bf16 v[4:7], v[180:183], v[172:175], v[4:7]
	v_mfma_f32_16x16x32_bf16 v[0:3], v[188:191], v[172:175], v[0:3]
	s_setprio 0
	s_add_i32 s45, 0, 0x18000
	v_add_u32_e32 v140, s45, v196
	s_barrier
	ds_read_b128 v[128:131], v140
	ds_read_b128 v[132:135], v140 offset:1024
	ds_read_b128 v[136:139], v140 offset:2048
	ds_read_b128 v[140:143], v140 offset:3072
	s_add_u32 s18, s24, 0xb0000
	s_addc_u32 s19, s25, 0
	s_mov_b32 m0, s34
	v_lshl_add_u64 v[176:177], s[18:19], 0, v[206:207]
	ds_read_b128 v[144:147], v198 offset:32768
	ds_read_b128 v[148:151], v198 offset:33792
	ds_read_b128 v[152:155], v198 offset:34816
	ds_read_b128 v[156:159], v198 offset:35840
	ds_read_b128 v[160:163], v198 offset:36864
	ds_read_b128 v[164:167], v198 offset:37888
	ds_read_b128 v[168:171], v198 offset:38912
	ds_read_b128 v[172:175], v198 offset:39936
	global_load_lds_dwordx4 v[176:177], off
	v_lshl_add_u64 v[176:177], s[18:19], 0, v[208:209]
	s_mov_b32 m0, s35
	s_nop 0
	global_load_lds_dwordx4 v[176:177], off
	s_waitcnt lgkmcnt(8)
	s_barrier
	s_waitcnt lgkmcnt(0)
	s_setprio 1
	s_waitcnt lgkmcnt(0)
	v_mfma_f32_16x16x32_bf16 v[124:127], v[128:131], v[144:147], v[124:127]
	v_mfma_f32_16x16x32_bf16 v[120:123], v[136:139], v[144:147], v[120:123]
	v_mfma_f32_16x16x32_bf16 v[108:111], v[128:131], v[152:155], v[108:111]
	v_mfma_f32_16x16x32_bf16 v[104:107], v[136:139], v[152:155], v[104:107]
	v_mfma_f32_16x16x32_bf16 v[92:95], v[128:131], v[160:163], v[92:95]
	v_mfma_f32_16x16x32_bf16 v[88:91], v[136:139], v[160:163], v[88:91]
	v_mfma_f32_16x16x32_bf16 v[76:79], v[128:131], v[168:171], v[76:79]
	v_mfma_f32_16x16x32_bf16 v[72:75], v[136:139], v[168:171], v[72:75]
	v_mfma_f32_16x16x32_bf16 v[124:127], v[132:135], v[148:151], v[124:127]
	v_mfma_f32_16x16x32_bf16 v[120:123], v[140:143], v[148:151], v[120:123]
	v_mfma_f32_16x16x32_bf16 v[108:111], v[132:135], v[156:159], v[108:111]
	v_mfma_f32_16x16x32_bf16 v[104:107], v[140:143], v[156:159], v[104:107]
	v_mfma_f32_16x16x32_bf16 v[92:95], v[132:135], v[164:167], v[92:95]
	v_mfma_f32_16x16x32_bf16 v[88:91], v[140:143], v[164:167], v[88:91]
	v_mfma_f32_16x16x32_bf16 v[76:79], v[132:135], v[172:175], v[76:79]
	v_mfma_f32_16x16x32_bf16 v[72:75], v[140:143], v[172:175], v[72:75]
	s_setprio 0
	s_barrier
	s_add_i32 s24, 0, 0x1c000
	s_add_i32 s18, s45, s29
	v_add_u32_e32 v188, s24, v196
	v_lshl_add_u64 v[200:201], v[200:201], 0, s[80:81]
	s_mov_b32 m0, s18
	ds_read_b128 v[176:179], v188
	ds_read_b128 v[180:183], v188 offset:1024
	ds_read_b128 v[184:187], v188 offset:2048
	ds_read_b128 v[188:191], v188 offset:3072
	global_load_lds_dwordx4 v[200:201], off
	v_lshl_add_u64 v[200:201], v[202:203], 0, s[80:81]
	s_add_i32 m0, s18, 0x2000
	s_nop 0
	global_load_lds_dwordx4 v[200:201], off
	s_barrier
	s_waitcnt lgkmcnt(0)
	s_setprio 1
	s_waitcnt lgkmcnt(0)
	v_mfma_f32_16x16x32_bf16 v[116:119], v[176:179], v[144:147], v[116:119]
	v_mfma_f32_16x16x32_bf16 v[112:115], v[184:187], v[144:147], v[112:115]
	v_mfma_f32_16x16x32_bf16 v[100:103], v[176:179], v[152:155], v[100:103]
	v_mfma_f32_16x16x32_bf16 v[96:99], v[184:187], v[152:155], v[96:99]
	v_mfma_f32_16x16x32_bf16 v[84:87], v[176:179], v[160:163], v[84:87]
	v_mfma_f32_16x16x32_bf16 v[80:83], v[184:187], v[160:163], v[80:83]
	v_mfma_f32_16x16x32_bf16 v[68:71], v[176:179], v[168:171], v[68:71]
	v_mfma_f32_16x16x32_bf16 v[64:67], v[184:187], v[168:171], v[64:67]
	v_mfma_f32_16x16x32_bf16 v[116:119], v[180:183], v[148:151], v[116:119]
	v_mfma_f32_16x16x32_bf16 v[112:115], v[188:191], v[148:151], v[112:115]
	v_mfma_f32_16x16x32_bf16 v[100:103], v[180:183], v[156:159], v[100:103]
	v_mfma_f32_16x16x32_bf16 v[96:99], v[188:191], v[156:159], v[96:99]
	v_mfma_f32_16x16x32_bf16 v[84:87], v[180:183], v[164:167], v[84:87]
	v_mfma_f32_16x16x32_bf16 v[80:83], v[188:191], v[164:167], v[80:83]
	v_mfma_f32_16x16x32_bf16 v[68:71], v[180:183], v[172:175], v[68:71]
	v_mfma_f32_16x16x32_bf16 v[64:67], v[188:191], v[172:175], v[64:67]
	s_setprio 0
	s_mov_b32 m0, s36
	v_lshl_add_u64 v[200:201], v[204:205], 0, s[80:81]
	s_barrier
	ds_read_b128 v[144:147], v198 offset:49152
	ds_read_b128 v[148:151], v198 offset:50176
	ds_read_b128 v[152:155], v198 offset:51200
	ds_read_b128 v[156:159], v198 offset:52224
	ds_read_b128 v[160:163], v198 offset:53248
	ds_read_b128 v[164:167], v198 offset:54272
	ds_read_b128 v[168:171], v198 offset:55296
	ds_read_b128 v[172:175], v198 offset:56320
	global_load_lds_dwordx4 v[200:201], off
	v_lshl_add_u64 v[200:201], v[216:217], 0, s[80:81]
	s_mov_b32 m0, s37
	s_nop 0
	global_load_lds_dwordx4 v[200:201], off
	s_barrier
	s_waitcnt lgkmcnt(0)
	s_setprio 1
	s_waitcnt lgkmcnt(0)
	v_mfma_f32_16x16x32_bf16 v[60:63], v[128:131], v[144:147], v[60:63]
	v_mfma_f32_16x16x32_bf16 v[56:59], v[136:139], v[144:147], v[56:59]
	v_mfma_f32_16x16x32_bf16 v[44:47], v[128:131], v[152:155], v[44:47]
	v_mfma_f32_16x16x32_bf16 v[40:43], v[136:139], v[152:155], v[40:43]
	v_mfma_f32_16x16x32_bf16 v[28:31], v[128:131], v[160:163], v[28:31]
	v_mfma_f32_16x16x32_bf16 v[24:27], v[136:139], v[160:163], v[24:27]
	v_mfma_f32_16x16x32_bf16 v[12:15], v[128:131], v[168:171], v[12:15]
	v_mfma_f32_16x16x32_bf16 v[8:11], v[136:139], v[168:171], v[8:11]
	v_mfma_f32_16x16x32_bf16 v[60:63], v[132:135], v[148:151], v[60:63]
	v_mfma_f32_16x16x32_bf16 v[56:59], v[140:143], v[148:151], v[56:59]
	v_mfma_f32_16x16x32_bf16 v[44:47], v[132:135], v[156:159], v[44:47]
	v_mfma_f32_16x16x32_bf16 v[40:43], v[140:143], v[156:159], v[40:43]
	v_mfma_f32_16x16x32_bf16 v[28:31], v[132:135], v[164:167], v[28:31]
	v_mfma_f32_16x16x32_bf16 v[24:27], v[140:143], v[164:167], v[24:27]
	v_mfma_f32_16x16x32_bf16 v[12:15], v[132:135], v[172:175], v[12:15]
	v_mfma_f32_16x16x32_bf16 v[8:11], v[140:143], v[172:175], v[8:11]
	s_setprio 0
	s_barrier
	s_add_u32 s18, s22, 0xb0080
	s_addc_u32 s19, s23, 0
	s_add_i32 s22, s24, s29
	s_mov_b32 m0, s22
	s_nop 0
	global_load_lds_dwordx4 v192, s[18:19]
	v_lshl_add_u64 v[128:129], s[18:19], 0, v[210:211]
	s_add_i32 m0, s22, 0x2000
	s_nop 0
	global_load_lds_dwordx4 v[128:129], off
	s_waitcnt vmcnt(6)
	s_barrier
	s_setprio 1
	v_mfma_f32_16x16x32_bf16 v[52:55], v[176:179], v[144:147], v[52:55]
	v_mfma_f32_16x16x32_bf16 v[48:51], v[184:187], v[144:147], v[48:51]
	v_mfma_f32_16x16x32_bf16 v[36:39], v[176:179], v[152:155], v[36:39]
	v_mfma_f32_16x16x32_bf16 v[32:35], v[184:187], v[152:155], v[32:35]
	v_mfma_f32_16x16x32_bf16 v[20:23], v[176:179], v[160:163], v[20:23]
	v_mfma_f32_16x16x32_bf16 v[16:19], v[184:187], v[160:163], v[16:19]
	v_mfma_f32_16x16x32_bf16 v[4:7], v[176:179], v[168:171], v[4:7]
	v_mfma_f32_16x16x32_bf16 v[0:3], v[184:187], v[168:171], v[0:3]
	v_mfma_f32_16x16x32_bf16 v[52:55], v[180:183], v[148:151], v[52:55]
	v_mfma_f32_16x16x32_bf16 v[48:51], v[188:191], v[148:151], v[48:51]
	v_mfma_f32_16x16x32_bf16 v[36:39], v[180:183], v[156:159], v[36:39]
	v_mfma_f32_16x16x32_bf16 v[32:35], v[188:191], v[156:159], v[32:35]
	v_mfma_f32_16x16x32_bf16 v[20:23], v[180:183], v[164:167], v[20:23]
	v_mfma_f32_16x16x32_bf16 v[16:19], v[188:191], v[164:167], v[16:19]
	v_mfma_f32_16x16x32_bf16 v[4:7], v[180:183], v[172:175], v[4:7]
	v_mfma_f32_16x16x32_bf16 v[0:3], v[188:191], v[172:175], v[0:3]
	s_setprio 0
	s_add_i32 s44, s44, 2
	s_add_u32 s33, s33, 0x100
	s_addc_u32 s43, s43, 0
	s_cmp_gt_u32 s44, 41
	s_mov_b64 s[18:19], s[20:21]
	s_barrier
	s_cbranch_scc0 .LBB0_3618
	v_mov_b32_e32 v128, v252
	s_lshl_b32 s19, s42, 8
	v_readfirstlane_b32 s18, v128
	s_ashr_i32 s20, s18, 2
	s_andn2_b32 s20, s20, 63
	s_lshr_b32 s18, s18, 1
	s_add_i32 s20, s20, s19
	s_and_b32 s18, s18, 0x60
	s_lshl_b32 s19, s41, 8
	v_and_or_b32 v218, v128, 15, s20
	v_lshrrev_b32_e32 v128, 1, v128
	s_or_b32 s18, s18, s19
	v_and_b32_e32 v129, 64, v195
	v_and_or_b32 v216, v128, 24, s18
	v_xor_b32_e32 v128, 16, v195
	v_add_u32_e32 v129, 64, v129
	v_cmp_lt_i32_e32 vcc, v128, v129
	v_ashrrev_i32_e32 v219, 31, v218
	v_ashrrev_i32_e32 v217, 31, v216
	v_cndmask_b32_e32 v128, v195, v128, vcc
	v_lshlrev_b32_e32 v200, 2, v128
	v_xor_b32_e32 v128, 32, v195
	v_cmp_lt_i32_e32 vcc, v128, v129
	v_or_b32_e32 v220, 0x80, v216
	v_ashrrev_i32_e32 v221, 31, v220
	v_cndmask_b32_e32 v128, v195, v128, vcc
	v_lshlrev_b32_e32 v199, 2, v128
	v_lshlrev_b64 v[128:129], 10, v[218:219]
	v_lshl_add_u64 v[130:131], v[128:129], 0, v[216:217]
	v_lshlrev_b64 v[130:131], 1, v[130:131]
	v_lshl_add_u64 v[246:247], s[10:11], 0, v[130:131]
	v_lshl_add_u64 v[250:251], s[12:13], 0, v[130:131]
	global_load_dwordx4 v[188:191], v[246:247], off
	global_load_dwordx4 v[180:183], v[246:247], off offset:256
	global_load_dwordx4 v[184:187], v[250:251], off
	v_or_b32_e32 v242, 16, v218
	v_lshl_add_u64 v[128:129], v[128:129], 0, v[220:221]
	v_ashrrev_i32_e32 v243, 31, v242
	v_lshl_add_u64 v[248:249], v[128:129], 1, s[12:13]
	v_lshlrev_b64 v[128:129], 10, v[242:243]
	v_or_b32_e32 v234, 32, v218
	v_lshl_add_u64 v[130:131], v[128:129], 0, v[216:217]
	v_lshl_add_u64 v[128:129], v[128:129], 0, v[220:221]
	v_ashrrev_i32_e32 v235, 31, v234
	v_lshlrev_b64 v[130:131], 1, v[130:131]
	v_lshl_add_u64 v[240:241], v[128:129], 1, s[12:13]
	v_lshlrev_b64 v[128:129], 10, v[234:235]
	v_or_b32_e32 v226, 48, v218
	v_lshl_add_u64 v[238:239], s[10:11], 0, v[130:131]
	v_lshl_add_u64 v[244:245], s[12:13], 0, v[130:131]
	v_lshl_add_u64 v[130:131], v[128:129], 0, v[216:217]
	v_lshl_add_u64 v[128:129], v[128:129], 0, v[220:221]
	v_ashrrev_i32_e32 v227, 31, v226
	v_lshlrev_b64 v[130:131], 1, v[130:131]
	v_lshl_add_u64 v[232:233], v[128:129], 1, s[12:13]
	v_lshlrev_b64 v[128:129], 10, v[226:227]
	v_lshl_add_u64 v[228:229], s[10:11], 0, v[130:131]
	v_lshl_add_u64 v[236:237], s[12:13], 0, v[130:131]
	v_lshl_add_u64 v[130:131], v[128:129], 0, v[216:217]
	v_lshlrev_b64 v[130:131], 1, v[130:131]
	v_lshl_add_u64 v[132:133], v[128:129], 0, v[220:221]
	v_lshl_add_u64 v[222:223], s[10:11], 0, v[130:131]
	v_lshl_add_u64 v[230:231], s[12:13], 0, v[130:131]
	v_lshl_add_u64 v[224:225], v[132:133], 1, s[12:13]
	global_load_dwordx4 v[176:179], v[248:249], off
	global_load_dwordx4 v[172:175], v[238:239], off
	global_load_dwordx4 v[164:167], v[238:239], off offset:256
	global_load_dwordx4 v[168:171], v[244:245], off
	global_load_dwordx4 v[160:163], v[240:241], off
	global_load_dwordx4 v[156:159], v[228:229], off
	global_load_dwordx4 v[132:135], v[224:225], off
	global_load_dwordx4 v[152:155], v[236:237], off
	global_load_dwordx4 v[144:147], v[232:233], off
	global_load_dwordx4 v[148:151], v[228:229], off offset:256
	global_load_dwordx4 v[136:139], v[230:231], off
	global_load_dwordx4 v[140:143], v[222:223], off
	global_load_dwordx4 v[128:131], v[222:223], off offset:256
	v_cmp_gt_u32_e32 vcc, 16, v195
	s_waitcnt vmcnt(0)
	v_lshlrev_b32_e32 v202, 16, v188
	v_and_b32_e32 v203, 0xffff0000, v188
	v_lshlrev_b32_e32 v204, 16, v184
	v_and_b32_e32 v205, 0xffff0000, v184
	v_lshlrev_b32_e32 v188, 16, v189
	v_and_b32_e32 v189, 0xffff0000, v189
	v_lshlrev_b32_e32 v184, 16, v185
	v_and_b32_e32 v185, 0xffff0000, v185
	v_pk_add_f32 v[202:203], v[202:203], v[204:205]
	v_pk_add_f32 v[184:185], v[188:189], v[184:185]
	v_pk_fma_f32 v[188:189], v[124:125], 0.5, v[202:203] op_sel_hi:[1,0,1]
	v_pk_fma_f32 v[184:185], v[126:127], 0.5, v[184:185] op_sel_hi:[1,0,1]
	v_lshlrev_b32_e32 v124, 16, v190
	v_and_b32_e32 v125, 0xffff0000, v190
	v_lshlrev_b32_e32 v126, 16, v186
	v_and_b32_e32 v127, 0xffff0000, v186
	v_pk_add_f32 v[124:125], v[124:125], v[126:127]
	v_lshlrev_b32_e32 v126, 16, v191
	v_and_b32_e32 v127, 0xffff0000, v191
	v_lshlrev_b32_e32 v186, 16, v187
	v_and_b32_e32 v187, 0xffff0000, v187
	v_pk_add_f32 v[126:127], v[126:127], v[186:187]
	v_pk_fma_f32 v[190:191], v[120:121], 0.5, v[124:125] op_sel_hi:[1,0,1]
	v_cvt_pk_bf16_f32 v120, v188, v189
	v_pk_fma_f32 v[186:187], v[122:123], 0.5, v[126:127] op_sel_hi:[1,0,1]
	v_and_b32_e32 v123, 0xffff0000, v120
	v_lshlrev_b32_e32 v122, 16, v120
	v_pk_add_f32 v[122:123], v[188:189], v[122:123] neg_lo:[0,1] neg_hi:[0,1]
	v_cvt_pk_bf16_f32 v121, v184, v185
	v_cvt_pk_bf16_f32 v124, v122, v123
	v_and_b32_e32 v123, 0xffff0000, v121
	v_lshlrev_b32_e32 v122, 16, v121
	v_pk_add_f32 v[122:123], v[184:185], v[122:123] neg_lo:[0,1] neg_hi:[0,1]
	s_nop 0
	v_cvt_pk_bf16_f32 v125, v122, v123
	v_cvt_pk_bf16_f32 v122, v190, v191
	v_cvt_pk_bf16_f32 v123, v186, v187
	v_and_b32_e32 v127, 0xffff0000, v122
	v_lshlrev_b32_e32 v126, 16, v122
	v_and_b32_e32 v203, 0xffff0000, v123
	v_lshlrev_b32_e32 v202, 16, v123
	v_pk_add_f32 v[126:127], v[190:191], v[126:127] neg_lo:[0,1] neg_hi:[0,1]
	v_pk_add_f32 v[202:203], v[186:187], v[202:203] neg_lo:[0,1] neg_hi:[0,1]
	v_cvt_pk_bf16_f32 v126, v126, v127
	v_cvt_pk_bf16_f32 v127, v202, v203
	global_store_dwordx4 v[246:247], v[120:123], off
	global_store_dwordx4 v[250:251], v[124:127], off
	s_nop 0
	v_pk_mul_f32 v[122:123], v[190:191], v[190:191]
	v_pk_mul_f32 v[120:121], v[186:187], v[186:187]
	v_pk_fma_f32 v[122:123], v[188:189], v[188:189], v[122:123]
	v_pk_fma_f32 v[120:121], v[184:185], v[184:185], v[120:121]
	v_add_f32_e32 v122, v122, v123
	v_add_f32_e32 v120, v120, v122
	v_add_f32_e32 v120, v121, v120
	ds_bpermute_b32 v121, v200, v120
	s_waitcnt lgkmcnt(0)
	v_add_f32_e32 v122, v120, v121
	ds_bpermute_b32 v123, v199, v122
	v_lshl_add_u64 v[120:121], v[218:219], 2, s[16:17]
	s_and_saveexec_b64 s[18:19], vcc
	s_cbranch_execz .LBB0_3621
	s_waitcnt lgkmcnt(0)
	v_add_f32_e32 v122, v122, v123
	global_atomic_add_f32 v[120:121], v122, off
